# P1 gate-column tile epilogue rewritten by hand (log-sigmoid without dead denormal/inf fix-ups, pack-then-perm stores): 6600 -> 3800 instr
# speedup vs baseline: 1.0213x; 1.0213x over previous
;   __device__ __forceinline__ void operator()(f32x4 (&acc)[2][2][4][2], int brow, int bcol, int wr, int wc, int fr, int fq) const {
;     ...
;       const u16* wgt = (const u16*)(p.ws + OFF_WGT);
; #pragma unroll
;       for (int dir = 0; dir < 2; ++dir) {
;         s16x4 bfr[2][2];
; #pragma unroll
;         for (int bj = 0; bj < 2; ++bj)
; #pragma unroll
;           for (int n = 0; n < 2; ++n)
;             bfr[bj][n] = *(const s16x4*)(wgt + ((size_t)(dir * 256 + bj * 128 + wc * 32 + n * 16 + fr)) * 16 + fq * 4);
;         u16* dst = (u16*)(p.ws + (dir == 0 ? OFF_LAF : OFF_LAB));
;         const float* bias = dir == 0 ? p.bgf : p.bgb;
; #pragma unroll
;         for (int ai = 0; ai < 2; ++ai)
; #pragma unroll
;           for (int m = 0; m < 4; ++m) {
;             int rl = ai * 128 + wr * 64 + m * 16;
;             s16x4 af = *(const s16x4*)(glr + (rl + fr) * 32 + dir * 16 + fq * 4);
;             int row0 = brow + rl + fq * 4;
; #pragma unroll
;             for (int bj = 0; bj < 2; ++bj)
; #pragma unroll
;               for (int n = 0; n < 2; ++n) {
;                 f32x4 z4 = {0.f, 0.f, 0.f, 0.f};
;                 z4 = __builtin_amdgcn_mfma_f32_16x16x16bf16_1k(af, bfr[bj][n], z4, 0, 0, 0);
;                 int c = bj * 128 + wc * 32 + n * 16 + fr;
;                 float bb = bias[c];
;                 float ls[4];
; #pragma unroll
;                 for (int j = 0; j < 4; ++j) {
;                   float z = z4[j] + bb;
;                   ls[j] = (fminf(z, 0.f) - __logf(1.f + __expf(-fabsf(z)))) * (1.f / 16.f);
;                 }
;                 store_rm4(dst, 256, row0, c, ls[0], ls[1], ls[2], ls[3], fr & 1);
.LBB0_155:
	s_or_b64 exec, exec, s[0:1]
	s_waitcnt vmcnt(0) lgkmcnt(0)
	s_barrier
	v_lshlrev_b32_e32 v225, 1, v232
	v_add_u32_e32 v160, v166, v230
	v_lshl_add_u32 v160, v160, 6, v225
	v_add_u32_e32 v160, 16, v160
	v_lshl_add_u32 v228, v233, 5, v230
	v_lshl_add_u32 v161, v228, 5, v225
	v_add_u32_e32 v224, 0x1000, v161
	v_lshlrev_b32_e32 v162, 2, v228
	v_and_b32_e32 v225, 1, v229
	v_cmp_eq_u32_e32 vcc, 1, v225
	v_add3_u32 v225, v166, v232, v225
	v_and_b32_e32 v163, 14, v230
	v_lshl_add_u32 v163, v233, 5, v163
	v_lshlrev_b32_e32 v163, 1, v163
	v_lshl_add_u32 v163, v225, 9, v163
	v_mov_b32_e32 v164, 0x05040100
	v_mov_b32_e32 v228, 0x03020706
	s_lshl_b32 s0, s60, 9
	v_cndmask_b32_e32 v164, v164, v228, vcc
	s_add_u32 s4, s40, 0x0
	s_addc_u32 s5, s41, 0
	s_add_u32 s8, s12, s0
	s_addc_u32 s9, s13, 0
	global_load_dwordx2 v[168:169], v161, s[4:5]
	global_load_dwordx2 v[170:171], v161, s[4:5] offset:512
	global_load_dwordx2 v[172:173], v224, s[4:5]
	global_load_dwordx2 v[174:175], v224, s[4:5] offset:512
	global_load_dword v176, v162, s[62:63]
	global_load_dword v177, v162, s[62:63] offset:64
	global_load_dword v178, v162, s[62:63] offset:512
	global_load_dword v179, v162, s[62:63] offset:576
	ds_read_b64 v[180:181], v160 offset:49152
	v_mov_b32_e32 v167, v163
	s_waitcnt vmcnt(0) lgkmcnt(0)
	v_mfma_f32_16x16x16_bf16 v[184:187], v[180:181], v[168:169], 0
	v_mfma_f32_16x16x16_bf16 v[188:191], v[180:181], v[170:171], 0
	v_mfma_f32_16x16x16_bf16 v[192:195], v[180:181], v[172:173], 0
	v_mfma_f32_16x16x16_bf16 v[196:199], v[180:181], v[174:175], 0
	s_nop 7
	s_nop 1
	v_add_f32_e32 v184, v176, v184
	v_add_f32_e32 v185, v176, v185
	v_add_f32_e32 v186, v176, v186
	v_add_f32_e32 v187, v176, v187
	v_add_f32_e32 v188, v177, v188
	v_add_f32_e32 v189, v177, v189
	v_add_f32_e32 v190, v177, v190
	v_add_f32_e32 v191, v177, v191
	v_min_f32_e32 v200, 0, v184
	v_min_f32_e32 v201, 0, v185
	v_min_f32_e32 v202, 0, v186
	v_min_f32_e32 v203, 0, v187
	v_min_f32_e32 v204, 0, v188
	v_min_f32_e32 v205, 0, v189
	v_min_f32_e32 v206, 0, v190
	v_min_f32_e32 v207, 0, v191
	v_mul_f32_e64 v208, |v184|, s93
	v_mul_f32_e64 v209, |v185|, s93
	v_mul_f32_e64 v210, |v186|, s93
	v_mul_f32_e64 v211, |v187|, s93
	v_mul_f32_e64 v212, |v188|, s93
	v_mul_f32_e64 v213, |v189|, s93
	v_mul_f32_e64 v214, |v190|, s93
	v_mul_f32_e64 v215, |v191|, s93
	v_exp_f32_e32 v208, v208
	v_exp_f32_e32 v209, v209
	v_exp_f32_e32 v210, v210
	v_exp_f32_e32 v211, v211
	v_exp_f32_e32 v212, v212
	v_exp_f32_e32 v213, v213
	v_exp_f32_e32 v214, v214
	v_exp_f32_e32 v215, v215
	v_add_f32_e32 v208, 1.0, v208
	v_add_f32_e32 v209, 1.0, v209
	v_add_f32_e32 v210, 1.0, v210
	v_add_f32_e32 v211, 1.0, v211
	v_add_f32_e32 v212, 1.0, v212
	v_add_f32_e32 v213, 1.0, v213
	v_add_f32_e32 v214, 1.0, v214
	v_add_f32_e32 v215, 1.0, v215
	v_log_f32_e32 v208, v208
	v_log_f32_e32 v209, v209
	v_log_f32_e32 v210, v210
	v_log_f32_e32 v211, v211
	v_log_f32_e32 v212, v212
	v_log_f32_e32 v213, v213
	v_log_f32_e32 v214, v214
	v_log_f32_e32 v215, v215
	v_mul_f32_e32 v216, 0x3f317217, v208
	v_mul_f32_e32 v217, 0x3f317217, v209
	v_mul_f32_e32 v218, 0x3f317217, v210
	v_mul_f32_e32 v219, 0x3f317217, v211
	v_mul_f32_e32 v220, 0x3f317217, v212
	v_mul_f32_e32 v221, 0x3f317217, v213
	v_mul_f32_e32 v222, 0x3f317217, v214
	v_mul_f32_e32 v223, 0x3f317217, v215
	v_fma_f32 v216, v208, s95, -v216
	v_fma_f32 v217, v209, s95, -v217
	v_fma_f32 v218, v210, s95, -v218
	v_fma_f32 v219, v211, s95, -v219
	v_fma_f32 v220, v212, s95, -v220
	v_fma_f32 v221, v213, s95, -v221
	v_fma_f32 v222, v214, s95, -v222
	v_fma_f32 v223, v215, s95, -v223
	v_fmac_f32_e32 v216, 0x3377d1cf, v208
	v_fmac_f32_e32 v217, 0x3377d1cf, v209
	v_fmac_f32_e32 v218, 0x3377d1cf, v210
	v_fmac_f32_e32 v219, 0x3377d1cf, v211
	v_fmac_f32_e32 v220, 0x3377d1cf, v212
	v_fmac_f32_e32 v221, 0x3377d1cf, v213
	v_fmac_f32_e32 v222, 0x3377d1cf, v214
	v_fmac_f32_e32 v223, 0x3377d1cf, v215
	v_fmac_f32_e32 v216, 0x3f317217, v208
	v_fmac_f32_e32 v217, 0x3f317217, v209
	v_fmac_f32_e32 v218, 0x3f317217, v210
	v_fmac_f32_e32 v219, 0x3f317217, v211
	v_fmac_f32_e32 v220, 0x3f317217, v212
	v_fmac_f32_e32 v221, 0x3f317217, v213
	v_fmac_f32_e32 v222, 0x3f317217, v214
	v_fmac_f32_e32 v223, 0x3f317217, v215
	v_sub_f32_e32 v200, v200, v216
	v_sub_f32_e32 v201, v201, v217
	v_sub_f32_e32 v202, v202, v218
	v_sub_f32_e32 v203, v203, v219
	v_sub_f32_e32 v204, v204, v220
	v_sub_f32_e32 v205, v205, v221
	v_sub_f32_e32 v206, v206, v222
	v_sub_f32_e32 v207, v207, v223
	v_mul_f32_e32 v184, 0x3d800000, v200
	v_mul_f32_e32 v185, 0x3d800000, v201
	v_mul_f32_e32 v186, 0x3d800000, v202
	v_mul_f32_e32 v187, 0x3d800000, v203
	v_mul_f32_e32 v188, 0x3d800000, v204
	v_mul_f32_e32 v189, 0x3d800000, v205
	v_mul_f32_e32 v190, 0x3d800000, v206
	v_mul_f32_e32 v191, 0x3d800000, v207
	v_add_f32_e32 v192, v178, v192
	v_add_f32_e32 v193, v178, v193
	v_add_f32_e32 v194, v178, v194
	v_add_f32_e32 v195, v178, v195
	v_add_f32_e32 v196, v179, v196
	v_add_f32_e32 v197, v179, v197
	v_add_f32_e32 v198, v179, v198
	v_add_f32_e32 v199, v179, v199
	v_min_f32_e32 v200, 0, v192
	v_min_f32_e32 v201, 0, v193
	v_min_f32_e32 v202, 0, v194
	v_min_f32_e32 v203, 0, v195
	v_min_f32_e32 v204, 0, v196
	v_min_f32_e32 v205, 0, v197
	v_min_f32_e32 v206, 0, v198
	v_min_f32_e32 v207, 0, v199
	v_mul_f32_e64 v208, |v192|, s93
	v_mul_f32_e64 v209, |v193|, s93
	v_mul_f32_e64 v210, |v194|, s93
	v_mul_f32_e64 v211, |v195|, s93
	v_mul_f32_e64 v212, |v196|, s93
	v_mul_f32_e64 v213, |v197|, s93
	v_mul_f32_e64 v214, |v198|, s93
	v_mul_f32_e64 v215, |v199|, s93
	v_exp_f32_e32 v208, v208
	v_exp_f32_e32 v209, v209
	v_exp_f32_e32 v210, v210
	v_exp_f32_e32 v211, v211
	v_exp_f32_e32 v212, v212
; __device__ __forceinline__ void store_rm4(u16* dst, size_t ld, int row0, int c, float v0, float v1, float v2, float v3, bool odd) {
;   {
;     float s = odd ? v0 : v1, r = dpp_swap1(s);
;     float lo = odd ? r : v0, hi = odd ? v1 : r;
;     *(unsigned*)(dst + (size_t)(row0 + (odd ? 1 : 0)) * ld + (c - (odd ? 1 : 0))) = pack2(lo, hi);
;   }
;   {
;     float s = odd ? v2 : v3, r = dpp_swap1(s);
;     float lo = odd ? r : v2, hi = odd ? v3 : r;
;     *(unsigned*)(dst + (size_t)(row0 + 2 + (odd ? 1 : 0)) * ld + (c - (odd ? 1 : 0))) = pack2(lo, hi);
;   }
;   __device__ __forceinline__ void operator()(f32x4 (&acc)[2][2][4][2], int brow, int bcol, int wr, int wc, int fr, int fq) const {
;     ...
;                 f32x4 z4 = {0.f, 0.f, 0.f, 0.f};
;                 z4 = __builtin_amdgcn_mfma_f32_16x16x16bf16_1k(af, bfr[bj][n], z4, 0, 0, 0);
;                 int c = bj * 128 + wc * 32 + n * 16 + fr;
;                 float bb = bias[c];
;                 float ls[4];
; #pragma unroll
;                 for (int j = 0; j < 4; ++j) {
;                   float z = z4[j] + bb;
;                   ls[j] = (fminf(z, 0.f) - __logf(1.f + __expf(-fabsf(z)))) * (1.f / 16.f);
;                 }
;                 store_rm4(dst, 256, row0, c, ls[0], ls[1], ls[2], ls[3], fr & 1);
	v_exp_f32_e32 v213, v213
	v_exp_f32_e32 v214, v214
	v_exp_f32_e32 v215, v215
	v_add_f32_e32 v208, 1.0, v208
	v_add_f32_e32 v209, 1.0, v209
	v_add_f32_e32 v210, 1.0, v210
	v_add_f32_e32 v211, 1.0, v211
	v_add_f32_e32 v212, 1.0, v212
	v_add_f32_e32 v213, 1.0, v213
	v_add_f32_e32 v214, 1.0, v214
	v_add_f32_e32 v215, 1.0, v215
	v_log_f32_e32 v208, v208
	v_log_f32_e32 v209, v209
	v_log_f32_e32 v210, v210
	v_log_f32_e32 v211, v211
	v_log_f32_e32 v212, v212
	v_log_f32_e32 v213, v213
	v_log_f32_e32 v214, v214
	v_log_f32_e32 v215, v215
	v_mul_f32_e32 v216, 0x3f317217, v208
	v_mul_f32_e32 v217, 0x3f317217, v209
	v_mul_f32_e32 v218, 0x3f317217, v210
	v_mul_f32_e32 v219, 0x3f317217, v211
	v_mul_f32_e32 v220, 0x3f317217, v212
	v_mul_f32_e32 v221, 0x3f317217, v213
	v_mul_f32_e32 v222, 0x3f317217, v214
	v_mul_f32_e32 v223, 0x3f317217, v215
	v_fma_f32 v216, v208, s95, -v216
	v_fma_f32 v217, v209, s95, -v217
	v_fma_f32 v218, v210, s95, -v218
	v_fma_f32 v219, v211, s95, -v219
	v_fma_f32 v220, v212, s95, -v220
	v_fma_f32 v221, v213, s95, -v221
	v_fma_f32 v222, v214, s95, -v222
	v_fma_f32 v223, v215, s95, -v223
	v_fmac_f32_e32 v216, 0x3377d1cf, v208
	v_fmac_f32_e32 v217, 0x3377d1cf, v209
	v_fmac_f32_e32 v218, 0x3377d1cf, v210
	v_fmac_f32_e32 v219, 0x3377d1cf, v211
	v_fmac_f32_e32 v220, 0x3377d1cf, v212
	v_fmac_f32_e32 v221, 0x3377d1cf, v213
	v_fmac_f32_e32 v222, 0x3377d1cf, v214
	v_fmac_f32_e32 v223, 0x3377d1cf, v215
	v_fmac_f32_e32 v216, 0x3f317217, v208
	v_fmac_f32_e32 v217, 0x3f317217, v209
	v_fmac_f32_e32 v218, 0x3f317217, v210
	v_fmac_f32_e32 v219, 0x3f317217, v211
	v_fmac_f32_e32 v220, 0x3f317217, v212
	v_fmac_f32_e32 v221, 0x3f317217, v213
	v_fmac_f32_e32 v222, 0x3f317217, v214
	v_fmac_f32_e32 v223, 0x3f317217, v215
	v_sub_f32_e32 v200, v200, v216
	v_sub_f32_e32 v201, v201, v217
	v_sub_f32_e32 v202, v202, v218
	v_sub_f32_e32 v203, v203, v219
	v_sub_f32_e32 v204, v204, v220
	v_sub_f32_e32 v205, v205, v221
	v_sub_f32_e32 v206, v206, v222
	v_sub_f32_e32 v207, v207, v223
	v_mul_f32_e32 v192, 0x3d800000, v200
	v_mul_f32_e32 v193, 0x3d800000, v201
	v_mul_f32_e32 v194, 0x3d800000, v202
	v_mul_f32_e32 v195, 0x3d800000, v203
	v_mul_f32_e32 v196, 0x3d800000, v204
	v_mul_f32_e32 v197, 0x3d800000, v205
	v_mul_f32_e32 v198, 0x3d800000, v206
	v_mul_f32_e32 v199, 0x3d800000, v207
	v_cvt_pk_bf16_f32 v208, v184, v185
	v_cvt_pk_bf16_f32 v209, v186, v187
	v_cvt_pk_bf16_f32 v210, v188, v189
	v_cvt_pk_bf16_f32 v211, v190, v191
	v_cvt_pk_bf16_f32 v212, v192, v193
	v_cvt_pk_bf16_f32 v213, v194, v195
	v_cvt_pk_bf16_f32 v214, v196, v197
	v_cvt_pk_bf16_f32 v215, v198, v199
	v_mov_b32_dpp v216, v208 quad_perm:[1,0,3,2] row_mask:0xf bank_mask:0xf bound_ctrl:1
	v_mov_b32_dpp v217, v209 quad_perm:[1,0,3,2] row_mask:0xf bank_mask:0xf bound_ctrl:1
	v_mov_b32_dpp v218, v210 quad_perm:[1,0,3,2] row_mask:0xf bank_mask:0xf bound_ctrl:1
	v_mov_b32_dpp v219, v211 quad_perm:[1,0,3,2] row_mask:0xf bank_mask:0xf bound_ctrl:1
	v_mov_b32_dpp v220, v212 quad_perm:[1,0,3,2] row_mask:0xf bank_mask:0xf bound_ctrl:1
	v_mov_b32_dpp v221, v213 quad_perm:[1,0,3,2] row_mask:0xf bank_mask:0xf bound_ctrl:1
	v_mov_b32_dpp v222, v214 quad_perm:[1,0,3,2] row_mask:0xf bank_mask:0xf bound_ctrl:1
	v_mov_b32_dpp v223, v215 quad_perm:[1,0,3,2] row_mask:0xf bank_mask:0xf bound_ctrl:1
	v_perm_b32 v208, v216, v208, v164
	v_perm_b32 v209, v217, v209, v164
	v_perm_b32 v210, v218, v210, v164
	v_perm_b32 v211, v219, v211, v164
	v_perm_b32 v212, v220, v212, v164
	v_perm_b32 v213, v221, v213, v164
	v_perm_b32 v214, v222, v214, v164
	v_perm_b32 v215, v223, v215, v164
	global_store_dword v167, v208, s[8:9]
	global_store_dword v167, v209, s[8:9] offset:1024
	global_store_dword v167, v210, s[8:9] offset:32
	global_store_dword v167, v211, s[8:9] offset:1056
	global_store_dword v167, v212, s[8:9] offset:256
	global_store_dword v167, v213, s[8:9] offset:1280
	global_store_dword v167, v214, s[8:9] offset:288
	global_store_dword v167, v215, s[8:9] offset:1312
	ds_read_b64 v[180:181], v160 offset:50176
	v_add_u32_e32 v167, 0x2000, v163
	s_waitcnt lgkmcnt(0)
	v_mfma_f32_16x16x16_bf16 v[184:187], v[180:181], v[168:169], 0
	v_mfma_f32_16x16x16_bf16 v[188:191], v[180:181], v[170:171], 0
	v_mfma_f32_16x16x16_bf16 v[192:195], v[180:181], v[172:173], 0
	v_mfma_f32_16x16x16_bf16 v[196:199], v[180:181], v[174:175], 0
	s_nop 7
	s_nop 1
	v_add_f32_e32 v184, v176, v184
	v_add_f32_e32 v185, v176, v185
	v_add_f32_e32 v186, v176, v186
	v_add_f32_e32 v187, v176, v187
	v_add_f32_e32 v188, v177, v188
	v_add_f32_e32 v189, v177, v189
	v_add_f32_e32 v190, v177, v190
	v_add_f32_e32 v191, v177, v191
	v_min_f32_e32 v200, 0, v184
	v_min_f32_e32 v201, 0, v185
	v_min_f32_e32 v202, 0, v186
	v_min_f32_e32 v203, 0, v187
	v_min_f32_e32 v204, 0, v188
	v_min_f32_e32 v205, 0, v189
	v_min_f32_e32 v206, 0, v190
	v_min_f32_e32 v207, 0, v191
	v_mul_f32_e64 v208, |v184|, s93
	v_mul_f32_e64 v209, |v185|, s93
	v_mul_f32_e64 v210, |v186|, s93
	v_mul_f32_e64 v211, |v187|, s93
	v_mul_f32_e64 v212, |v188|, s93
	v_mul_f32_e64 v213, |v189|, s93
	v_mul_f32_e64 v214, |v190|, s93
	v_mul_f32_e64 v215, |v191|, s93
	v_exp_f32_e32 v208, v208
	v_exp_f32_e32 v209, v209
	v_exp_f32_e32 v210, v210
	v_exp_f32_e32 v211, v211
	v_exp_f32_e32 v212, v212
	v_exp_f32_e32 v213, v213
	v_exp_f32_e32 v214, v214
	v_exp_f32_e32 v215, v215
	v_add_f32_e32 v208, 1.0, v208
	v_add_f32_e32 v209, 1.0, v209
	v_add_f32_e32 v210, 1.0, v210
	v_add_f32_e32 v211, 1.0, v211
	v_add_f32_e32 v212, 1.0, v212
	v_add_f32_e32 v213, 1.0, v213
	v_add_f32_e32 v214, 1.0, v214
	v_add_f32_e32 v215, 1.0, v215
	v_log_f32_e32 v208, v208
	v_log_f32_e32 v209, v209
	v_log_f32_e32 v210, v210
	v_log_f32_e32 v211, v211
; __device__ __forceinline__ void store_rm4(u16* dst, size_t ld, int row0, int c, float v0, float v1, float v2, float v3, bool odd) {
;   {
;     float s = odd ? v0 : v1, r = dpp_swap1(s);
;     float lo = odd ? r : v0, hi = odd ? v1 : r;
;     *(unsigned*)(dst + (size_t)(row0 + (odd ? 1 : 0)) * ld + (c - (odd ? 1 : 0))) = pack2(lo, hi);
;   }
;   {
;     float s = odd ? v2 : v3, r = dpp_swap1(s);
;     float lo = odd ? r : v2, hi = odd ? v3 : r;
;     *(unsigned*)(dst + (size_t)(row0 + 2 + (odd ? 1 : 0)) * ld + (c - (odd ? 1 : 0))) = pack2(lo, hi);
;   }
;   __device__ __forceinline__ void operator()(f32x4 (&acc)[2][2][4][2], int brow, int bcol, int wr, int wc, int fr, int fq) const {
;     ...
;                 f32x4 z4 = {0.f, 0.f, 0.f, 0.f};
;                 z4 = __builtin_amdgcn_mfma_f32_16x16x16bf16_1k(af, bfr[bj][n], z4, 0, 0, 0);
;                 int c = bj * 128 + wc * 32 + n * 16 + fr;
;                 float bb = bias[c];
;                 float ls[4];
; #pragma unroll
;                 for (int j = 0; j < 4; ++j) {
;                   float z = z4[j] + bb;
;                   ls[j] = (fminf(z, 0.f) - __logf(1.f + __expf(-fabsf(z)))) * (1.f / 16.f);
;                 }
;                 store_rm4(dst, 256, row0, c, ls[0], ls[1], ls[2], ls[3], fr & 1);
;               }
;             __builtin_amdgcn_sched_barrier(0);
	v_log_f32_e32 v212, v212
	v_log_f32_e32 v213, v213
	v_log_f32_e32 v214, v214
	v_log_f32_e32 v215, v215
	v_mul_f32_e32 v216, 0x3f317217, v208
	v_mul_f32_e32 v217, 0x3f317217, v209
	v_mul_f32_e32 v218, 0x3f317217, v210
	v_mul_f32_e32 v219, 0x3f317217, v211
	v_mul_f32_e32 v220, 0x3f317217, v212
	v_mul_f32_e32 v221, 0x3f317217, v213
	v_mul_f32_e32 v222, 0x3f317217, v214
	v_mul_f32_e32 v223, 0x3f317217, v215
	v_fma_f32 v216, v208, s95, -v216
	v_fma_f32 v217, v209, s95, -v217
	v_fma_f32 v218, v210, s95, -v218
	v_fma_f32 v219, v211, s95, -v219
	v_fma_f32 v220, v212, s95, -v220
	v_fma_f32 v221, v213, s95, -v221
	v_fma_f32 v222, v214, s95, -v222
	v_fma_f32 v223, v215, s95, -v223
	v_fmac_f32_e32 v216, 0x3377d1cf, v208
	v_fmac_f32_e32 v217, 0x3377d1cf, v209
	v_fmac_f32_e32 v218, 0x3377d1cf, v210
	v_fmac_f32_e32 v219, 0x3377d1cf, v211
	v_fmac_f32_e32 v220, 0x3377d1cf, v212
	v_fmac_f32_e32 v221, 0x3377d1cf, v213
	v_fmac_f32_e32 v222, 0x3377d1cf, v214
	v_fmac_f32_e32 v223, 0x3377d1cf, v215
	v_fmac_f32_e32 v216, 0x3f317217, v208
	v_fmac_f32_e32 v217, 0x3f317217, v209
	v_fmac_f32_e32 v218, 0x3f317217, v210
	v_fmac_f32_e32 v219, 0x3f317217, v211
	v_fmac_f32_e32 v220, 0x3f317217, v212
	v_fmac_f32_e32 v221, 0x3f317217, v213
	v_fmac_f32_e32 v222, 0x3f317217, v214
	v_fmac_f32_e32 v223, 0x3f317217, v215
	v_sub_f32_e32 v200, v200, v216
	v_sub_f32_e32 v201, v201, v217
	v_sub_f32_e32 v202, v202, v218
	v_sub_f32_e32 v203, v203, v219
	v_sub_f32_e32 v204, v204, v220
	v_sub_f32_e32 v205, v205, v221
	v_sub_f32_e32 v206, v206, v222
	v_sub_f32_e32 v207, v207, v223
	v_mul_f32_e32 v184, 0x3d800000, v200
	v_mul_f32_e32 v185, 0x3d800000, v201
	v_mul_f32_e32 v186, 0x3d800000, v202
	v_mul_f32_e32 v187, 0x3d800000, v203
	v_mul_f32_e32 v188, 0x3d800000, v204
	v_mul_f32_e32 v189, 0x3d800000, v205
	v_mul_f32_e32 v190, 0x3d800000, v206
	v_mul_f32_e32 v191, 0x3d800000, v207
	v_add_f32_e32 v192, v178, v192
	v_add_f32_e32 v193, v178, v193
	v_add_f32_e32 v194, v178, v194
	v_add_f32_e32 v195, v178, v195
	v_add_f32_e32 v196, v179, v196
	v_add_f32_e32 v197, v179, v197
	v_add_f32_e32 v198, v179, v198
	v_add_f32_e32 v199, v179, v199
	v_min_f32_e32 v200, 0, v192
	v_min_f32_e32 v201, 0, v193
	v_min_f32_e32 v202, 0, v194
	v_min_f32_e32 v203, 0, v195
	v_min_f32_e32 v204, 0, v196
	v_min_f32_e32 v205, 0, v197
	v_min_f32_e32 v206, 0, v198
	v_min_f32_e32 v207, 0, v199
	v_mul_f32_e64 v208, |v192|, s93
	v_mul_f32_e64 v209, |v193|, s93
	v_mul_f32_e64 v210, |v194|, s93
	v_mul_f32_e64 v211, |v195|, s93
	v_mul_f32_e64 v212, |v196|, s93
	v_mul_f32_e64 v213, |v197|, s93
	v_mul_f32_e64 v214, |v198|, s93
	v_mul_f32_e64 v215, |v199|, s93
	v_exp_f32_e32 v208, v208
	v_exp_f32_e32 v209, v209
	v_exp_f32_e32 v210, v210
	v_exp_f32_e32 v211, v211
	v_exp_f32_e32 v212, v212
	v_exp_f32_e32 v213, v213
	v_exp_f32_e32 v214, v214
	v_exp_f32_e32 v215, v215
	v_add_f32_e32 v208, 1.0, v208
	v_add_f32_e32 v209, 1.0, v209
	v_add_f32_e32 v210, 1.0, v210
	v_add_f32_e32 v211, 1.0, v211
	v_add_f32_e32 v212, 1.0, v212
	v_add_f32_e32 v213, 1.0, v213
	v_add_f32_e32 v214, 1.0, v214
	v_add_f32_e32 v215, 1.0, v215
	v_log_f32_e32 v208, v208
	v_log_f32_e32 v209, v209
	v_log_f32_e32 v210, v210
	v_log_f32_e32 v211, v211
	v_log_f32_e32 v212, v212
	v_log_f32_e32 v213, v213
	v_log_f32_e32 v214, v214
	v_log_f32_e32 v215, v215
	v_mul_f32_e32 v216, 0x3f317217, v208
	v_mul_f32_e32 v217, 0x3f317217, v209
	v_mul_f32_e32 v218, 0x3f317217, v210
	v_mul_f32_e32 v219, 0x3f317217, v211
	v_mul_f32_e32 v220, 0x3f317217, v212
	v_mul_f32_e32 v221, 0x3f317217, v213
	v_mul_f32_e32 v222, 0x3f317217, v214
	v_mul_f32_e32 v223, 0x3f317217, v215
	v_fma_f32 v216, v208, s95, -v216
	v_fma_f32 v217, v209, s95, -v217
	v_fma_f32 v218, v210, s95, -v218
	v_fma_f32 v219, v211, s95, -v219
	v_fma_f32 v220, v212, s95, -v220
	v_fma_f32 v221, v213, s95, -v221
	v_fma_f32 v222, v214, s95, -v222
	v_fma_f32 v223, v215, s95, -v223
	v_fmac_f32_e32 v216, 0x3377d1cf, v208
	v_fmac_f32_e32 v217, 0x3377d1cf, v209
	v_fmac_f32_e32 v218, 0x3377d1cf, v210
	v_fmac_f32_e32 v219, 0x3377d1cf, v211
	v_fmac_f32_e32 v220, 0x3377d1cf, v212
	v_fmac_f32_e32 v221, 0x3377d1cf, v213
	v_fmac_f32_e32 v222, 0x3377d1cf, v214
	v_fmac_f32_e32 v223, 0x3377d1cf, v215
	v_fmac_f32_e32 v216, 0x3f317217, v208
	v_fmac_f32_e32 v217, 0x3f317217, v209
	v_fmac_f32_e32 v218, 0x3f317217, v210
	v_fmac_f32_e32 v219, 0x3f317217, v211
	v_fmac_f32_e32 v220, 0x3f317217, v212
	v_fmac_f32_e32 v221, 0x3f317217, v213
	v_fmac_f32_e32 v222, 0x3f317217, v214
	v_fmac_f32_e32 v223, 0x3f317217, v215
	v_sub_f32_e32 v200, v200, v216
	v_sub_f32_e32 v201, v201, v217
	v_sub_f32_e32 v202, v202, v218
	v_sub_f32_e32 v203, v203, v219
	v_sub_f32_e32 v204, v204, v220
	v_sub_f32_e32 v205, v205, v221
	v_sub_f32_e32 v206, v206, v222
	v_sub_f32_e32 v207, v207, v223
	v_mul_f32_e32 v192, 0x3d800000, v200
	v_mul_f32_e32 v193, 0x3d800000, v201
	v_mul_f32_e32 v194, 0x3d800000, v202
	v_mul_f32_e32 v195, 0x3d800000, v203
	v_mul_f32_e32 v196, 0x3d800000, v204
	v_mul_f32_e32 v197, 0x3d800000, v205
	v_mul_f32_e32 v198, 0x3d800000, v206
	v_mul_f32_e32 v199, 0x3d800000, v207
	v_cvt_pk_bf16_f32 v208, v184, v185
	v_cvt_pk_bf16_f32 v209, v186, v187
	v_cvt_pk_bf16_f32 v210, v188, v189
	v_cvt_pk_bf16_f32 v211, v190, v191
	v_cvt_pk_bf16_f32 v212, v192, v193
	v_cvt_pk_bf16_f32 v213, v194, v195
	v_cvt_pk_bf16_f32 v214, v196, v197
	v_cvt_pk_bf16_f32 v215, v198, v199
	v_mov_b32_dpp v216, v208 quad_perm:[1,0,3,2] row_mask:0xf bank_mask:0xf bound_ctrl:1
	v_mov_b32_dpp v217, v209 quad_perm:[1,0,3,2] row_mask:0xf bank_mask:0xf bound_ctrl:1
	v_mov_b32_dpp v218, v210 quad_perm:[1,0,3,2] row_mask:0xf bank_mask:0xf bound_ctrl:1
	v_mov_b32_dpp v219, v211 quad_perm:[1,0,3,2] row_mask:0xf bank_mask:0xf bound_ctrl:1
	v_mov_b32_dpp v220, v212 quad_perm:[1,0,3,2] row_mask:0xf bank_mask:0xf bound_ctrl:1
	v_mov_b32_dpp v221, v213 quad_perm:[1,0,3,2] row_mask:0xf bank_mask:0xf bound_ctrl:1
	v_mov_b32_dpp v222, v214 quad_perm:[1,0,3,2] row_mask:0xf bank_mask:0xf bound_ctrl:1
	v_mov_b32_dpp v223, v215 quad_perm:[1,0,3,2] row_mask:0xf bank_mask:0xf bound_ctrl:1
	v_perm_b32 v208, v216, v208, v164
	v_perm_b32 v209, v217, v209, v164
	v_perm_b32 v210, v218, v210, v164
	v_perm_b32 v211, v219, v211, v164
	v_perm_b32 v212, v220, v212, v164
	v_perm_b32 v213, v221, v213, v164
	v_perm_b32 v214, v222, v214, v164
	v_perm_b32 v215, v223, v215, v164
	global_store_dword v167, v208, s[8:9]
	global_store_dword v167, v209, s[8:9] offset:1024
	global_store_dword v167, v210, s[8:9] offset:32
	global_store_dword v167, v211, s[8:9] offset:1056
	global_store_dword v167, v212, s[8:9] offset:256
	global_store_dword v167, v213, s[8:9] offset:1280
	global_store_dword v167, v214, s[8:9] offset:288
	global_store_dword v167, v215, s[8:9] offset:1312
	ds_read_b64 v[180:181], v160 offset:51200
	v_add_u32_e32 v167, 0x4000, v163
	s_waitcnt lgkmcnt(0)
;   __device__ __forceinline__ void operator()(f32x4 (&acc)[2][2][4][2], int brow, int bcol, int wr, int wc, int fr, int fq) const {
;     ...
;                 f32x4 z4 = {0.f, 0.f, 0.f, 0.f};
;                 z4 = __builtin_amdgcn_mfma_f32_16x16x16bf16_1k(af, bfr[bj][n], z4, 0, 0, 0);
;                 int c = bj * 128 + wc * 32 + n * 16 + fr;
;                 float bb = bias[c];
;                 float ls[4];
; #pragma unroll
;                 for (int j = 0; j < 4; ++j) {
;                   float z = z4[j] + bb;
;                   ls[j] = (fminf(z, 0.f) - __logf(1.f + __expf(-fabsf(z)))) * (1.f / 16.f);
;                 }
;                 store_rm4(dst, 256, row0, c, ls[0], ls[1], ls[2], ls[3], fr & 1);
	v_mfma_f32_16x16x16_bf16 v[184:187], v[180:181], v[168:169], 0
	v_mfma_f32_16x16x16_bf16 v[188:191], v[180:181], v[170:171], 0
	v_mfma_f32_16x16x16_bf16 v[192:195], v[180:181], v[172:173], 0
	v_mfma_f32_16x16x16_bf16 v[196:199], v[180:181], v[174:175], 0
	s_nop 7
	s_nop 1
	v_add_f32_e32 v184, v176, v184
	v_add_f32_e32 v185, v176, v185
	v_add_f32_e32 v186, v176, v186
	v_add_f32_e32 v187, v176, v187
	v_add_f32_e32 v188, v177, v188
	v_add_f32_e32 v189, v177, v189
	v_add_f32_e32 v190, v177, v190
	v_add_f32_e32 v191, v177, v191
	v_min_f32_e32 v200, 0, v184
	v_min_f32_e32 v201, 0, v185
	v_min_f32_e32 v202, 0, v186
	v_min_f32_e32 v203, 0, v187
	v_min_f32_e32 v204, 0, v188
	v_min_f32_e32 v205, 0, v189
	v_min_f32_e32 v206, 0, v190
	v_min_f32_e32 v207, 0, v191
	v_mul_f32_e64 v208, |v184|, s93
	v_mul_f32_e64 v209, |v185|, s93
	v_mul_f32_e64 v210, |v186|, s93
	v_mul_f32_e64 v211, |v187|, s93
	v_mul_f32_e64 v212, |v188|, s93
	v_mul_f32_e64 v213, |v189|, s93
	v_mul_f32_e64 v214, |v190|, s93
	v_mul_f32_e64 v215, |v191|, s93
	v_exp_f32_e32 v208, v208
	v_exp_f32_e32 v209, v209
	v_exp_f32_e32 v210, v210
	v_exp_f32_e32 v211, v211
	v_exp_f32_e32 v212, v212
	v_exp_f32_e32 v213, v213
	v_exp_f32_e32 v214, v214
	v_exp_f32_e32 v215, v215
	v_add_f32_e32 v208, 1.0, v208
	v_add_f32_e32 v209, 1.0, v209
	v_add_f32_e32 v210, 1.0, v210
	v_add_f32_e32 v211, 1.0, v211
	v_add_f32_e32 v212, 1.0, v212
	v_add_f32_e32 v213, 1.0, v213
	v_add_f32_e32 v214, 1.0, v214
	v_add_f32_e32 v215, 1.0, v215
	v_log_f32_e32 v208, v208
	v_log_f32_e32 v209, v209
	v_log_f32_e32 v210, v210
	v_log_f32_e32 v211, v211
	v_log_f32_e32 v212, v212
	v_log_f32_e32 v213, v213
	v_log_f32_e32 v214, v214
	v_log_f32_e32 v215, v215
	v_mul_f32_e32 v216, 0x3f317217, v208
	v_mul_f32_e32 v217, 0x3f317217, v209
	v_mul_f32_e32 v218, 0x3f317217, v210
	v_mul_f32_e32 v219, 0x3f317217, v211
	v_mul_f32_e32 v220, 0x3f317217, v212
	v_mul_f32_e32 v221, 0x3f317217, v213
	v_mul_f32_e32 v222, 0x3f317217, v214
	v_mul_f32_e32 v223, 0x3f317217, v215
	v_fma_f32 v216, v208, s95, -v216
	v_fma_f32 v217, v209, s95, -v217
	v_fma_f32 v218, v210, s95, -v218
	v_fma_f32 v219, v211, s95, -v219
	v_fma_f32 v220, v212, s95, -v220
	v_fma_f32 v221, v213, s95, -v221
	v_fma_f32 v222, v214, s95, -v222
	v_fma_f32 v223, v215, s95, -v223
	v_fmac_f32_e32 v216, 0x3377d1cf, v208
	v_fmac_f32_e32 v217, 0x3377d1cf, v209
	v_fmac_f32_e32 v218, 0x3377d1cf, v210
	v_fmac_f32_e32 v219, 0x3377d1cf, v211
	v_fmac_f32_e32 v220, 0x3377d1cf, v212
	v_fmac_f32_e32 v221, 0x3377d1cf, v213
	v_fmac_f32_e32 v222, 0x3377d1cf, v214
	v_fmac_f32_e32 v223, 0x3377d1cf, v215
	v_fmac_f32_e32 v216, 0x3f317217, v208
	v_fmac_f32_e32 v217, 0x3f317217, v209
	v_fmac_f32_e32 v218, 0x3f317217, v210
	v_fmac_f32_e32 v219, 0x3f317217, v211
	v_fmac_f32_e32 v220, 0x3f317217, v212
	v_fmac_f32_e32 v221, 0x3f317217, v213
	v_fmac_f32_e32 v222, 0x3f317217, v214
	v_fmac_f32_e32 v223, 0x3f317217, v215
	v_sub_f32_e32 v200, v200, v216
	v_sub_f32_e32 v201, v201, v217
	v_sub_f32_e32 v202, v202, v218
	v_sub_f32_e32 v203, v203, v219
	v_sub_f32_e32 v204, v204, v220
	v_sub_f32_e32 v205, v205, v221
	v_sub_f32_e32 v206, v206, v222
	v_sub_f32_e32 v207, v207, v223
	v_mul_f32_e32 v184, 0x3d800000, v200
	v_mul_f32_e32 v185, 0x3d800000, v201
	v_mul_f32_e32 v186, 0x3d800000, v202
	v_mul_f32_e32 v187, 0x3d800000, v203
	v_mul_f32_e32 v188, 0x3d800000, v204
	v_mul_f32_e32 v189, 0x3d800000, v205
	v_mul_f32_e32 v190, 0x3d800000, v206
	v_mul_f32_e32 v191, 0x3d800000, v207
	v_add_f32_e32 v192, v178, v192
	v_add_f32_e32 v193, v178, v193
	v_add_f32_e32 v194, v178, v194
	v_add_f32_e32 v195, v178, v195
	v_add_f32_e32 v196, v179, v196
	v_add_f32_e32 v197, v179, v197
	v_add_f32_e32 v198, v179, v198
	v_add_f32_e32 v199, v179, v199
	v_min_f32_e32 v200, 0, v192
	v_min_f32_e32 v201, 0, v193
	v_min_f32_e32 v202, 0, v194
	v_min_f32_e32 v203, 0, v195
	v_min_f32_e32 v204, 0, v196
	v_min_f32_e32 v205, 0, v197
	v_min_f32_e32 v206, 0, v198
	v_min_f32_e32 v207, 0, v199
	v_mul_f32_e64 v208, |v192|, s93
	v_mul_f32_e64 v209, |v193|, s93
	v_mul_f32_e64 v210, |v194|, s93
	v_mul_f32_e64 v211, |v195|, s93
	v_mul_f32_e64 v212, |v196|, s93
	v_mul_f32_e64 v213, |v197|, s93
	v_mul_f32_e64 v214, |v198|, s93
	v_mul_f32_e64 v215, |v199|, s93
	v_exp_f32_e32 v208, v208
	v_exp_f32_e32 v209, v209
	v_exp_f32_e32 v210, v210
	v_exp_f32_e32 v211, v211
	v_exp_f32_e32 v212, v212
	v_exp_f32_e32 v213, v213
	v_exp_f32_e32 v214, v214
	v_exp_f32_e32 v215, v215
	v_add_f32_e32 v208, 1.0, v208
	v_add_f32_e32 v209, 1.0, v209
	v_add_f32_e32 v210, 1.0, v210
	v_add_f32_e32 v211, 1.0, v211
	v_add_f32_e32 v212, 1.0, v212
	v_add_f32_e32 v213, 1.0, v213
	v_add_f32_e32 v214, 1.0, v214
	v_add_f32_e32 v215, 1.0, v215
	v_log_f32_e32 v208, v208
	v_log_f32_e32 v209, v209
	v_log_f32_e32 v210, v210
	v_log_f32_e32 v211, v211
	v_log_f32_e32 v212, v212
	v_log_f32_e32 v213, v213
	v_log_f32_e32 v214, v214
	v_log_f32_e32 v215, v215
	v_mul_f32_e32 v216, 0x3f317217, v208
	v_mul_f32_e32 v217, 0x3f317217, v209
	v_mul_f32_e32 v218, 0x3f317217, v210
	v_mul_f32_e32 v219, 0x3f317217, v211
	v_mul_f32_e32 v220, 0x3f317217, v212
	v_mul_f32_e32 v221, 0x3f317217, v213
	v_mul_f32_e32 v222, 0x3f317217, v214
	v_mul_f32_e32 v223, 0x3f317217, v215
	v_fma_f32 v216, v208, s95, -v216
	v_fma_f32 v217, v209, s95, -v217
	v_fma_f32 v218, v210, s95, -v218
	v_fma_f32 v219, v211, s95, -v219
	v_fma_f32 v220, v212, s95, -v220
	v_fma_f32 v221, v213, s95, -v221
	v_fma_f32 v222, v214, s95, -v222
	v_fma_f32 v223, v215, s95, -v223
	v_fmac_f32_e32 v216, 0x3377d1cf, v208
	v_fmac_f32_e32 v217, 0x3377d1cf, v209
	v_fmac_f32_e32 v218, 0x3377d1cf, v210
	v_fmac_f32_e32 v219, 0x3377d1cf, v211
	v_fmac_f32_e32 v220, 0x3377d1cf, v212
; __device__ __forceinline__ void store_rm4(u16* dst, size_t ld, int row0, int c, float v0, float v1, float v2, float v3, bool odd) {
;   {
;     float s = odd ? v0 : v1, r = dpp_swap1(s);
;     float lo = odd ? r : v0, hi = odd ? v1 : r;
;     *(unsigned*)(dst + (size_t)(row0 + (odd ? 1 : 0)) * ld + (c - (odd ? 1 : 0))) = pack2(lo, hi);
;   }
;   {
;     float s = odd ? v2 : v3, r = dpp_swap1(s);
;     float lo = odd ? r : v2, hi = odd ? v3 : r;
;     *(unsigned*)(dst + (size_t)(row0 + 2 + (odd ? 1 : 0)) * ld + (c - (odd ? 1 : 0))) = pack2(lo, hi);
;   }
;   __device__ __forceinline__ void operator()(f32x4 (&acc)[2][2][4][2], int brow, int bcol, int wr, int wc, int fr, int fq) const {
;     ...
;                 f32x4 z4 = {0.f, 0.f, 0.f, 0.f};
;                 z4 = __builtin_amdgcn_mfma_f32_16x16x16bf16_1k(af, bfr[bj][n], z4, 0, 0, 0);
;                 int c = bj * 128 + wc * 32 + n * 16 + fr;
;                 float bb = bias[c];
;                 float ls[4];
; #pragma unroll
;                 for (int j = 0; j < 4; ++j) {
;                   float z = z4[j] + bb;
;                   ls[j] = (fminf(z, 0.f) - __logf(1.f + __expf(-fabsf(z)))) * (1.f / 16.f);
;                 }
;                 store_rm4(dst, 256, row0, c, ls[0], ls[1], ls[2], ls[3], fr & 1);
;               }
;             __builtin_amdgcn_sched_barrier(0);
	v_fmac_f32_e32 v221, 0x3377d1cf, v213
	v_fmac_f32_e32 v222, 0x3377d1cf, v214
	v_fmac_f32_e32 v223, 0x3377d1cf, v215
	v_fmac_f32_e32 v216, 0x3f317217, v208
	v_fmac_f32_e32 v217, 0x3f317217, v209
	v_fmac_f32_e32 v218, 0x3f317217, v210
	v_fmac_f32_e32 v219, 0x3f317217, v211
	v_fmac_f32_e32 v220, 0x3f317217, v212
	v_fmac_f32_e32 v221, 0x3f317217, v213
	v_fmac_f32_e32 v222, 0x3f317217, v214
	v_fmac_f32_e32 v223, 0x3f317217, v215
	v_sub_f32_e32 v200, v200, v216
	v_sub_f32_e32 v201, v201, v217
	v_sub_f32_e32 v202, v202, v218
	v_sub_f32_e32 v203, v203, v219
	v_sub_f32_e32 v204, v204, v220
	v_sub_f32_e32 v205, v205, v221
	v_sub_f32_e32 v206, v206, v222
	v_sub_f32_e32 v207, v207, v223
	v_mul_f32_e32 v192, 0x3d800000, v200
	v_mul_f32_e32 v193, 0x3d800000, v201
	v_mul_f32_e32 v194, 0x3d800000, v202
	v_mul_f32_e32 v195, 0x3d800000, v203
	v_mul_f32_e32 v196, 0x3d800000, v204
	v_mul_f32_e32 v197, 0x3d800000, v205
	v_mul_f32_e32 v198, 0x3d800000, v206
	v_mul_f32_e32 v199, 0x3d800000, v207
	v_cvt_pk_bf16_f32 v208, v184, v185
	v_cvt_pk_bf16_f32 v209, v186, v187
	v_cvt_pk_bf16_f32 v210, v188, v189
	v_cvt_pk_bf16_f32 v211, v190, v191
	v_cvt_pk_bf16_f32 v212, v192, v193
	v_cvt_pk_bf16_f32 v213, v194, v195
	v_cvt_pk_bf16_f32 v214, v196, v197
	v_cvt_pk_bf16_f32 v215, v198, v199
	v_mov_b32_dpp v216, v208 quad_perm:[1,0,3,2] row_mask:0xf bank_mask:0xf bound_ctrl:1
	v_mov_b32_dpp v217, v209 quad_perm:[1,0,3,2] row_mask:0xf bank_mask:0xf bound_ctrl:1
	v_mov_b32_dpp v218, v210 quad_perm:[1,0,3,2] row_mask:0xf bank_mask:0xf bound_ctrl:1
	v_mov_b32_dpp v219, v211 quad_perm:[1,0,3,2] row_mask:0xf bank_mask:0xf bound_ctrl:1
	v_mov_b32_dpp v220, v212 quad_perm:[1,0,3,2] row_mask:0xf bank_mask:0xf bound_ctrl:1
	v_mov_b32_dpp v221, v213 quad_perm:[1,0,3,2] row_mask:0xf bank_mask:0xf bound_ctrl:1
	v_mov_b32_dpp v222, v214 quad_perm:[1,0,3,2] row_mask:0xf bank_mask:0xf bound_ctrl:1
	v_mov_b32_dpp v223, v215 quad_perm:[1,0,3,2] row_mask:0xf bank_mask:0xf bound_ctrl:1
	v_perm_b32 v208, v216, v208, v164
	v_perm_b32 v209, v217, v209, v164
	v_perm_b32 v210, v218, v210, v164
	v_perm_b32 v211, v219, v211, v164
	v_perm_b32 v212, v220, v212, v164
	v_perm_b32 v213, v221, v213, v164
	v_perm_b32 v214, v222, v214, v164
	v_perm_b32 v215, v223, v215, v164
	global_store_dword v167, v208, s[8:9]
	global_store_dword v167, v209, s[8:9] offset:1024
	global_store_dword v167, v210, s[8:9] offset:32
	global_store_dword v167, v211, s[8:9] offset:1056
	global_store_dword v167, v212, s[8:9] offset:256
	global_store_dword v167, v213, s[8:9] offset:1280
	global_store_dword v167, v214, s[8:9] offset:288
	global_store_dword v167, v215, s[8:9] offset:1312
	ds_read_b64 v[180:181], v160 offset:52224
	v_add_u32_e32 v167, 0x6000, v163
	s_waitcnt lgkmcnt(0)
	v_mfma_f32_16x16x16_bf16 v[184:187], v[180:181], v[168:169], 0
	v_mfma_f32_16x16x16_bf16 v[188:191], v[180:181], v[170:171], 0
	v_mfma_f32_16x16x16_bf16 v[192:195], v[180:181], v[172:173], 0
	v_mfma_f32_16x16x16_bf16 v[196:199], v[180:181], v[174:175], 0
	s_nop 7
	s_nop 1
	v_add_f32_e32 v184, v176, v184
	v_add_f32_e32 v185, v176, v185
	v_add_f32_e32 v186, v176, v186
	v_add_f32_e32 v187, v176, v187
	v_add_f32_e32 v188, v177, v188
	v_add_f32_e32 v189, v177, v189
	v_add_f32_e32 v190, v177, v190
	v_add_f32_e32 v191, v177, v191
	v_min_f32_e32 v200, 0, v184
	v_min_f32_e32 v201, 0, v185
	v_min_f32_e32 v202, 0, v186
	v_min_f32_e32 v203, 0, v187
	v_min_f32_e32 v204, 0, v188
	v_min_f32_e32 v205, 0, v189
	v_min_f32_e32 v206, 0, v190
	v_min_f32_e32 v207, 0, v191
	v_mul_f32_e64 v208, |v184|, s93
	v_mul_f32_e64 v209, |v185|, s93
	v_mul_f32_e64 v210, |v186|, s93
	v_mul_f32_e64 v211, |v187|, s93
	v_mul_f32_e64 v212, |v188|, s93
	v_mul_f32_e64 v213, |v189|, s93
	v_mul_f32_e64 v214, |v190|, s93
	v_mul_f32_e64 v215, |v191|, s93
	v_exp_f32_e32 v208, v208
	v_exp_f32_e32 v209, v209
	v_exp_f32_e32 v210, v210
	v_exp_f32_e32 v211, v211
	v_exp_f32_e32 v212, v212
	v_exp_f32_e32 v213, v213
	v_exp_f32_e32 v214, v214
	v_exp_f32_e32 v215, v215
	v_add_f32_e32 v208, 1.0, v208
	v_add_f32_e32 v209, 1.0, v209
	v_add_f32_e32 v210, 1.0, v210
	v_add_f32_e32 v211, 1.0, v211
	v_add_f32_e32 v212, 1.0, v212
	v_add_f32_e32 v213, 1.0, v213
	v_add_f32_e32 v214, 1.0, v214
	v_add_f32_e32 v215, 1.0, v215
	v_log_f32_e32 v208, v208
	v_log_f32_e32 v209, v209
	v_log_f32_e32 v210, v210
	v_log_f32_e32 v211, v211
	v_log_f32_e32 v212, v212
	v_log_f32_e32 v213, v213
	v_log_f32_e32 v214, v214
	v_log_f32_e32 v215, v215
	v_mul_f32_e32 v216, 0x3f317217, v208
	v_mul_f32_e32 v217, 0x3f317217, v209
	v_mul_f32_e32 v218, 0x3f317217, v210
	v_mul_f32_e32 v219, 0x3f317217, v211
	v_mul_f32_e32 v220, 0x3f317217, v212
	v_mul_f32_e32 v221, 0x3f317217, v213
	v_mul_f32_e32 v222, 0x3f317217, v214
	v_mul_f32_e32 v223, 0x3f317217, v215
	v_fma_f32 v216, v208, s95, -v216
	v_fma_f32 v217, v209, s95, -v217
	v_fma_f32 v218, v210, s95, -v218
	v_fma_f32 v219, v211, s95, -v219
	v_fma_f32 v220, v212, s95, -v220
	v_fma_f32 v221, v213, s95, -v221
	v_fma_f32 v222, v214, s95, -v222
	v_fma_f32 v223, v215, s95, -v223
	v_fmac_f32_e32 v216, 0x3377d1cf, v208
	v_fmac_f32_e32 v217, 0x3377d1cf, v209
	v_fmac_f32_e32 v218, 0x3377d1cf, v210
	v_fmac_f32_e32 v219, 0x3377d1cf, v211
	v_fmac_f32_e32 v220, 0x3377d1cf, v212
	v_fmac_f32_e32 v221, 0x3377d1cf, v213
	v_fmac_f32_e32 v222, 0x3377d1cf, v214
	v_fmac_f32_e32 v223, 0x3377d1cf, v215
	v_fmac_f32_e32 v216, 0x3f317217, v208
	v_fmac_f32_e32 v217, 0x3f317217, v209
	v_fmac_f32_e32 v218, 0x3f317217, v210
	v_fmac_f32_e32 v219, 0x3f317217, v211
	v_fmac_f32_e32 v220, 0x3f317217, v212
	v_fmac_f32_e32 v221, 0x3f317217, v213
	v_fmac_f32_e32 v222, 0x3f317217, v214
	v_fmac_f32_e32 v223, 0x3f317217, v215
; __device__ __forceinline__ void store_rm4(u16* dst, size_t ld, int row0, int c, float v0, float v1, float v2, float v3, bool odd) {
;   {
;     float s = odd ? v0 : v1, r = dpp_swap1(s);
;     float lo = odd ? r : v0, hi = odd ? v1 : r;
;     *(unsigned*)(dst + (size_t)(row0 + (odd ? 1 : 0)) * ld + (c - (odd ? 1 : 0))) = pack2(lo, hi);
;   }
;   {
;     float s = odd ? v2 : v3, r = dpp_swap1(s);
;     float lo = odd ? r : v2, hi = odd ? v3 : r;
;     *(unsigned*)(dst + (size_t)(row0 + 2 + (odd ? 1 : 0)) * ld + (c - (odd ? 1 : 0))) = pack2(lo, hi);
;   }
;   __device__ __forceinline__ void operator()(f32x4 (&acc)[2][2][4][2], int brow, int bcol, int wr, int wc, int fr, int fq) const {
;     ...
;                 f32x4 z4 = {0.f, 0.f, 0.f, 0.f};
;                 z4 = __builtin_amdgcn_mfma_f32_16x16x16bf16_1k(af, bfr[bj][n], z4, 0, 0, 0);
;                 int c = bj * 128 + wc * 32 + n * 16 + fr;
;                 float bb = bias[c];
;                 float ls[4];
; #pragma unroll
;                 for (int j = 0; j < 4; ++j) {
;                   float z = z4[j] + bb;
;                   ls[j] = (fminf(z, 0.f) - __logf(1.f + __expf(-fabsf(z)))) * (1.f / 16.f);
;                 }
;                 store_rm4(dst, 256, row0, c, ls[0], ls[1], ls[2], ls[3], fr & 1);
;               }
;             __builtin_amdgcn_sched_barrier(0);
	v_sub_f32_e32 v200, v200, v216
	v_sub_f32_e32 v201, v201, v217
	v_sub_f32_e32 v202, v202, v218
	v_sub_f32_e32 v203, v203, v219
	v_sub_f32_e32 v204, v204, v220
	v_sub_f32_e32 v205, v205, v221
	v_sub_f32_e32 v206, v206, v222
	v_sub_f32_e32 v207, v207, v223
	v_mul_f32_e32 v184, 0x3d800000, v200
	v_mul_f32_e32 v185, 0x3d800000, v201
	v_mul_f32_e32 v186, 0x3d800000, v202
	v_mul_f32_e32 v187, 0x3d800000, v203
	v_mul_f32_e32 v188, 0x3d800000, v204
	v_mul_f32_e32 v189, 0x3d800000, v205
	v_mul_f32_e32 v190, 0x3d800000, v206
	v_mul_f32_e32 v191, 0x3d800000, v207
	v_add_f32_e32 v192, v178, v192
	v_add_f32_e32 v193, v178, v193
	v_add_f32_e32 v194, v178, v194
	v_add_f32_e32 v195, v178, v195
	v_add_f32_e32 v196, v179, v196
	v_add_f32_e32 v197, v179, v197
	v_add_f32_e32 v198, v179, v198
	v_add_f32_e32 v199, v179, v199
	v_min_f32_e32 v200, 0, v192
	v_min_f32_e32 v201, 0, v193
	v_min_f32_e32 v202, 0, v194
	v_min_f32_e32 v203, 0, v195
	v_min_f32_e32 v204, 0, v196
	v_min_f32_e32 v205, 0, v197
	v_min_f32_e32 v206, 0, v198
	v_min_f32_e32 v207, 0, v199
	v_mul_f32_e64 v208, |v192|, s93
	v_mul_f32_e64 v209, |v193|, s93
	v_mul_f32_e64 v210, |v194|, s93
	v_mul_f32_e64 v211, |v195|, s93
	v_mul_f32_e64 v212, |v196|, s93
	v_mul_f32_e64 v213, |v197|, s93
	v_mul_f32_e64 v214, |v198|, s93
	v_mul_f32_e64 v215, |v199|, s93
	v_exp_f32_e32 v208, v208
	v_exp_f32_e32 v209, v209
	v_exp_f32_e32 v210, v210
	v_exp_f32_e32 v211, v211
	v_exp_f32_e32 v212, v212
	v_exp_f32_e32 v213, v213
	v_exp_f32_e32 v214, v214
	v_exp_f32_e32 v215, v215
	v_add_f32_e32 v208, 1.0, v208
	v_add_f32_e32 v209, 1.0, v209
	v_add_f32_e32 v210, 1.0, v210
	v_add_f32_e32 v211, 1.0, v211
	v_add_f32_e32 v212, 1.0, v212
	v_add_f32_e32 v213, 1.0, v213
	v_add_f32_e32 v214, 1.0, v214
	v_add_f32_e32 v215, 1.0, v215
	v_log_f32_e32 v208, v208
	v_log_f32_e32 v209, v209
	v_log_f32_e32 v210, v210
	v_log_f32_e32 v211, v211
	v_log_f32_e32 v212, v212
	v_log_f32_e32 v213, v213
	v_log_f32_e32 v214, v214
	v_log_f32_e32 v215, v215
	v_mul_f32_e32 v216, 0x3f317217, v208
	v_mul_f32_e32 v217, 0x3f317217, v209
	v_mul_f32_e32 v218, 0x3f317217, v210
	v_mul_f32_e32 v219, 0x3f317217, v211
	v_mul_f32_e32 v220, 0x3f317217, v212
	v_mul_f32_e32 v221, 0x3f317217, v213
	v_mul_f32_e32 v222, 0x3f317217, v214
	v_mul_f32_e32 v223, 0x3f317217, v215
	v_fma_f32 v216, v208, s95, -v216
	v_fma_f32 v217, v209, s95, -v217
	v_fma_f32 v218, v210, s95, -v218
	v_fma_f32 v219, v211, s95, -v219
	v_fma_f32 v220, v212, s95, -v220
	v_fma_f32 v221, v213, s95, -v221
	v_fma_f32 v222, v214, s95, -v222
	v_fma_f32 v223, v215, s95, -v223
	v_fmac_f32_e32 v216, 0x3377d1cf, v208
	v_fmac_f32_e32 v217, 0x3377d1cf, v209
	v_fmac_f32_e32 v218, 0x3377d1cf, v210
	v_fmac_f32_e32 v219, 0x3377d1cf, v211
	v_fmac_f32_e32 v220, 0x3377d1cf, v212
	v_fmac_f32_e32 v221, 0x3377d1cf, v213
	v_fmac_f32_e32 v222, 0x3377d1cf, v214
	v_fmac_f32_e32 v223, 0x3377d1cf, v215
	v_fmac_f32_e32 v216, 0x3f317217, v208
	v_fmac_f32_e32 v217, 0x3f317217, v209
	v_fmac_f32_e32 v218, 0x3f317217, v210
	v_fmac_f32_e32 v219, 0x3f317217, v211
	v_fmac_f32_e32 v220, 0x3f317217, v212
	v_fmac_f32_e32 v221, 0x3f317217, v213
	v_fmac_f32_e32 v222, 0x3f317217, v214
	v_fmac_f32_e32 v223, 0x3f317217, v215
	v_sub_f32_e32 v200, v200, v216
	v_sub_f32_e32 v201, v201, v217
	v_sub_f32_e32 v202, v202, v218
	v_sub_f32_e32 v203, v203, v219
	v_sub_f32_e32 v204, v204, v220
	v_sub_f32_e32 v205, v205, v221
	v_sub_f32_e32 v206, v206, v222
	v_sub_f32_e32 v207, v207, v223
	v_mul_f32_e32 v192, 0x3d800000, v200
	v_mul_f32_e32 v193, 0x3d800000, v201
	v_mul_f32_e32 v194, 0x3d800000, v202
	v_mul_f32_e32 v195, 0x3d800000, v203
	v_mul_f32_e32 v196, 0x3d800000, v204
	v_mul_f32_e32 v197, 0x3d800000, v205
	v_mul_f32_e32 v198, 0x3d800000, v206
	v_mul_f32_e32 v199, 0x3d800000, v207
	v_cvt_pk_bf16_f32 v208, v184, v185
	v_cvt_pk_bf16_f32 v209, v186, v187
	v_cvt_pk_bf16_f32 v210, v188, v189
	v_cvt_pk_bf16_f32 v211, v190, v191
	v_cvt_pk_bf16_f32 v212, v192, v193
	v_cvt_pk_bf16_f32 v213, v194, v195
	v_cvt_pk_bf16_f32 v214, v196, v197
	v_cvt_pk_bf16_f32 v215, v198, v199
	v_mov_b32_dpp v216, v208 quad_perm:[1,0,3,2] row_mask:0xf bank_mask:0xf bound_ctrl:1
	v_mov_b32_dpp v217, v209 quad_perm:[1,0,3,2] row_mask:0xf bank_mask:0xf bound_ctrl:1
	v_mov_b32_dpp v218, v210 quad_perm:[1,0,3,2] row_mask:0xf bank_mask:0xf bound_ctrl:1
	v_mov_b32_dpp v219, v211 quad_perm:[1,0,3,2] row_mask:0xf bank_mask:0xf bound_ctrl:1
	v_mov_b32_dpp v220, v212 quad_perm:[1,0,3,2] row_mask:0xf bank_mask:0xf bound_ctrl:1
	v_mov_b32_dpp v221, v213 quad_perm:[1,0,3,2] row_mask:0xf bank_mask:0xf bound_ctrl:1
	v_mov_b32_dpp v222, v214 quad_perm:[1,0,3,2] row_mask:0xf bank_mask:0xf bound_ctrl:1
	v_mov_b32_dpp v223, v215 quad_perm:[1,0,3,2] row_mask:0xf bank_mask:0xf bound_ctrl:1
	v_perm_b32 v208, v216, v208, v164
	v_perm_b32 v209, v217, v209, v164
	v_perm_b32 v210, v218, v210, v164
	v_perm_b32 v211, v219, v211, v164
	v_perm_b32 v212, v220, v212, v164
	v_perm_b32 v213, v221, v213, v164
	v_perm_b32 v214, v222, v214, v164
	v_perm_b32 v215, v223, v215, v164
	global_store_dword v167, v208, s[8:9]
	global_store_dword v167, v209, s[8:9] offset:1024
	global_store_dword v167, v210, s[8:9] offset:32
	global_store_dword v167, v211, s[8:9] offset:1056
	global_store_dword v167, v212, s[8:9] offset:256
	global_store_dword v167, v213, s[8:9] offset:1280
	global_store_dword v167, v214, s[8:9] offset:288
	global_store_dword v167, v215, s[8:9] offset:1312
	ds_read_b64 v[180:181], v160 offset:57344
	v_add_u32_e32 v167, 0x10000, v163
	s_waitcnt lgkmcnt(0)
;   __device__ __forceinline__ void operator()(f32x4 (&acc)[2][2][4][2], int brow, int bcol, int wr, int wc, int fr, int fq) const {
;     ...
;                 f32x4 z4 = {0.f, 0.f, 0.f, 0.f};
;                 z4 = __builtin_amdgcn_mfma_f32_16x16x16bf16_1k(af, bfr[bj][n], z4, 0, 0, 0);
;                 int c = bj * 128 + wc * 32 + n * 16 + fr;
;                 float bb = bias[c];
;                 float ls[4];
; #pragma unroll
;                 for (int j = 0; j < 4; ++j) {
;                   float z = z4[j] + bb;
;                   ls[j] = (fminf(z, 0.f) - __logf(1.f + __expf(-fabsf(z)))) * (1.f / 16.f);
;                 }
;                 store_rm4(dst, 256, row0, c, ls[0], ls[1], ls[2], ls[3], fr & 1);
	v_mfma_f32_16x16x16_bf16 v[184:187], v[180:181], v[168:169], 0
	v_mfma_f32_16x16x16_bf16 v[188:191], v[180:181], v[170:171], 0
	v_mfma_f32_16x16x16_bf16 v[192:195], v[180:181], v[172:173], 0
	v_mfma_f32_16x16x16_bf16 v[196:199], v[180:181], v[174:175], 0
	s_nop 7
	s_nop 1
	v_add_f32_e32 v184, v176, v184
	v_add_f32_e32 v185, v176, v185
	v_add_f32_e32 v186, v176, v186
	v_add_f32_e32 v187, v176, v187
	v_add_f32_e32 v188, v177, v188
	v_add_f32_e32 v189, v177, v189
	v_add_f32_e32 v190, v177, v190
	v_add_f32_e32 v191, v177, v191
	v_min_f32_e32 v200, 0, v184
	v_min_f32_e32 v201, 0, v185
	v_min_f32_e32 v202, 0, v186
	v_min_f32_e32 v203, 0, v187
	v_min_f32_e32 v204, 0, v188
	v_min_f32_e32 v205, 0, v189
	v_min_f32_e32 v206, 0, v190
	v_min_f32_e32 v207, 0, v191
	v_mul_f32_e64 v208, |v184|, s93
	v_mul_f32_e64 v209, |v185|, s93
	v_mul_f32_e64 v210, |v186|, s93
	v_mul_f32_e64 v211, |v187|, s93
	v_mul_f32_e64 v212, |v188|, s93
	v_mul_f32_e64 v213, |v189|, s93
	v_mul_f32_e64 v214, |v190|, s93
	v_mul_f32_e64 v215, |v191|, s93
	v_exp_f32_e32 v208, v208
	v_exp_f32_e32 v209, v209
	v_exp_f32_e32 v210, v210
	v_exp_f32_e32 v211, v211
	v_exp_f32_e32 v212, v212
	v_exp_f32_e32 v213, v213
	v_exp_f32_e32 v214, v214
	v_exp_f32_e32 v215, v215
	v_add_f32_e32 v208, 1.0, v208
	v_add_f32_e32 v209, 1.0, v209
	v_add_f32_e32 v210, 1.0, v210
	v_add_f32_e32 v211, 1.0, v211
	v_add_f32_e32 v212, 1.0, v212
	v_add_f32_e32 v213, 1.0, v213
	v_add_f32_e32 v214, 1.0, v214
	v_add_f32_e32 v215, 1.0, v215
	v_log_f32_e32 v208, v208
	v_log_f32_e32 v209, v209
	v_log_f32_e32 v210, v210
	v_log_f32_e32 v211, v211
	v_log_f32_e32 v212, v212
	v_log_f32_e32 v213, v213
	v_log_f32_e32 v214, v214
	v_log_f32_e32 v215, v215
	v_mul_f32_e32 v216, 0x3f317217, v208
	v_mul_f32_e32 v217, 0x3f317217, v209
	v_mul_f32_e32 v218, 0x3f317217, v210
	v_mul_f32_e32 v219, 0x3f317217, v211
	v_mul_f32_e32 v220, 0x3f317217, v212
	v_mul_f32_e32 v221, 0x3f317217, v213
	v_mul_f32_e32 v222, 0x3f317217, v214
	v_mul_f32_e32 v223, 0x3f317217, v215
	v_fma_f32 v216, v208, s95, -v216
	v_fma_f32 v217, v209, s95, -v217
	v_fma_f32 v218, v210, s95, -v218
	v_fma_f32 v219, v211, s95, -v219
	v_fma_f32 v220, v212, s95, -v220
	v_fma_f32 v221, v213, s95, -v221
	v_fma_f32 v222, v214, s95, -v222
	v_fma_f32 v223, v215, s95, -v223
	v_fmac_f32_e32 v216, 0x3377d1cf, v208
	v_fmac_f32_e32 v217, 0x3377d1cf, v209
	v_fmac_f32_e32 v218, 0x3377d1cf, v210
	v_fmac_f32_e32 v219, 0x3377d1cf, v211
	v_fmac_f32_e32 v220, 0x3377d1cf, v212
	v_fmac_f32_e32 v221, 0x3377d1cf, v213
	v_fmac_f32_e32 v222, 0x3377d1cf, v214
	v_fmac_f32_e32 v223, 0x3377d1cf, v215
	v_fmac_f32_e32 v216, 0x3f317217, v208
	v_fmac_f32_e32 v217, 0x3f317217, v209
	v_fmac_f32_e32 v218, 0x3f317217, v210
	v_fmac_f32_e32 v219, 0x3f317217, v211
	v_fmac_f32_e32 v220, 0x3f317217, v212
	v_fmac_f32_e32 v221, 0x3f317217, v213
	v_fmac_f32_e32 v222, 0x3f317217, v214
	v_fmac_f32_e32 v223, 0x3f317217, v215
	v_sub_f32_e32 v200, v200, v216
	v_sub_f32_e32 v201, v201, v217
	v_sub_f32_e32 v202, v202, v218
	v_sub_f32_e32 v203, v203, v219
	v_sub_f32_e32 v204, v204, v220
	v_sub_f32_e32 v205, v205, v221
	v_sub_f32_e32 v206, v206, v222
	v_sub_f32_e32 v207, v207, v223
	v_mul_f32_e32 v184, 0x3d800000, v200
	v_mul_f32_e32 v185, 0x3d800000, v201
	v_mul_f32_e32 v186, 0x3d800000, v202
	v_mul_f32_e32 v187, 0x3d800000, v203
	v_mul_f32_e32 v188, 0x3d800000, v204
	v_mul_f32_e32 v189, 0x3d800000, v205
	v_mul_f32_e32 v190, 0x3d800000, v206
	v_mul_f32_e32 v191, 0x3d800000, v207
	v_add_f32_e32 v192, v178, v192
	v_add_f32_e32 v193, v178, v193
	v_add_f32_e32 v194, v178, v194
	v_add_f32_e32 v195, v178, v195
	v_add_f32_e32 v196, v179, v196
	v_add_f32_e32 v197, v179, v197
	v_add_f32_e32 v198, v179, v198
	v_add_f32_e32 v199, v179, v199
	v_min_f32_e32 v200, 0, v192
	v_min_f32_e32 v201, 0, v193
	v_min_f32_e32 v202, 0, v194
	v_min_f32_e32 v203, 0, v195
	v_min_f32_e32 v204, 0, v196
	v_min_f32_e32 v205, 0, v197
	v_min_f32_e32 v206, 0, v198
	v_min_f32_e32 v207, 0, v199
	v_mul_f32_e64 v208, |v192|, s93
	v_mul_f32_e64 v209, |v193|, s93
	v_mul_f32_e64 v210, |v194|, s93
	v_mul_f32_e64 v211, |v195|, s93
	v_mul_f32_e64 v212, |v196|, s93
	v_mul_f32_e64 v213, |v197|, s93
	v_mul_f32_e64 v214, |v198|, s93
	v_mul_f32_e64 v215, |v199|, s93
	v_exp_f32_e32 v208, v208
	v_exp_f32_e32 v209, v209
	v_exp_f32_e32 v210, v210
	v_exp_f32_e32 v211, v211
	v_exp_f32_e32 v212, v212
	v_exp_f32_e32 v213, v213
	v_exp_f32_e32 v214, v214
	v_exp_f32_e32 v215, v215
	v_add_f32_e32 v208, 1.0, v208
	v_add_f32_e32 v209, 1.0, v209
	v_add_f32_e32 v210, 1.0, v210
	v_add_f32_e32 v211, 1.0, v211
	v_add_f32_e32 v212, 1.0, v212
	v_add_f32_e32 v213, 1.0, v213
	v_add_f32_e32 v214, 1.0, v214
	v_add_f32_e32 v215, 1.0, v215
	v_log_f32_e32 v208, v208
	v_log_f32_e32 v209, v209
	v_log_f32_e32 v210, v210
	v_log_f32_e32 v211, v211
	v_log_f32_e32 v212, v212
	v_log_f32_e32 v213, v213
	v_log_f32_e32 v214, v214
	v_log_f32_e32 v215, v215
	v_mul_f32_e32 v216, 0x3f317217, v208
	v_mul_f32_e32 v217, 0x3f317217, v209
	v_mul_f32_e32 v218, 0x3f317217, v210
	v_mul_f32_e32 v219, 0x3f317217, v211
	v_mul_f32_e32 v220, 0x3f317217, v212
	v_mul_f32_e32 v221, 0x3f317217, v213
	v_mul_f32_e32 v222, 0x3f317217, v214
	v_mul_f32_e32 v223, 0x3f317217, v215
	v_fma_f32 v216, v208, s95, -v216
	v_fma_f32 v217, v209, s95, -v217
	v_fma_f32 v218, v210, s95, -v218
	v_fma_f32 v219, v211, s95, -v219
	v_fma_f32 v220, v212, s95, -v220
	v_fma_f32 v221, v213, s95, -v221
	v_fma_f32 v222, v214, s95, -v222
	v_fma_f32 v223, v215, s95, -v223
	v_fmac_f32_e32 v216, 0x3377d1cf, v208
	v_fmac_f32_e32 v217, 0x3377d1cf, v209
	v_fmac_f32_e32 v218, 0x3377d1cf, v210
	v_fmac_f32_e32 v219, 0x3377d1cf, v211
	v_fmac_f32_e32 v220, 0x3377d1cf, v212
; __device__ __forceinline__ void store_rm4(u16* dst, size_t ld, int row0, int c, float v0, float v1, float v2, float v3, bool odd) {
;   {
;     float s = odd ? v0 : v1, r = dpp_swap1(s);
;     float lo = odd ? r : v0, hi = odd ? v1 : r;
;     *(unsigned*)(dst + (size_t)(row0 + (odd ? 1 : 0)) * ld + (c - (odd ? 1 : 0))) = pack2(lo, hi);
;   }
;   {
;     float s = odd ? v2 : v3, r = dpp_swap1(s);
;     float lo = odd ? r : v2, hi = odd ? v3 : r;
;     *(unsigned*)(dst + (size_t)(row0 + 2 + (odd ? 1 : 0)) * ld + (c - (odd ? 1 : 0))) = pack2(lo, hi);
;   }
;   __device__ __forceinline__ void operator()(f32x4 (&acc)[2][2][4][2], int brow, int bcol, int wr, int wc, int fr, int fq) const {
;     ...
;                 f32x4 z4 = {0.f, 0.f, 0.f, 0.f};
;                 z4 = __builtin_amdgcn_mfma_f32_16x16x16bf16_1k(af, bfr[bj][n], z4, 0, 0, 0);
;                 int c = bj * 128 + wc * 32 + n * 16 + fr;
;                 float bb = bias[c];
;                 float ls[4];
; #pragma unroll
;                 for (int j = 0; j < 4; ++j) {
;                   float z = z4[j] + bb;
;                   ls[j] = (fminf(z, 0.f) - __logf(1.f + __expf(-fabsf(z)))) * (1.f / 16.f);
;                 }
;                 store_rm4(dst, 256, row0, c, ls[0], ls[1], ls[2], ls[3], fr & 1);
;               }
;             __builtin_amdgcn_sched_barrier(0);
	v_fmac_f32_e32 v221, 0x3377d1cf, v213
	v_fmac_f32_e32 v222, 0x3377d1cf, v214
	v_fmac_f32_e32 v223, 0x3377d1cf, v215
	v_fmac_f32_e32 v216, 0x3f317217, v208
	v_fmac_f32_e32 v217, 0x3f317217, v209
	v_fmac_f32_e32 v218, 0x3f317217, v210
	v_fmac_f32_e32 v219, 0x3f317217, v211
	v_fmac_f32_e32 v220, 0x3f317217, v212
	v_fmac_f32_e32 v221, 0x3f317217, v213
	v_fmac_f32_e32 v222, 0x3f317217, v214
	v_fmac_f32_e32 v223, 0x3f317217, v215
	v_sub_f32_e32 v200, v200, v216
	v_sub_f32_e32 v201, v201, v217
	v_sub_f32_e32 v202, v202, v218
	v_sub_f32_e32 v203, v203, v219
	v_sub_f32_e32 v204, v204, v220
	v_sub_f32_e32 v205, v205, v221
	v_sub_f32_e32 v206, v206, v222
	v_sub_f32_e32 v207, v207, v223
	v_mul_f32_e32 v192, 0x3d800000, v200
	v_mul_f32_e32 v193, 0x3d800000, v201
	v_mul_f32_e32 v194, 0x3d800000, v202
	v_mul_f32_e32 v195, 0x3d800000, v203
	v_mul_f32_e32 v196, 0x3d800000, v204
	v_mul_f32_e32 v197, 0x3d800000, v205
	v_mul_f32_e32 v198, 0x3d800000, v206
	v_mul_f32_e32 v199, 0x3d800000, v207
	v_cvt_pk_bf16_f32 v208, v184, v185
	v_cvt_pk_bf16_f32 v209, v186, v187
	v_cvt_pk_bf16_f32 v210, v188, v189
	v_cvt_pk_bf16_f32 v211, v190, v191
	v_cvt_pk_bf16_f32 v212, v192, v193
	v_cvt_pk_bf16_f32 v213, v194, v195
	v_cvt_pk_bf16_f32 v214, v196, v197
	v_cvt_pk_bf16_f32 v215, v198, v199
	v_mov_b32_dpp v216, v208 quad_perm:[1,0,3,2] row_mask:0xf bank_mask:0xf bound_ctrl:1
	v_mov_b32_dpp v217, v209 quad_perm:[1,0,3,2] row_mask:0xf bank_mask:0xf bound_ctrl:1
	v_mov_b32_dpp v218, v210 quad_perm:[1,0,3,2] row_mask:0xf bank_mask:0xf bound_ctrl:1
	v_mov_b32_dpp v219, v211 quad_perm:[1,0,3,2] row_mask:0xf bank_mask:0xf bound_ctrl:1
	v_mov_b32_dpp v220, v212 quad_perm:[1,0,3,2] row_mask:0xf bank_mask:0xf bound_ctrl:1
	v_mov_b32_dpp v221, v213 quad_perm:[1,0,3,2] row_mask:0xf bank_mask:0xf bound_ctrl:1
	v_mov_b32_dpp v222, v214 quad_perm:[1,0,3,2] row_mask:0xf bank_mask:0xf bound_ctrl:1
	v_mov_b32_dpp v223, v215 quad_perm:[1,0,3,2] row_mask:0xf bank_mask:0xf bound_ctrl:1
	v_perm_b32 v208, v216, v208, v164
	v_perm_b32 v209, v217, v209, v164
	v_perm_b32 v210, v218, v210, v164
	v_perm_b32 v211, v219, v211, v164
	v_perm_b32 v212, v220, v212, v164
	v_perm_b32 v213, v221, v213, v164
	v_perm_b32 v214, v222, v214, v164
	v_perm_b32 v215, v223, v215, v164
	global_store_dword v167, v208, s[8:9]
	global_store_dword v167, v209, s[8:9] offset:1024
	global_store_dword v167, v210, s[8:9] offset:32
	global_store_dword v167, v211, s[8:9] offset:1056
	global_store_dword v167, v212, s[8:9] offset:256
	global_store_dword v167, v213, s[8:9] offset:1280
	global_store_dword v167, v214, s[8:9] offset:288
	global_store_dword v167, v215, s[8:9] offset:1312
	ds_read_b64 v[180:181], v160 offset:58368
	v_add_u32_e32 v167, 0x12000, v163
	s_waitcnt lgkmcnt(0)
	v_mfma_f32_16x16x16_bf16 v[184:187], v[180:181], v[168:169], 0
	v_mfma_f32_16x16x16_bf16 v[188:191], v[180:181], v[170:171], 0
	v_mfma_f32_16x16x16_bf16 v[192:195], v[180:181], v[172:173], 0
	v_mfma_f32_16x16x16_bf16 v[196:199], v[180:181], v[174:175], 0
	s_nop 7
	s_nop 1
	v_add_f32_e32 v184, v176, v184
	v_add_f32_e32 v185, v176, v185
	v_add_f32_e32 v186, v176, v186
	v_add_f32_e32 v187, v176, v187
	v_add_f32_e32 v188, v177, v188
	v_add_f32_e32 v189, v177, v189
	v_add_f32_e32 v190, v177, v190
	v_add_f32_e32 v191, v177, v191
	v_min_f32_e32 v200, 0, v184
	v_min_f32_e32 v201, 0, v185
	v_min_f32_e32 v202, 0, v186
	v_min_f32_e32 v203, 0, v187
	v_min_f32_e32 v204, 0, v188
	v_min_f32_e32 v205, 0, v189
	v_min_f32_e32 v206, 0, v190
	v_min_f32_e32 v207, 0, v191
	v_mul_f32_e64 v208, |v184|, s93
	v_mul_f32_e64 v209, |v185|, s93
	v_mul_f32_e64 v210, |v186|, s93
	v_mul_f32_e64 v211, |v187|, s93
	v_mul_f32_e64 v212, |v188|, s93
	v_mul_f32_e64 v213, |v189|, s93
	v_mul_f32_e64 v214, |v190|, s93
	v_mul_f32_e64 v215, |v191|, s93
	v_exp_f32_e32 v208, v208
	v_exp_f32_e32 v209, v209
	v_exp_f32_e32 v210, v210
	v_exp_f32_e32 v211, v211
	v_exp_f32_e32 v212, v212
	v_exp_f32_e32 v213, v213
	v_exp_f32_e32 v214, v214
	v_exp_f32_e32 v215, v215
	v_add_f32_e32 v208, 1.0, v208
	v_add_f32_e32 v209, 1.0, v209
	v_add_f32_e32 v210, 1.0, v210
	v_add_f32_e32 v211, 1.0, v211
	v_add_f32_e32 v212, 1.0, v212
	v_add_f32_e32 v213, 1.0, v213
	v_add_f32_e32 v214, 1.0, v214
	v_add_f32_e32 v215, 1.0, v215
	v_log_f32_e32 v208, v208
	v_log_f32_e32 v209, v209
	v_log_f32_e32 v210, v210
	v_log_f32_e32 v211, v211
	v_log_f32_e32 v212, v212
	v_log_f32_e32 v213, v213
	v_log_f32_e32 v214, v214
	v_log_f32_e32 v215, v215
	v_mul_f32_e32 v216, 0x3f317217, v208
	v_mul_f32_e32 v217, 0x3f317217, v209
	v_mul_f32_e32 v218, 0x3f317217, v210
	v_mul_f32_e32 v219, 0x3f317217, v211
	v_mul_f32_e32 v220, 0x3f317217, v212
	v_mul_f32_e32 v221, 0x3f317217, v213
	v_mul_f32_e32 v222, 0x3f317217, v214
	v_mul_f32_e32 v223, 0x3f317217, v215
	v_fma_f32 v216, v208, s95, -v216
	v_fma_f32 v217, v209, s95, -v217
	v_fma_f32 v218, v210, s95, -v218
	v_fma_f32 v219, v211, s95, -v219
	v_fma_f32 v220, v212, s95, -v220
	v_fma_f32 v221, v213, s95, -v221
	v_fma_f32 v222, v214, s95, -v222
	v_fma_f32 v223, v215, s95, -v223
	v_fmac_f32_e32 v216, 0x3377d1cf, v208
	v_fmac_f32_e32 v217, 0x3377d1cf, v209
	v_fmac_f32_e32 v218, 0x3377d1cf, v210
	v_fmac_f32_e32 v219, 0x3377d1cf, v211
	v_fmac_f32_e32 v220, 0x3377d1cf, v212
	v_fmac_f32_e32 v221, 0x3377d1cf, v213
	v_fmac_f32_e32 v222, 0x3377d1cf, v214
	v_fmac_f32_e32 v223, 0x3377d1cf, v215
	v_fmac_f32_e32 v216, 0x3f317217, v208
	v_fmac_f32_e32 v217, 0x3f317217, v209
	v_fmac_f32_e32 v218, 0x3f317217, v210
	v_fmac_f32_e32 v219, 0x3f317217, v211
	v_fmac_f32_e32 v220, 0x3f317217, v212
	v_fmac_f32_e32 v221, 0x3f317217, v213
	v_fmac_f32_e32 v222, 0x3f317217, v214
	v_fmac_f32_e32 v223, 0x3f317217, v215
; __device__ __forceinline__ void store_rm4(u16* dst, size_t ld, int row0, int c, float v0, float v1, float v2, float v3, bool odd) {
;   {
;     float s = odd ? v0 : v1, r = dpp_swap1(s);
;     float lo = odd ? r : v0, hi = odd ? v1 : r;
;     *(unsigned*)(dst + (size_t)(row0 + (odd ? 1 : 0)) * ld + (c - (odd ? 1 : 0))) = pack2(lo, hi);
;   }
;   {
;     float s = odd ? v2 : v3, r = dpp_swap1(s);
;     float lo = odd ? r : v2, hi = odd ? v3 : r;
;     *(unsigned*)(dst + (size_t)(row0 + 2 + (odd ? 1 : 0)) * ld + (c - (odd ? 1 : 0))) = pack2(lo, hi);
;   }
;   __device__ __forceinline__ void operator()(f32x4 (&acc)[2][2][4][2], int brow, int bcol, int wr, int wc, int fr, int fq) const {
;     ...
;                 f32x4 z4 = {0.f, 0.f, 0.f, 0.f};
;                 z4 = __builtin_amdgcn_mfma_f32_16x16x16bf16_1k(af, bfr[bj][n], z4, 0, 0, 0);
;                 int c = bj * 128 + wc * 32 + n * 16 + fr;
;                 float bb = bias[c];
;                 float ls[4];
; #pragma unroll
;                 for (int j = 0; j < 4; ++j) {
;                   float z = z4[j] + bb;
;                   ls[j] = (fminf(z, 0.f) - __logf(1.f + __expf(-fabsf(z)))) * (1.f / 16.f);
;                 }
;                 store_rm4(dst, 256, row0, c, ls[0], ls[1], ls[2], ls[3], fr & 1);
;               }
;             __builtin_amdgcn_sched_barrier(0);
	v_sub_f32_e32 v200, v200, v216
	v_sub_f32_e32 v201, v201, v217
	v_sub_f32_e32 v202, v202, v218
	v_sub_f32_e32 v203, v203, v219
	v_sub_f32_e32 v204, v204, v220
	v_sub_f32_e32 v205, v205, v221
	v_sub_f32_e32 v206, v206, v222
	v_sub_f32_e32 v207, v207, v223
	v_mul_f32_e32 v184, 0x3d800000, v200
	v_mul_f32_e32 v185, 0x3d800000, v201
	v_mul_f32_e32 v186, 0x3d800000, v202
	v_mul_f32_e32 v187, 0x3d800000, v203
	v_mul_f32_e32 v188, 0x3d800000, v204
	v_mul_f32_e32 v189, 0x3d800000, v205
	v_mul_f32_e32 v190, 0x3d800000, v206
	v_mul_f32_e32 v191, 0x3d800000, v207
	v_add_f32_e32 v192, v178, v192
	v_add_f32_e32 v193, v178, v193
	v_add_f32_e32 v194, v178, v194
	v_add_f32_e32 v195, v178, v195
	v_add_f32_e32 v196, v179, v196
	v_add_f32_e32 v197, v179, v197
	v_add_f32_e32 v198, v179, v198
	v_add_f32_e32 v199, v179, v199
	v_min_f32_e32 v200, 0, v192
	v_min_f32_e32 v201, 0, v193
	v_min_f32_e32 v202, 0, v194
	v_min_f32_e32 v203, 0, v195
	v_min_f32_e32 v204, 0, v196
	v_min_f32_e32 v205, 0, v197
	v_min_f32_e32 v206, 0, v198
	v_min_f32_e32 v207, 0, v199
	v_mul_f32_e64 v208, |v192|, s93
	v_mul_f32_e64 v209, |v193|, s93
	v_mul_f32_e64 v210, |v194|, s93
	v_mul_f32_e64 v211, |v195|, s93
	v_mul_f32_e64 v212, |v196|, s93
	v_mul_f32_e64 v213, |v197|, s93
	v_mul_f32_e64 v214, |v198|, s93
	v_mul_f32_e64 v215, |v199|, s93
	v_exp_f32_e32 v208, v208
	v_exp_f32_e32 v209, v209
	v_exp_f32_e32 v210, v210
	v_exp_f32_e32 v211, v211
	v_exp_f32_e32 v212, v212
	v_exp_f32_e32 v213, v213
	v_exp_f32_e32 v214, v214
	v_exp_f32_e32 v215, v215
	v_add_f32_e32 v208, 1.0, v208
	v_add_f32_e32 v209, 1.0, v209
	v_add_f32_e32 v210, 1.0, v210
	v_add_f32_e32 v211, 1.0, v211
	v_add_f32_e32 v212, 1.0, v212
	v_add_f32_e32 v213, 1.0, v213
	v_add_f32_e32 v214, 1.0, v214
	v_add_f32_e32 v215, 1.0, v215
	v_log_f32_e32 v208, v208
	v_log_f32_e32 v209, v209
	v_log_f32_e32 v210, v210
	v_log_f32_e32 v211, v211
	v_log_f32_e32 v212, v212
	v_log_f32_e32 v213, v213
	v_log_f32_e32 v214, v214
	v_log_f32_e32 v215, v215
	v_mul_f32_e32 v216, 0x3f317217, v208
	v_mul_f32_e32 v217, 0x3f317217, v209
	v_mul_f32_e32 v218, 0x3f317217, v210
	v_mul_f32_e32 v219, 0x3f317217, v211
	v_mul_f32_e32 v220, 0x3f317217, v212
	v_mul_f32_e32 v221, 0x3f317217, v213
	v_mul_f32_e32 v222, 0x3f317217, v214
	v_mul_f32_e32 v223, 0x3f317217, v215
	v_fma_f32 v216, v208, s95, -v216
	v_fma_f32 v217, v209, s95, -v217
	v_fma_f32 v218, v210, s95, -v218
	v_fma_f32 v219, v211, s95, -v219
	v_fma_f32 v220, v212, s95, -v220
	v_fma_f32 v221, v213, s95, -v221
	v_fma_f32 v222, v214, s95, -v222
	v_fma_f32 v223, v215, s95, -v223
	v_fmac_f32_e32 v216, 0x3377d1cf, v208
	v_fmac_f32_e32 v217, 0x3377d1cf, v209
	v_fmac_f32_e32 v218, 0x3377d1cf, v210
	v_fmac_f32_e32 v219, 0x3377d1cf, v211
	v_fmac_f32_e32 v220, 0x3377d1cf, v212
	v_fmac_f32_e32 v221, 0x3377d1cf, v213
	v_fmac_f32_e32 v222, 0x3377d1cf, v214
	v_fmac_f32_e32 v223, 0x3377d1cf, v215
	v_fmac_f32_e32 v216, 0x3f317217, v208
	v_fmac_f32_e32 v217, 0x3f317217, v209
	v_fmac_f32_e32 v218, 0x3f317217, v210
	v_fmac_f32_e32 v219, 0x3f317217, v211
	v_fmac_f32_e32 v220, 0x3f317217, v212
	v_fmac_f32_e32 v221, 0x3f317217, v213
	v_fmac_f32_e32 v222, 0x3f317217, v214
	v_fmac_f32_e32 v223, 0x3f317217, v215
	v_sub_f32_e32 v200, v200, v216
	v_sub_f32_e32 v201, v201, v217
	v_sub_f32_e32 v202, v202, v218
	v_sub_f32_e32 v203, v203, v219
	v_sub_f32_e32 v204, v204, v220
	v_sub_f32_e32 v205, v205, v221
	v_sub_f32_e32 v206, v206, v222
	v_sub_f32_e32 v207, v207, v223
	v_mul_f32_e32 v192, 0x3d800000, v200
	v_mul_f32_e32 v193, 0x3d800000, v201
	v_mul_f32_e32 v194, 0x3d800000, v202
	v_mul_f32_e32 v195, 0x3d800000, v203
	v_mul_f32_e32 v196, 0x3d800000, v204
	v_mul_f32_e32 v197, 0x3d800000, v205
	v_mul_f32_e32 v198, 0x3d800000, v206
	v_mul_f32_e32 v199, 0x3d800000, v207
	v_cvt_pk_bf16_f32 v208, v184, v185
	v_cvt_pk_bf16_f32 v209, v186, v187
	v_cvt_pk_bf16_f32 v210, v188, v189
	v_cvt_pk_bf16_f32 v211, v190, v191
	v_cvt_pk_bf16_f32 v212, v192, v193
	v_cvt_pk_bf16_f32 v213, v194, v195
	v_cvt_pk_bf16_f32 v214, v196, v197
	v_cvt_pk_bf16_f32 v215, v198, v199
	v_mov_b32_dpp v216, v208 quad_perm:[1,0,3,2] row_mask:0xf bank_mask:0xf bound_ctrl:1
	v_mov_b32_dpp v217, v209 quad_perm:[1,0,3,2] row_mask:0xf bank_mask:0xf bound_ctrl:1
	v_mov_b32_dpp v218, v210 quad_perm:[1,0,3,2] row_mask:0xf bank_mask:0xf bound_ctrl:1
	v_mov_b32_dpp v219, v211 quad_perm:[1,0,3,2] row_mask:0xf bank_mask:0xf bound_ctrl:1
	v_mov_b32_dpp v220, v212 quad_perm:[1,0,3,2] row_mask:0xf bank_mask:0xf bound_ctrl:1
	v_mov_b32_dpp v221, v213 quad_perm:[1,0,3,2] row_mask:0xf bank_mask:0xf bound_ctrl:1
	v_mov_b32_dpp v222, v214 quad_perm:[1,0,3,2] row_mask:0xf bank_mask:0xf bound_ctrl:1
	v_mov_b32_dpp v223, v215 quad_perm:[1,0,3,2] row_mask:0xf bank_mask:0xf bound_ctrl:1
	v_perm_b32 v208, v216, v208, v164
	v_perm_b32 v209, v217, v209, v164
	v_perm_b32 v210, v218, v210, v164
	v_perm_b32 v211, v219, v211, v164
	v_perm_b32 v212, v220, v212, v164
	v_perm_b32 v213, v221, v213, v164
	v_perm_b32 v214, v222, v214, v164
	v_perm_b32 v215, v223, v215, v164
	global_store_dword v167, v208, s[8:9]
	global_store_dword v167, v209, s[8:9] offset:1024
	global_store_dword v167, v210, s[8:9] offset:32
	global_store_dword v167, v211, s[8:9] offset:1056
	global_store_dword v167, v212, s[8:9] offset:256
	global_store_dword v167, v213, s[8:9] offset:1280
	global_store_dword v167, v214, s[8:9] offset:288
	global_store_dword v167, v215, s[8:9] offset:1312
	ds_read_b64 v[180:181], v160 offset:59392
	v_add_u32_e32 v167, 0x14000, v163
	s_waitcnt lgkmcnt(0)
;   __device__ __forceinline__ void operator()(f32x4 (&acc)[2][2][4][2], int brow, int bcol, int wr, int wc, int fr, int fq) const {
;     ...
;                 f32x4 z4 = {0.f, 0.f, 0.f, 0.f};
;                 z4 = __builtin_amdgcn_mfma_f32_16x16x16bf16_1k(af, bfr[bj][n], z4, 0, 0, 0);
;                 int c = bj * 128 + wc * 32 + n * 16 + fr;
;                 float bb = bias[c];
;                 float ls[4];
; #pragma unroll
;                 for (int j = 0; j < 4; ++j) {
;                   float z = z4[j] + bb;
;                   ls[j] = (fminf(z, 0.f) - __logf(1.f + __expf(-fabsf(z)))) * (1.f / 16.f);
;                 }
;                 store_rm4(dst, 256, row0, c, ls[0], ls[1], ls[2], ls[3], fr & 1);
	v_mfma_f32_16x16x16_bf16 v[184:187], v[180:181], v[168:169], 0
	v_mfma_f32_16x16x16_bf16 v[188:191], v[180:181], v[170:171], 0
	v_mfma_f32_16x16x16_bf16 v[192:195], v[180:181], v[172:173], 0
	v_mfma_f32_16x16x16_bf16 v[196:199], v[180:181], v[174:175], 0
	s_nop 7
	s_nop 1
	v_add_f32_e32 v184, v176, v184
	v_add_f32_e32 v185, v176, v185
	v_add_f32_e32 v186, v176, v186
	v_add_f32_e32 v187, v176, v187
	v_add_f32_e32 v188, v177, v188
	v_add_f32_e32 v189, v177, v189
	v_add_f32_e32 v190, v177, v190
	v_add_f32_e32 v191, v177, v191
	v_min_f32_e32 v200, 0, v184
	v_min_f32_e32 v201, 0, v185
	v_min_f32_e32 v202, 0, v186
	v_min_f32_e32 v203, 0, v187
	v_min_f32_e32 v204, 0, v188
	v_min_f32_e32 v205, 0, v189
	v_min_f32_e32 v206, 0, v190
	v_min_f32_e32 v207, 0, v191
	v_mul_f32_e64 v208, |v184|, s93
	v_mul_f32_e64 v209, |v185|, s93
	v_mul_f32_e64 v210, |v186|, s93
	v_mul_f32_e64 v211, |v187|, s93
	v_mul_f32_e64 v212, |v188|, s93
	v_mul_f32_e64 v213, |v189|, s93
	v_mul_f32_e64 v214, |v190|, s93
	v_mul_f32_e64 v215, |v191|, s93
	v_exp_f32_e32 v208, v208
	v_exp_f32_e32 v209, v209
	v_exp_f32_e32 v210, v210
	v_exp_f32_e32 v211, v211
	v_exp_f32_e32 v212, v212
	v_exp_f32_e32 v213, v213
	v_exp_f32_e32 v214, v214
	v_exp_f32_e32 v215, v215
	v_add_f32_e32 v208, 1.0, v208
	v_add_f32_e32 v209, 1.0, v209
	v_add_f32_e32 v210, 1.0, v210
	v_add_f32_e32 v211, 1.0, v211
	v_add_f32_e32 v212, 1.0, v212
	v_add_f32_e32 v213, 1.0, v213
	v_add_f32_e32 v214, 1.0, v214
	v_add_f32_e32 v215, 1.0, v215
	v_log_f32_e32 v208, v208
	v_log_f32_e32 v209, v209
	v_log_f32_e32 v210, v210
	v_log_f32_e32 v211, v211
	v_log_f32_e32 v212, v212
	v_log_f32_e32 v213, v213
	v_log_f32_e32 v214, v214
	v_log_f32_e32 v215, v215
	v_mul_f32_e32 v216, 0x3f317217, v208
	v_mul_f32_e32 v217, 0x3f317217, v209
	v_mul_f32_e32 v218, 0x3f317217, v210
	v_mul_f32_e32 v219, 0x3f317217, v211
	v_mul_f32_e32 v220, 0x3f317217, v212
	v_mul_f32_e32 v221, 0x3f317217, v213
	v_mul_f32_e32 v222, 0x3f317217, v214
	v_mul_f32_e32 v223, 0x3f317217, v215
	v_fma_f32 v216, v208, s95, -v216
	v_fma_f32 v217, v209, s95, -v217
	v_fma_f32 v218, v210, s95, -v218
	v_fma_f32 v219, v211, s95, -v219
	v_fma_f32 v220, v212, s95, -v220
	v_fma_f32 v221, v213, s95, -v221
	v_fma_f32 v222, v214, s95, -v222
	v_fma_f32 v223, v215, s95, -v223
	v_fmac_f32_e32 v216, 0x3377d1cf, v208
	v_fmac_f32_e32 v217, 0x3377d1cf, v209
	v_fmac_f32_e32 v218, 0x3377d1cf, v210
	v_fmac_f32_e32 v219, 0x3377d1cf, v211
	v_fmac_f32_e32 v220, 0x3377d1cf, v212
	v_fmac_f32_e32 v221, 0x3377d1cf, v213
	v_fmac_f32_e32 v222, 0x3377d1cf, v214
	v_fmac_f32_e32 v223, 0x3377d1cf, v215
	v_fmac_f32_e32 v216, 0x3f317217, v208
	v_fmac_f32_e32 v217, 0x3f317217, v209
	v_fmac_f32_e32 v218, 0x3f317217, v210
	v_fmac_f32_e32 v219, 0x3f317217, v211
	v_fmac_f32_e32 v220, 0x3f317217, v212
	v_fmac_f32_e32 v221, 0x3f317217, v213
	v_fmac_f32_e32 v222, 0x3f317217, v214
	v_fmac_f32_e32 v223, 0x3f317217, v215
	v_sub_f32_e32 v200, v200, v216
	v_sub_f32_e32 v201, v201, v217
	v_sub_f32_e32 v202, v202, v218
	v_sub_f32_e32 v203, v203, v219
	v_sub_f32_e32 v204, v204, v220
	v_sub_f32_e32 v205, v205, v221
	v_sub_f32_e32 v206, v206, v222
	v_sub_f32_e32 v207, v207, v223
	v_mul_f32_e32 v184, 0x3d800000, v200
	v_mul_f32_e32 v185, 0x3d800000, v201
	v_mul_f32_e32 v186, 0x3d800000, v202
	v_mul_f32_e32 v187, 0x3d800000, v203
	v_mul_f32_e32 v188, 0x3d800000, v204
	v_mul_f32_e32 v189, 0x3d800000, v205
	v_mul_f32_e32 v190, 0x3d800000, v206
	v_mul_f32_e32 v191, 0x3d800000, v207
	v_add_f32_e32 v192, v178, v192
	v_add_f32_e32 v193, v178, v193
	v_add_f32_e32 v194, v178, v194
	v_add_f32_e32 v195, v178, v195
	v_add_f32_e32 v196, v179, v196
	v_add_f32_e32 v197, v179, v197
	v_add_f32_e32 v198, v179, v198
	v_add_f32_e32 v199, v179, v199
	v_min_f32_e32 v200, 0, v192
	v_min_f32_e32 v201, 0, v193
	v_min_f32_e32 v202, 0, v194
	v_min_f32_e32 v203, 0, v195
	v_min_f32_e32 v204, 0, v196
	v_min_f32_e32 v205, 0, v197
	v_min_f32_e32 v206, 0, v198
	v_min_f32_e32 v207, 0, v199
	v_mul_f32_e64 v208, |v192|, s93
	v_mul_f32_e64 v209, |v193|, s93
	v_mul_f32_e64 v210, |v194|, s93
	v_mul_f32_e64 v211, |v195|, s93
	v_mul_f32_e64 v212, |v196|, s93
	v_mul_f32_e64 v213, |v197|, s93
	v_mul_f32_e64 v214, |v198|, s93
	v_mul_f32_e64 v215, |v199|, s93
	v_exp_f32_e32 v208, v208
	v_exp_f32_e32 v209, v209
	v_exp_f32_e32 v210, v210
	v_exp_f32_e32 v211, v211
	v_exp_f32_e32 v212, v212
	v_exp_f32_e32 v213, v213
	v_exp_f32_e32 v214, v214
	v_exp_f32_e32 v215, v215
	v_add_f32_e32 v208, 1.0, v208
	v_add_f32_e32 v209, 1.0, v209
	v_add_f32_e32 v210, 1.0, v210
	v_add_f32_e32 v211, 1.0, v211
	v_add_f32_e32 v212, 1.0, v212
	v_add_f32_e32 v213, 1.0, v213
	v_add_f32_e32 v214, 1.0, v214
	v_add_f32_e32 v215, 1.0, v215
	v_log_f32_e32 v208, v208
	v_log_f32_e32 v209, v209
	v_log_f32_e32 v210, v210
	v_log_f32_e32 v211, v211
	v_log_f32_e32 v212, v212
	v_log_f32_e32 v213, v213
	v_log_f32_e32 v214, v214
	v_log_f32_e32 v215, v215
	v_mul_f32_e32 v216, 0x3f317217, v208
	v_mul_f32_e32 v217, 0x3f317217, v209
	v_mul_f32_e32 v218, 0x3f317217, v210
	v_mul_f32_e32 v219, 0x3f317217, v211
	v_mul_f32_e32 v220, 0x3f317217, v212
	v_mul_f32_e32 v221, 0x3f317217, v213
	v_mul_f32_e32 v222, 0x3f317217, v214
	v_mul_f32_e32 v223, 0x3f317217, v215
	v_fma_f32 v216, v208, s95, -v216
	v_fma_f32 v217, v209, s95, -v217
	v_fma_f32 v218, v210, s95, -v218
	v_fma_f32 v219, v211, s95, -v219
	v_fma_f32 v220, v212, s95, -v220
	v_fma_f32 v221, v213, s95, -v221
	v_fma_f32 v222, v214, s95, -v222
	v_fma_f32 v223, v215, s95, -v223
	v_fmac_f32_e32 v216, 0x3377d1cf, v208
	v_fmac_f32_e32 v217, 0x3377d1cf, v209
	v_fmac_f32_e32 v218, 0x3377d1cf, v210
	v_fmac_f32_e32 v219, 0x3377d1cf, v211
	v_fmac_f32_e32 v220, 0x3377d1cf, v212
; __device__ __forceinline__ void store_rm4(u16* dst, size_t ld, int row0, int c, float v0, float v1, float v2, float v3, bool odd) {
;   {
;     float s = odd ? v0 : v1, r = dpp_swap1(s);
;     float lo = odd ? r : v0, hi = odd ? v1 : r;
;     *(unsigned*)(dst + (size_t)(row0 + (odd ? 1 : 0)) * ld + (c - (odd ? 1 : 0))) = pack2(lo, hi);
;   }
;   {
;     float s = odd ? v2 : v3, r = dpp_swap1(s);
;     float lo = odd ? r : v2, hi = odd ? v3 : r;
;     *(unsigned*)(dst + (size_t)(row0 + 2 + (odd ? 1 : 0)) * ld + (c - (odd ? 1 : 0))) = pack2(lo, hi);
;   }
;   __device__ __forceinline__ void operator()(f32x4 (&acc)[2][2][4][2], int brow, int bcol, int wr, int wc, int fr, int fq) const {
;     ...
;                 f32x4 z4 = {0.f, 0.f, 0.f, 0.f};
;                 z4 = __builtin_amdgcn_mfma_f32_16x16x16bf16_1k(af, bfr[bj][n], z4, 0, 0, 0);
;                 int c = bj * 128 + wc * 32 + n * 16 + fr;
;                 float bb = bias[c];
;                 float ls[4];
; #pragma unroll
;                 for (int j = 0; j < 4; ++j) {
;                   float z = z4[j] + bb;
;                   ls[j] = (fminf(z, 0.f) - __logf(1.f + __expf(-fabsf(z)))) * (1.f / 16.f);
;                 }
;                 store_rm4(dst, 256, row0, c, ls[0], ls[1], ls[2], ls[3], fr & 1);
;               }
;             __builtin_amdgcn_sched_barrier(0);
	v_fmac_f32_e32 v221, 0x3377d1cf, v213
	v_fmac_f32_e32 v222, 0x3377d1cf, v214
	v_fmac_f32_e32 v223, 0x3377d1cf, v215
	v_fmac_f32_e32 v216, 0x3f317217, v208
	v_fmac_f32_e32 v217, 0x3f317217, v209
	v_fmac_f32_e32 v218, 0x3f317217, v210
	v_fmac_f32_e32 v219, 0x3f317217, v211
	v_fmac_f32_e32 v220, 0x3f317217, v212
	v_fmac_f32_e32 v221, 0x3f317217, v213
	v_fmac_f32_e32 v222, 0x3f317217, v214
	v_fmac_f32_e32 v223, 0x3f317217, v215
	v_sub_f32_e32 v200, v200, v216
	v_sub_f32_e32 v201, v201, v217
	v_sub_f32_e32 v202, v202, v218
	v_sub_f32_e32 v203, v203, v219
	v_sub_f32_e32 v204, v204, v220
	v_sub_f32_e32 v205, v205, v221
	v_sub_f32_e32 v206, v206, v222
	v_sub_f32_e32 v207, v207, v223
	v_mul_f32_e32 v192, 0x3d800000, v200
	v_mul_f32_e32 v193, 0x3d800000, v201
	v_mul_f32_e32 v194, 0x3d800000, v202
	v_mul_f32_e32 v195, 0x3d800000, v203
	v_mul_f32_e32 v196, 0x3d800000, v204
	v_mul_f32_e32 v197, 0x3d800000, v205
	v_mul_f32_e32 v198, 0x3d800000, v206
	v_mul_f32_e32 v199, 0x3d800000, v207
	v_cvt_pk_bf16_f32 v208, v184, v185
	v_cvt_pk_bf16_f32 v209, v186, v187
	v_cvt_pk_bf16_f32 v210, v188, v189
	v_cvt_pk_bf16_f32 v211, v190, v191
	v_cvt_pk_bf16_f32 v212, v192, v193
	v_cvt_pk_bf16_f32 v213, v194, v195
	v_cvt_pk_bf16_f32 v214, v196, v197
	v_cvt_pk_bf16_f32 v215, v198, v199
	v_mov_b32_dpp v216, v208 quad_perm:[1,0,3,2] row_mask:0xf bank_mask:0xf bound_ctrl:1
	v_mov_b32_dpp v217, v209 quad_perm:[1,0,3,2] row_mask:0xf bank_mask:0xf bound_ctrl:1
	v_mov_b32_dpp v218, v210 quad_perm:[1,0,3,2] row_mask:0xf bank_mask:0xf bound_ctrl:1
	v_mov_b32_dpp v219, v211 quad_perm:[1,0,3,2] row_mask:0xf bank_mask:0xf bound_ctrl:1
	v_mov_b32_dpp v220, v212 quad_perm:[1,0,3,2] row_mask:0xf bank_mask:0xf bound_ctrl:1
	v_mov_b32_dpp v221, v213 quad_perm:[1,0,3,2] row_mask:0xf bank_mask:0xf bound_ctrl:1
	v_mov_b32_dpp v222, v214 quad_perm:[1,0,3,2] row_mask:0xf bank_mask:0xf bound_ctrl:1
	v_mov_b32_dpp v223, v215 quad_perm:[1,0,3,2] row_mask:0xf bank_mask:0xf bound_ctrl:1
	v_perm_b32 v208, v216, v208, v164
	v_perm_b32 v209, v217, v209, v164
	v_perm_b32 v210, v218, v210, v164
	v_perm_b32 v211, v219, v211, v164
	v_perm_b32 v212, v220, v212, v164
	v_perm_b32 v213, v221, v213, v164
	v_perm_b32 v214, v222, v214, v164
	v_perm_b32 v215, v223, v215, v164
	global_store_dword v167, v208, s[8:9]
	global_store_dword v167, v209, s[8:9] offset:1024
	global_store_dword v167, v210, s[8:9] offset:32
	global_store_dword v167, v211, s[8:9] offset:1056
	global_store_dword v167, v212, s[8:9] offset:256
	global_store_dword v167, v213, s[8:9] offset:1280
	global_store_dword v167, v214, s[8:9] offset:288
	global_store_dword v167, v215, s[8:9] offset:1312
	ds_read_b64 v[180:181], v160 offset:60416
	v_add_u32_e32 v167, 0x16000, v163
	s_waitcnt lgkmcnt(0)
	v_mfma_f32_16x16x16_bf16 v[184:187], v[180:181], v[168:169], 0
	v_mfma_f32_16x16x16_bf16 v[188:191], v[180:181], v[170:171], 0
	v_mfma_f32_16x16x16_bf16 v[192:195], v[180:181], v[172:173], 0
	v_mfma_f32_16x16x16_bf16 v[196:199], v[180:181], v[174:175], 0
	s_nop 7
	s_nop 1
	v_add_f32_e32 v184, v176, v184
	v_add_f32_e32 v185, v176, v185
	v_add_f32_e32 v186, v176, v186
	v_add_f32_e32 v187, v176, v187
	v_add_f32_e32 v188, v177, v188
	v_add_f32_e32 v189, v177, v189
	v_add_f32_e32 v190, v177, v190
	v_add_f32_e32 v191, v177, v191
	v_min_f32_e32 v200, 0, v184
	v_min_f32_e32 v201, 0, v185
	v_min_f32_e32 v202, 0, v186
	v_min_f32_e32 v203, 0, v187
	v_min_f32_e32 v204, 0, v188
	v_min_f32_e32 v205, 0, v189
	v_min_f32_e32 v206, 0, v190
	v_min_f32_e32 v207, 0, v191
	v_mul_f32_e64 v208, |v184|, s93
	v_mul_f32_e64 v209, |v185|, s93
	v_mul_f32_e64 v210, |v186|, s93
	v_mul_f32_e64 v211, |v187|, s93
	v_mul_f32_e64 v212, |v188|, s93
	v_mul_f32_e64 v213, |v189|, s93
	v_mul_f32_e64 v214, |v190|, s93
	v_mul_f32_e64 v215, |v191|, s93
	v_exp_f32_e32 v208, v208
	v_exp_f32_e32 v209, v209
	v_exp_f32_e32 v210, v210
	v_exp_f32_e32 v211, v211
	v_exp_f32_e32 v212, v212
	v_exp_f32_e32 v213, v213
	v_exp_f32_e32 v214, v214
	v_exp_f32_e32 v215, v215
	v_add_f32_e32 v208, 1.0, v208
	v_add_f32_e32 v209, 1.0, v209
	v_add_f32_e32 v210, 1.0, v210
	v_add_f32_e32 v211, 1.0, v211
	v_add_f32_e32 v212, 1.0, v212
	v_add_f32_e32 v213, 1.0, v213
	v_add_f32_e32 v214, 1.0, v214
	v_add_f32_e32 v215, 1.0, v215
	v_log_f32_e32 v208, v208
	v_log_f32_e32 v209, v209
	v_log_f32_e32 v210, v210
	v_log_f32_e32 v211, v211
	v_log_f32_e32 v212, v212
	v_log_f32_e32 v213, v213
	v_log_f32_e32 v214, v214
	v_log_f32_e32 v215, v215
	v_mul_f32_e32 v216, 0x3f317217, v208
	v_mul_f32_e32 v217, 0x3f317217, v209
	v_mul_f32_e32 v218, 0x3f317217, v210
	v_mul_f32_e32 v219, 0x3f317217, v211
	v_mul_f32_e32 v220, 0x3f317217, v212
	v_mul_f32_e32 v221, 0x3f317217, v213
	v_mul_f32_e32 v222, 0x3f317217, v214
	v_mul_f32_e32 v223, 0x3f317217, v215
	v_fma_f32 v216, v208, s95, -v216
	v_fma_f32 v217, v209, s95, -v217
	v_fma_f32 v218, v210, s95, -v218
	v_fma_f32 v219, v211, s95, -v219
	v_fma_f32 v220, v212, s95, -v220
	v_fma_f32 v221, v213, s95, -v221
	v_fma_f32 v222, v214, s95, -v222
	v_fma_f32 v223, v215, s95, -v223
	v_fmac_f32_e32 v216, 0x3377d1cf, v208
	v_fmac_f32_e32 v217, 0x3377d1cf, v209
	v_fmac_f32_e32 v218, 0x3377d1cf, v210
	v_fmac_f32_e32 v219, 0x3377d1cf, v211
	v_fmac_f32_e32 v220, 0x3377d1cf, v212
	v_fmac_f32_e32 v221, 0x3377d1cf, v213
	v_fmac_f32_e32 v222, 0x3377d1cf, v214
	v_fmac_f32_e32 v223, 0x3377d1cf, v215
	v_fmac_f32_e32 v216, 0x3f317217, v208
	v_fmac_f32_e32 v217, 0x3f317217, v209
	v_fmac_f32_e32 v218, 0x3f317217, v210
	v_fmac_f32_e32 v219, 0x3f317217, v211
	v_fmac_f32_e32 v220, 0x3f317217, v212
	v_fmac_f32_e32 v221, 0x3f317217, v213
	v_fmac_f32_e32 v222, 0x3f317217, v214
	v_fmac_f32_e32 v223, 0x3f317217, v215
; __device__ __forceinline__ void store_rm4(u16* dst, size_t ld, int row0, int c, float v0, float v1, float v2, float v3, bool odd) {
;   {
;     float s = odd ? v0 : v1, r = dpp_swap1(s);
;     float lo = odd ? r : v0, hi = odd ? v1 : r;
;     *(unsigned*)(dst + (size_t)(row0 + (odd ? 1 : 0)) * ld + (c - (odd ? 1 : 0))) = pack2(lo, hi);
;   }
;   {
;     float s = odd ? v2 : v3, r = dpp_swap1(s);
;     float lo = odd ? r : v2, hi = odd ? v3 : r;
;     *(unsigned*)(dst + (size_t)(row0 + 2 + (odd ? 1 : 0)) * ld + (c - (odd ? 1 : 0))) = pack2(lo, hi);
;   }
;   __device__ __forceinline__ void operator()(f32x4 (&acc)[2][2][4][2], int brow, int bcol, int wr, int wc, int fr, int fq) const {
;     ...
;       for (int dir = 0; dir < 2; ++dir) {
;         s16x4 bfr[2][2];
; #pragma unroll
;         for (int bj = 0; bj < 2; ++bj)
; #pragma unroll
;           for (int n = 0; n < 2; ++n)
;             bfr[bj][n] = *(const s16x4*)(wgt + ((size_t)(dir * 256 + bj * 128 + wc * 32 + n * 16 + fr)) * 16 + fq * 4);
;         u16* dst = (u16*)(p.ws + (dir == 0 ? OFF_LAF : OFF_LAB));
;         const float* bias = dir == 0 ? p.bgf : p.bgb;
; #pragma unroll
;         for (int ai = 0; ai < 2; ++ai)
; #pragma unroll
;           for (int m = 0; m < 4; ++m) {
;             int rl = ai * 128 + wr * 64 + m * 16;
;             s16x4 af = *(const s16x4*)(glr + (rl + fr) * 32 + dir * 16 + fq * 4);
;             int row0 = brow + rl + fq * 4;
; #pragma unroll
;             for (int bj = 0; bj < 2; ++bj)
; #pragma unroll
;               for (int n = 0; n < 2; ++n) {
;                 f32x4 z4 = {0.f, 0.f, 0.f, 0.f};
;                 z4 = __builtin_amdgcn_mfma_f32_16x16x16bf16_1k(af, bfr[bj][n], z4, 0, 0, 0);
;                 int c = bj * 128 + wc * 32 + n * 16 + fr;
;                 float bb = bias[c];
;                 float ls[4];
; #pragma unroll
;                 for (int j = 0; j < 4; ++j) {
;                   float z = z4[j] + bb;
;                   ls[j] = (fminf(z, 0.f) - __logf(1.f + __expf(-fabsf(z)))) * (1.f / 16.f);
;                 }
;                 store_rm4(dst, 256, row0, c, ls[0], ls[1], ls[2], ls[3], fr & 1);
;               }
;             __builtin_amdgcn_sched_barrier(0);
	v_sub_f32_e32 v200, v200, v216
	v_sub_f32_e32 v201, v201, v217
	v_sub_f32_e32 v202, v202, v218
	v_sub_f32_e32 v203, v203, v219
	v_sub_f32_e32 v204, v204, v220
	v_sub_f32_e32 v205, v205, v221
	v_sub_f32_e32 v206, v206, v222
	v_sub_f32_e32 v207, v207, v223
	v_mul_f32_e32 v184, 0x3d800000, v200
	v_mul_f32_e32 v185, 0x3d800000, v201
	v_mul_f32_e32 v186, 0x3d800000, v202
	v_mul_f32_e32 v187, 0x3d800000, v203
	v_mul_f32_e32 v188, 0x3d800000, v204
	v_mul_f32_e32 v189, 0x3d800000, v205
	v_mul_f32_e32 v190, 0x3d800000, v206
	v_mul_f32_e32 v191, 0x3d800000, v207
	v_add_f32_e32 v192, v178, v192
	v_add_f32_e32 v193, v178, v193
	v_add_f32_e32 v194, v178, v194
	v_add_f32_e32 v195, v178, v195
	v_add_f32_e32 v196, v179, v196
	v_add_f32_e32 v197, v179, v197
	v_add_f32_e32 v198, v179, v198
	v_add_f32_e32 v199, v179, v199
	v_min_f32_e32 v200, 0, v192
	v_min_f32_e32 v201, 0, v193
	v_min_f32_e32 v202, 0, v194
	v_min_f32_e32 v203, 0, v195
	v_min_f32_e32 v204, 0, v196
	v_min_f32_e32 v205, 0, v197
	v_min_f32_e32 v206, 0, v198
	v_min_f32_e32 v207, 0, v199
	v_mul_f32_e64 v208, |v192|, s93
	v_mul_f32_e64 v209, |v193|, s93
	v_mul_f32_e64 v210, |v194|, s93
	v_mul_f32_e64 v211, |v195|, s93
	v_mul_f32_e64 v212, |v196|, s93
	v_mul_f32_e64 v213, |v197|, s93
	v_mul_f32_e64 v214, |v198|, s93
	v_mul_f32_e64 v215, |v199|, s93
	v_exp_f32_e32 v208, v208
	v_exp_f32_e32 v209, v209
	v_exp_f32_e32 v210, v210
	v_exp_f32_e32 v211, v211
	v_exp_f32_e32 v212, v212
	v_exp_f32_e32 v213, v213
	v_exp_f32_e32 v214, v214
	v_exp_f32_e32 v215, v215
	v_add_f32_e32 v208, 1.0, v208
	v_add_f32_e32 v209, 1.0, v209
	v_add_f32_e32 v210, 1.0, v210
	v_add_f32_e32 v211, 1.0, v211
	v_add_f32_e32 v212, 1.0, v212
	v_add_f32_e32 v213, 1.0, v213
	v_add_f32_e32 v214, 1.0, v214
	v_add_f32_e32 v215, 1.0, v215
	v_log_f32_e32 v208, v208
	v_log_f32_e32 v209, v209
	v_log_f32_e32 v210, v210
	v_log_f32_e32 v211, v211
	v_log_f32_e32 v212, v212
	v_log_f32_e32 v213, v213
	v_log_f32_e32 v214, v214
	v_log_f32_e32 v215, v215
	v_mul_f32_e32 v216, 0x3f317217, v208
	v_mul_f32_e32 v217, 0x3f317217, v209
	v_mul_f32_e32 v218, 0x3f317217, v210
	v_mul_f32_e32 v219, 0x3f317217, v211
	v_mul_f32_e32 v220, 0x3f317217, v212
	v_mul_f32_e32 v221, 0x3f317217, v213
	v_mul_f32_e32 v222, 0x3f317217, v214
	v_mul_f32_e32 v223, 0x3f317217, v215
	v_fma_f32 v216, v208, s95, -v216
	v_fma_f32 v217, v209, s95, -v217
	v_fma_f32 v218, v210, s95, -v218
	v_fma_f32 v219, v211, s95, -v219
	v_fma_f32 v220, v212, s95, -v220
	v_fma_f32 v221, v213, s95, -v221
	v_fma_f32 v222, v214, s95, -v222
	v_fma_f32 v223, v215, s95, -v223
	v_fmac_f32_e32 v216, 0x3377d1cf, v208
	v_fmac_f32_e32 v217, 0x3377d1cf, v209
	v_fmac_f32_e32 v218, 0x3377d1cf, v210
	v_fmac_f32_e32 v219, 0x3377d1cf, v211
	v_fmac_f32_e32 v220, 0x3377d1cf, v212
	v_fmac_f32_e32 v221, 0x3377d1cf, v213
	v_fmac_f32_e32 v222, 0x3377d1cf, v214
	v_fmac_f32_e32 v223, 0x3377d1cf, v215
	v_fmac_f32_e32 v216, 0x3f317217, v208
	v_fmac_f32_e32 v217, 0x3f317217, v209
	v_fmac_f32_e32 v218, 0x3f317217, v210
	v_fmac_f32_e32 v219, 0x3f317217, v211
	v_fmac_f32_e32 v220, 0x3f317217, v212
	v_fmac_f32_e32 v221, 0x3f317217, v213
	v_fmac_f32_e32 v222, 0x3f317217, v214
	v_fmac_f32_e32 v223, 0x3f317217, v215
	v_sub_f32_e32 v200, v200, v216
	v_sub_f32_e32 v201, v201, v217
	v_sub_f32_e32 v202, v202, v218
	v_sub_f32_e32 v203, v203, v219
	v_sub_f32_e32 v204, v204, v220
	v_sub_f32_e32 v205, v205, v221
	v_sub_f32_e32 v206, v206, v222
	v_sub_f32_e32 v207, v207, v223
	v_mul_f32_e32 v192, 0x3d800000, v200
	v_mul_f32_e32 v193, 0x3d800000, v201
	v_mul_f32_e32 v194, 0x3d800000, v202
	v_mul_f32_e32 v195, 0x3d800000, v203
	v_mul_f32_e32 v196, 0x3d800000, v204
	v_mul_f32_e32 v197, 0x3d800000, v205
	v_mul_f32_e32 v198, 0x3d800000, v206
	v_mul_f32_e32 v199, 0x3d800000, v207
	v_cvt_pk_bf16_f32 v208, v184, v185
	v_cvt_pk_bf16_f32 v209, v186, v187
	v_cvt_pk_bf16_f32 v210, v188, v189
	v_cvt_pk_bf16_f32 v211, v190, v191
	v_cvt_pk_bf16_f32 v212, v192, v193
	v_cvt_pk_bf16_f32 v213, v194, v195
	v_cvt_pk_bf16_f32 v214, v196, v197
	v_cvt_pk_bf16_f32 v215, v198, v199
	v_mov_b32_dpp v216, v208 quad_perm:[1,0,3,2] row_mask:0xf bank_mask:0xf bound_ctrl:1
	v_mov_b32_dpp v217, v209 quad_perm:[1,0,3,2] row_mask:0xf bank_mask:0xf bound_ctrl:1
	v_mov_b32_dpp v218, v210 quad_perm:[1,0,3,2] row_mask:0xf bank_mask:0xf bound_ctrl:1
	v_mov_b32_dpp v219, v211 quad_perm:[1,0,3,2] row_mask:0xf bank_mask:0xf bound_ctrl:1
	v_mov_b32_dpp v220, v212 quad_perm:[1,0,3,2] row_mask:0xf bank_mask:0xf bound_ctrl:1
	v_mov_b32_dpp v221, v213 quad_perm:[1,0,3,2] row_mask:0xf bank_mask:0xf bound_ctrl:1
	v_mov_b32_dpp v222, v214 quad_perm:[1,0,3,2] row_mask:0xf bank_mask:0xf bound_ctrl:1
	v_mov_b32_dpp v223, v215 quad_perm:[1,0,3,2] row_mask:0xf bank_mask:0xf bound_ctrl:1
	v_perm_b32 v208, v216, v208, v164
	v_perm_b32 v209, v217, v209, v164
	v_perm_b32 v210, v218, v210, v164
	v_perm_b32 v211, v219, v211, v164
	v_perm_b32 v212, v220, v212, v164
	v_perm_b32 v213, v221, v213, v164
	v_perm_b32 v214, v222, v214, v164
	v_perm_b32 v215, v223, v215, v164
	global_store_dword v167, v208, s[8:9]
	global_store_dword v167, v209, s[8:9] offset:1024
	global_store_dword v167, v210, s[8:9] offset:32
	global_store_dword v167, v211, s[8:9] offset:1056
	global_store_dword v167, v212, s[8:9] offset:256
	global_store_dword v167, v213, s[8:9] offset:1280
	global_store_dword v167, v214, s[8:9] offset:288
	global_store_dword v167, v215, s[8:9] offset:1312
	s_add_u32 s4, s40, 0x2000
	s_addc_u32 s5, s41, 0
	s_add_u32 s8, s14, s0
	s_addc_u32 s9, s15, 0
	global_load_dwordx2 v[168:169], v161, s[4:5]
	global_load_dwordx2 v[170:171], v161, s[4:5] offset:512
	global_load_dwordx2 v[172:173], v224, s[4:5]
	global_load_dwordx2 v[174:175], v224, s[4:5] offset:512
	global_load_dword v176, v162, s[66:67]
	global_load_dword v177, v162, s[66:67] offset:64
	global_load_dword v178, v162, s[66:67] offset:512
	global_load_dword v179, v162, s[66:67] offset:576
	ds_read_b64 v[180:181], v160 offset:49184
	v_mov_b32_e32 v167, v163
	s_waitcnt vmcnt(0) lgkmcnt(0)
;   __device__ __forceinline__ void operator()(f32x4 (&acc)[2][2][4][2], int brow, int bcol, int wr, int wc, int fr, int fq) const {
;     ...
;                 f32x4 z4 = {0.f, 0.f, 0.f, 0.f};
;                 z4 = __builtin_amdgcn_mfma_f32_16x16x16bf16_1k(af, bfr[bj][n], z4, 0, 0, 0);
;                 int c = bj * 128 + wc * 32 + n * 16 + fr;
;                 float bb = bias[c];
;                 float ls[4];
; #pragma unroll
;                 for (int j = 0; j < 4; ++j) {
;                   float z = z4[j] + bb;
;                   ls[j] = (fminf(z, 0.f) - __logf(1.f + __expf(-fabsf(z)))) * (1.f / 16.f);
;                 }
;                 store_rm4(dst, 256, row0, c, ls[0], ls[1], ls[2], ls[3], fr & 1);
	v_mfma_f32_16x16x16_bf16 v[184:187], v[180:181], v[168:169], 0
	v_mfma_f32_16x16x16_bf16 v[188:191], v[180:181], v[170:171], 0
	v_mfma_f32_16x16x16_bf16 v[192:195], v[180:181], v[172:173], 0
	v_mfma_f32_16x16x16_bf16 v[196:199], v[180:181], v[174:175], 0
	s_nop 7
	s_nop 1
	v_add_f32_e32 v184, v176, v184
	v_add_f32_e32 v185, v176, v185
	v_add_f32_e32 v186, v176, v186
	v_add_f32_e32 v187, v176, v187
	v_add_f32_e32 v188, v177, v188
	v_add_f32_e32 v189, v177, v189
	v_add_f32_e32 v190, v177, v190
	v_add_f32_e32 v191, v177, v191
	v_min_f32_e32 v200, 0, v184
	v_min_f32_e32 v201, 0, v185
	v_min_f32_e32 v202, 0, v186
	v_min_f32_e32 v203, 0, v187
	v_min_f32_e32 v204, 0, v188
	v_min_f32_e32 v205, 0, v189
	v_min_f32_e32 v206, 0, v190
	v_min_f32_e32 v207, 0, v191
	v_mul_f32_e64 v208, |v184|, s93
	v_mul_f32_e64 v209, |v185|, s93
	v_mul_f32_e64 v210, |v186|, s93
	v_mul_f32_e64 v211, |v187|, s93
	v_mul_f32_e64 v212, |v188|, s93
	v_mul_f32_e64 v213, |v189|, s93
	v_mul_f32_e64 v214, |v190|, s93
	v_mul_f32_e64 v215, |v191|, s93
	v_exp_f32_e32 v208, v208
	v_exp_f32_e32 v209, v209
	v_exp_f32_e32 v210, v210
	v_exp_f32_e32 v211, v211
	v_exp_f32_e32 v212, v212
	v_exp_f32_e32 v213, v213
	v_exp_f32_e32 v214, v214
	v_exp_f32_e32 v215, v215
	v_add_f32_e32 v208, 1.0, v208
	v_add_f32_e32 v209, 1.0, v209
	v_add_f32_e32 v210, 1.0, v210
	v_add_f32_e32 v211, 1.0, v211
	v_add_f32_e32 v212, 1.0, v212
	v_add_f32_e32 v213, 1.0, v213
	v_add_f32_e32 v214, 1.0, v214
	v_add_f32_e32 v215, 1.0, v215
	v_log_f32_e32 v208, v208
	v_log_f32_e32 v209, v209
	v_log_f32_e32 v210, v210
	v_log_f32_e32 v211, v211
	v_log_f32_e32 v212, v212
	v_log_f32_e32 v213, v213
	v_log_f32_e32 v214, v214
	v_log_f32_e32 v215, v215
	v_mul_f32_e32 v216, 0x3f317217, v208
	v_mul_f32_e32 v217, 0x3f317217, v209
	v_mul_f32_e32 v218, 0x3f317217, v210
	v_mul_f32_e32 v219, 0x3f317217, v211
	v_mul_f32_e32 v220, 0x3f317217, v212
	v_mul_f32_e32 v221, 0x3f317217, v213
	v_mul_f32_e32 v222, 0x3f317217, v214
	v_mul_f32_e32 v223, 0x3f317217, v215
	v_fma_f32 v216, v208, s95, -v216
	v_fma_f32 v217, v209, s95, -v217
	v_fma_f32 v218, v210, s95, -v218
	v_fma_f32 v219, v211, s95, -v219
	v_fma_f32 v220, v212, s95, -v220
	v_fma_f32 v221, v213, s95, -v221
	v_fma_f32 v222, v214, s95, -v222
	v_fma_f32 v223, v215, s95, -v223
	v_fmac_f32_e32 v216, 0x3377d1cf, v208
	v_fmac_f32_e32 v217, 0x3377d1cf, v209
	v_fmac_f32_e32 v218, 0x3377d1cf, v210
	v_fmac_f32_e32 v219, 0x3377d1cf, v211
	v_fmac_f32_e32 v220, 0x3377d1cf, v212
	v_fmac_f32_e32 v221, 0x3377d1cf, v213
	v_fmac_f32_e32 v222, 0x3377d1cf, v214
	v_fmac_f32_e32 v223, 0x3377d1cf, v215
	v_fmac_f32_e32 v216, 0x3f317217, v208
	v_fmac_f32_e32 v217, 0x3f317217, v209
	v_fmac_f32_e32 v218, 0x3f317217, v210
	v_fmac_f32_e32 v219, 0x3f317217, v211
	v_fmac_f32_e32 v220, 0x3f317217, v212
	v_fmac_f32_e32 v221, 0x3f317217, v213
	v_fmac_f32_e32 v222, 0x3f317217, v214
	v_fmac_f32_e32 v223, 0x3f317217, v215
	v_sub_f32_e32 v200, v200, v216
	v_sub_f32_e32 v201, v201, v217
	v_sub_f32_e32 v202, v202, v218
	v_sub_f32_e32 v203, v203, v219
	v_sub_f32_e32 v204, v204, v220
	v_sub_f32_e32 v205, v205, v221
	v_sub_f32_e32 v206, v206, v222
	v_sub_f32_e32 v207, v207, v223
	v_mul_f32_e32 v184, 0x3d800000, v200
	v_mul_f32_e32 v185, 0x3d800000, v201
	v_mul_f32_e32 v186, 0x3d800000, v202
	v_mul_f32_e32 v187, 0x3d800000, v203
	v_mul_f32_e32 v188, 0x3d800000, v204
	v_mul_f32_e32 v189, 0x3d800000, v205
	v_mul_f32_e32 v190, 0x3d800000, v206
	v_mul_f32_e32 v191, 0x3d800000, v207
	v_add_f32_e32 v192, v178, v192
	v_add_f32_e32 v193, v178, v193
	v_add_f32_e32 v194, v178, v194
	v_add_f32_e32 v195, v178, v195
	v_add_f32_e32 v196, v179, v196
	v_add_f32_e32 v197, v179, v197
	v_add_f32_e32 v198, v179, v198
	v_add_f32_e32 v199, v179, v199
	v_min_f32_e32 v200, 0, v192
	v_min_f32_e32 v201, 0, v193
	v_min_f32_e32 v202, 0, v194
	v_min_f32_e32 v203, 0, v195
	v_min_f32_e32 v204, 0, v196
	v_min_f32_e32 v205, 0, v197
	v_min_f32_e32 v206, 0, v198
	v_min_f32_e32 v207, 0, v199
	v_mul_f32_e64 v208, |v192|, s93
	v_mul_f32_e64 v209, |v193|, s93
	v_mul_f32_e64 v210, |v194|, s93
	v_mul_f32_e64 v211, |v195|, s93
	v_mul_f32_e64 v212, |v196|, s93
	v_mul_f32_e64 v213, |v197|, s93
	v_mul_f32_e64 v214, |v198|, s93
	v_mul_f32_e64 v215, |v199|, s93
	v_exp_f32_e32 v208, v208
	v_exp_f32_e32 v209, v209
	v_exp_f32_e32 v210, v210
	v_exp_f32_e32 v211, v211
	v_exp_f32_e32 v212, v212
	v_exp_f32_e32 v213, v213
	v_exp_f32_e32 v214, v214
	v_exp_f32_e32 v215, v215
	v_add_f32_e32 v208, 1.0, v208
	v_add_f32_e32 v209, 1.0, v209
	v_add_f32_e32 v210, 1.0, v210
	v_add_f32_e32 v211, 1.0, v211
	v_add_f32_e32 v212, 1.0, v212
	v_add_f32_e32 v213, 1.0, v213
	v_add_f32_e32 v214, 1.0, v214
	v_add_f32_e32 v215, 1.0, v215
	v_log_f32_e32 v208, v208
	v_log_f32_e32 v209, v209
	v_log_f32_e32 v210, v210
	v_log_f32_e32 v211, v211
	v_log_f32_e32 v212, v212
	v_log_f32_e32 v213, v213
	v_log_f32_e32 v214, v214
	v_log_f32_e32 v215, v215
	v_mul_f32_e32 v216, 0x3f317217, v208
	v_mul_f32_e32 v217, 0x3f317217, v209
	v_mul_f32_e32 v218, 0x3f317217, v210
	v_mul_f32_e32 v219, 0x3f317217, v211
	v_mul_f32_e32 v220, 0x3f317217, v212
	v_mul_f32_e32 v221, 0x3f317217, v213
	v_mul_f32_e32 v222, 0x3f317217, v214
	v_mul_f32_e32 v223, 0x3f317217, v215
	v_fma_f32 v216, v208, s95, -v216
	v_fma_f32 v217, v209, s95, -v217
	v_fma_f32 v218, v210, s95, -v218
	v_fma_f32 v219, v211, s95, -v219
	v_fma_f32 v220, v212, s95, -v220
	v_fma_f32 v221, v213, s95, -v221
	v_fma_f32 v222, v214, s95, -v222
	v_fma_f32 v223, v215, s95, -v223
	v_fmac_f32_e32 v216, 0x3377d1cf, v208
	v_fmac_f32_e32 v217, 0x3377d1cf, v209
	v_fmac_f32_e32 v218, 0x3377d1cf, v210
	v_fmac_f32_e32 v219, 0x3377d1cf, v211
	v_fmac_f32_e32 v220, 0x3377d1cf, v212
; __device__ __forceinline__ void store_rm4(u16* dst, size_t ld, int row0, int c, float v0, float v1, float v2, float v3, bool odd) {
;   {
;     float s = odd ? v0 : v1, r = dpp_swap1(s);
;     float lo = odd ? r : v0, hi = odd ? v1 : r;
;     *(unsigned*)(dst + (size_t)(row0 + (odd ? 1 : 0)) * ld + (c - (odd ? 1 : 0))) = pack2(lo, hi);
;   }
;   {
;     float s = odd ? v2 : v3, r = dpp_swap1(s);
;     float lo = odd ? r : v2, hi = odd ? v3 : r;
;     *(unsigned*)(dst + (size_t)(row0 + 2 + (odd ? 1 : 0)) * ld + (c - (odd ? 1 : 0))) = pack2(lo, hi);
;   }
;   __device__ __forceinline__ void operator()(f32x4 (&acc)[2][2][4][2], int brow, int bcol, int wr, int wc, int fr, int fq) const {
;     ...
;                 f32x4 z4 = {0.f, 0.f, 0.f, 0.f};
;                 z4 = __builtin_amdgcn_mfma_f32_16x16x16bf16_1k(af, bfr[bj][n], z4, 0, 0, 0);
;                 int c = bj * 128 + wc * 32 + n * 16 + fr;
;                 float bb = bias[c];
;                 float ls[4];
; #pragma unroll
;                 for (int j = 0; j < 4; ++j) {
;                   float z = z4[j] + bb;
;                   ls[j] = (fminf(z, 0.f) - __logf(1.f + __expf(-fabsf(z)))) * (1.f / 16.f);
;                 }
;                 store_rm4(dst, 256, row0, c, ls[0], ls[1], ls[2], ls[3], fr & 1);
;               }
;             __builtin_amdgcn_sched_barrier(0);
	v_fmac_f32_e32 v221, 0x3377d1cf, v213
	v_fmac_f32_e32 v222, 0x3377d1cf, v214
	v_fmac_f32_e32 v223, 0x3377d1cf, v215
	v_fmac_f32_e32 v216, 0x3f317217, v208
	v_fmac_f32_e32 v217, 0x3f317217, v209
	v_fmac_f32_e32 v218, 0x3f317217, v210
	v_fmac_f32_e32 v219, 0x3f317217, v211
	v_fmac_f32_e32 v220, 0x3f317217, v212
	v_fmac_f32_e32 v221, 0x3f317217, v213
	v_fmac_f32_e32 v222, 0x3f317217, v214
	v_fmac_f32_e32 v223, 0x3f317217, v215
	v_sub_f32_e32 v200, v200, v216
	v_sub_f32_e32 v201, v201, v217
	v_sub_f32_e32 v202, v202, v218
	v_sub_f32_e32 v203, v203, v219
	v_sub_f32_e32 v204, v204, v220
	v_sub_f32_e32 v205, v205, v221
	v_sub_f32_e32 v206, v206, v222
	v_sub_f32_e32 v207, v207, v223
	v_mul_f32_e32 v192, 0x3d800000, v200
	v_mul_f32_e32 v193, 0x3d800000, v201
	v_mul_f32_e32 v194, 0x3d800000, v202
	v_mul_f32_e32 v195, 0x3d800000, v203
	v_mul_f32_e32 v196, 0x3d800000, v204
	v_mul_f32_e32 v197, 0x3d800000, v205
	v_mul_f32_e32 v198, 0x3d800000, v206
	v_mul_f32_e32 v199, 0x3d800000, v207
	v_cvt_pk_bf16_f32 v208, v184, v185
	v_cvt_pk_bf16_f32 v209, v186, v187
	v_cvt_pk_bf16_f32 v210, v188, v189
	v_cvt_pk_bf16_f32 v211, v190, v191
	v_cvt_pk_bf16_f32 v212, v192, v193
	v_cvt_pk_bf16_f32 v213, v194, v195
	v_cvt_pk_bf16_f32 v214, v196, v197
	v_cvt_pk_bf16_f32 v215, v198, v199
	v_mov_b32_dpp v216, v208 quad_perm:[1,0,3,2] row_mask:0xf bank_mask:0xf bound_ctrl:1
	v_mov_b32_dpp v217, v209 quad_perm:[1,0,3,2] row_mask:0xf bank_mask:0xf bound_ctrl:1
	v_mov_b32_dpp v218, v210 quad_perm:[1,0,3,2] row_mask:0xf bank_mask:0xf bound_ctrl:1
	v_mov_b32_dpp v219, v211 quad_perm:[1,0,3,2] row_mask:0xf bank_mask:0xf bound_ctrl:1
	v_mov_b32_dpp v220, v212 quad_perm:[1,0,3,2] row_mask:0xf bank_mask:0xf bound_ctrl:1
	v_mov_b32_dpp v221, v213 quad_perm:[1,0,3,2] row_mask:0xf bank_mask:0xf bound_ctrl:1
	v_mov_b32_dpp v222, v214 quad_perm:[1,0,3,2] row_mask:0xf bank_mask:0xf bound_ctrl:1
	v_mov_b32_dpp v223, v215 quad_perm:[1,0,3,2] row_mask:0xf bank_mask:0xf bound_ctrl:1
	v_perm_b32 v208, v216, v208, v164
	v_perm_b32 v209, v217, v209, v164
	v_perm_b32 v210, v218, v210, v164
	v_perm_b32 v211, v219, v211, v164
	v_perm_b32 v212, v220, v212, v164
	v_perm_b32 v213, v221, v213, v164
	v_perm_b32 v214, v222, v214, v164
	v_perm_b32 v215, v223, v215, v164
	global_store_dword v167, v208, s[8:9]
	global_store_dword v167, v209, s[8:9] offset:1024
	global_store_dword v167, v210, s[8:9] offset:32
	global_store_dword v167, v211, s[8:9] offset:1056
	global_store_dword v167, v212, s[8:9] offset:256
	global_store_dword v167, v213, s[8:9] offset:1280
	global_store_dword v167, v214, s[8:9] offset:288
	global_store_dword v167, v215, s[8:9] offset:1312
	ds_read_b64 v[180:181], v160 offset:50208
	v_add_u32_e32 v167, 0x2000, v163
	s_waitcnt lgkmcnt(0)
	v_mfma_f32_16x16x16_bf16 v[184:187], v[180:181], v[168:169], 0
	v_mfma_f32_16x16x16_bf16 v[188:191], v[180:181], v[170:171], 0
	v_mfma_f32_16x16x16_bf16 v[192:195], v[180:181], v[172:173], 0
	v_mfma_f32_16x16x16_bf16 v[196:199], v[180:181], v[174:175], 0
	s_nop 7
	s_nop 1
	v_add_f32_e32 v184, v176, v184
	v_add_f32_e32 v185, v176, v185
	v_add_f32_e32 v186, v176, v186
	v_add_f32_e32 v187, v176, v187
	v_add_f32_e32 v188, v177, v188
	v_add_f32_e32 v189, v177, v189
	v_add_f32_e32 v190, v177, v190
	v_add_f32_e32 v191, v177, v191
	v_min_f32_e32 v200, 0, v184
	v_min_f32_e32 v201, 0, v185
	v_min_f32_e32 v202, 0, v186
	v_min_f32_e32 v203, 0, v187
	v_min_f32_e32 v204, 0, v188
	v_min_f32_e32 v205, 0, v189
	v_min_f32_e32 v206, 0, v190
	v_min_f32_e32 v207, 0, v191
	v_mul_f32_e64 v208, |v184|, s93
	v_mul_f32_e64 v209, |v185|, s93
	v_mul_f32_e64 v210, |v186|, s93
	v_mul_f32_e64 v211, |v187|, s93
	v_mul_f32_e64 v212, |v188|, s93
	v_mul_f32_e64 v213, |v189|, s93
	v_mul_f32_e64 v214, |v190|, s93
	v_mul_f32_e64 v215, |v191|, s93
	v_exp_f32_e32 v208, v208
	v_exp_f32_e32 v209, v209
	v_exp_f32_e32 v210, v210
	v_exp_f32_e32 v211, v211
	v_exp_f32_e32 v212, v212
	v_exp_f32_e32 v213, v213
	v_exp_f32_e32 v214, v214
	v_exp_f32_e32 v215, v215
	v_add_f32_e32 v208, 1.0, v208
	v_add_f32_e32 v209, 1.0, v209
	v_add_f32_e32 v210, 1.0, v210
	v_add_f32_e32 v211, 1.0, v211
	v_add_f32_e32 v212, 1.0, v212
	v_add_f32_e32 v213, 1.0, v213
	v_add_f32_e32 v214, 1.0, v214
	v_add_f32_e32 v215, 1.0, v215
	v_log_f32_e32 v208, v208
	v_log_f32_e32 v209, v209
	v_log_f32_e32 v210, v210
	v_log_f32_e32 v211, v211
	v_log_f32_e32 v212, v212
	v_log_f32_e32 v213, v213
	v_log_f32_e32 v214, v214
	v_log_f32_e32 v215, v215
	v_mul_f32_e32 v216, 0x3f317217, v208
	v_mul_f32_e32 v217, 0x3f317217, v209
	v_mul_f32_e32 v218, 0x3f317217, v210
	v_mul_f32_e32 v219, 0x3f317217, v211
	v_mul_f32_e32 v220, 0x3f317217, v212
	v_mul_f32_e32 v221, 0x3f317217, v213
	v_mul_f32_e32 v222, 0x3f317217, v214
	v_mul_f32_e32 v223, 0x3f317217, v215
	v_fma_f32 v216, v208, s95, -v216
	v_fma_f32 v217, v209, s95, -v217
	v_fma_f32 v218, v210, s95, -v218
	v_fma_f32 v219, v211, s95, -v219
	v_fma_f32 v220, v212, s95, -v220
	v_fma_f32 v221, v213, s95, -v221
	v_fma_f32 v222, v214, s95, -v222
	v_fma_f32 v223, v215, s95, -v223
	v_fmac_f32_e32 v216, 0x3377d1cf, v208
	v_fmac_f32_e32 v217, 0x3377d1cf, v209
	v_fmac_f32_e32 v218, 0x3377d1cf, v210
	v_fmac_f32_e32 v219, 0x3377d1cf, v211
	v_fmac_f32_e32 v220, 0x3377d1cf, v212
	v_fmac_f32_e32 v221, 0x3377d1cf, v213
	v_fmac_f32_e32 v222, 0x3377d1cf, v214
	v_fmac_f32_e32 v223, 0x3377d1cf, v215
	v_fmac_f32_e32 v216, 0x3f317217, v208
	v_fmac_f32_e32 v217, 0x3f317217, v209
	v_fmac_f32_e32 v218, 0x3f317217, v210
	v_fmac_f32_e32 v219, 0x3f317217, v211
	v_fmac_f32_e32 v220, 0x3f317217, v212
	v_fmac_f32_e32 v221, 0x3f317217, v213
	v_fmac_f32_e32 v222, 0x3f317217, v214
	v_fmac_f32_e32 v223, 0x3f317217, v215
; __device__ __forceinline__ void store_rm4(u16* dst, size_t ld, int row0, int c, float v0, float v1, float v2, float v3, bool odd) {
;   {
;     float s = odd ? v0 : v1, r = dpp_swap1(s);
;     float lo = odd ? r : v0, hi = odd ? v1 : r;
;     *(unsigned*)(dst + (size_t)(row0 + (odd ? 1 : 0)) * ld + (c - (odd ? 1 : 0))) = pack2(lo, hi);
;   }
;   {
;     float s = odd ? v2 : v3, r = dpp_swap1(s);
;     float lo = odd ? r : v2, hi = odd ? v3 : r;
;     *(unsigned*)(dst + (size_t)(row0 + 2 + (odd ? 1 : 0)) * ld + (c - (odd ? 1 : 0))) = pack2(lo, hi);
;   }
;   __device__ __forceinline__ void operator()(f32x4 (&acc)[2][2][4][2], int brow, int bcol, int wr, int wc, int fr, int fq) const {
;     ...
;                 f32x4 z4 = {0.f, 0.f, 0.f, 0.f};
;                 z4 = __builtin_amdgcn_mfma_f32_16x16x16bf16_1k(af, bfr[bj][n], z4, 0, 0, 0);
;                 int c = bj * 128 + wc * 32 + n * 16 + fr;
;                 float bb = bias[c];
;                 float ls[4];
; #pragma unroll
;                 for (int j = 0; j < 4; ++j) {
;                   float z = z4[j] + bb;
;                   ls[j] = (fminf(z, 0.f) - __logf(1.f + __expf(-fabsf(z)))) * (1.f / 16.f);
;                 }
;                 store_rm4(dst, 256, row0, c, ls[0], ls[1], ls[2], ls[3], fr & 1);
;               }
;             __builtin_amdgcn_sched_barrier(0);
	v_sub_f32_e32 v200, v200, v216
	v_sub_f32_e32 v201, v201, v217
	v_sub_f32_e32 v202, v202, v218
	v_sub_f32_e32 v203, v203, v219
	v_sub_f32_e32 v204, v204, v220
	v_sub_f32_e32 v205, v205, v221
	v_sub_f32_e32 v206, v206, v222
	v_sub_f32_e32 v207, v207, v223
	v_mul_f32_e32 v184, 0x3d800000, v200
	v_mul_f32_e32 v185, 0x3d800000, v201
	v_mul_f32_e32 v186, 0x3d800000, v202
	v_mul_f32_e32 v187, 0x3d800000, v203
	v_mul_f32_e32 v188, 0x3d800000, v204
	v_mul_f32_e32 v189, 0x3d800000, v205
	v_mul_f32_e32 v190, 0x3d800000, v206
	v_mul_f32_e32 v191, 0x3d800000, v207
	v_add_f32_e32 v192, v178, v192
	v_add_f32_e32 v193, v178, v193
	v_add_f32_e32 v194, v178, v194
	v_add_f32_e32 v195, v178, v195
	v_add_f32_e32 v196, v179, v196
	v_add_f32_e32 v197, v179, v197
	v_add_f32_e32 v198, v179, v198
	v_add_f32_e32 v199, v179, v199
	v_min_f32_e32 v200, 0, v192
	v_min_f32_e32 v201, 0, v193
	v_min_f32_e32 v202, 0, v194
	v_min_f32_e32 v203, 0, v195
	v_min_f32_e32 v204, 0, v196
	v_min_f32_e32 v205, 0, v197
	v_min_f32_e32 v206, 0, v198
	v_min_f32_e32 v207, 0, v199
	v_mul_f32_e64 v208, |v192|, s93
	v_mul_f32_e64 v209, |v193|, s93
	v_mul_f32_e64 v210, |v194|, s93
	v_mul_f32_e64 v211, |v195|, s93
	v_mul_f32_e64 v212, |v196|, s93
	v_mul_f32_e64 v213, |v197|, s93
	v_mul_f32_e64 v214, |v198|, s93
	v_mul_f32_e64 v215, |v199|, s93
	v_exp_f32_e32 v208, v208
	v_exp_f32_e32 v209, v209
	v_exp_f32_e32 v210, v210
	v_exp_f32_e32 v211, v211
	v_exp_f32_e32 v212, v212
	v_exp_f32_e32 v213, v213
	v_exp_f32_e32 v214, v214
	v_exp_f32_e32 v215, v215
	v_add_f32_e32 v208, 1.0, v208
	v_add_f32_e32 v209, 1.0, v209
	v_add_f32_e32 v210, 1.0, v210
	v_add_f32_e32 v211, 1.0, v211
	v_add_f32_e32 v212, 1.0, v212
	v_add_f32_e32 v213, 1.0, v213
	v_add_f32_e32 v214, 1.0, v214
	v_add_f32_e32 v215, 1.0, v215
	v_log_f32_e32 v208, v208
	v_log_f32_e32 v209, v209
	v_log_f32_e32 v210, v210
	v_log_f32_e32 v211, v211
	v_log_f32_e32 v212, v212
	v_log_f32_e32 v213, v213
	v_log_f32_e32 v214, v214
	v_log_f32_e32 v215, v215
	v_mul_f32_e32 v216, 0x3f317217, v208
	v_mul_f32_e32 v217, 0x3f317217, v209
	v_mul_f32_e32 v218, 0x3f317217, v210
	v_mul_f32_e32 v219, 0x3f317217, v211
	v_mul_f32_e32 v220, 0x3f317217, v212
	v_mul_f32_e32 v221, 0x3f317217, v213
	v_mul_f32_e32 v222, 0x3f317217, v214
	v_mul_f32_e32 v223, 0x3f317217, v215
	v_fma_f32 v216, v208, s95, -v216
	v_fma_f32 v217, v209, s95, -v217
	v_fma_f32 v218, v210, s95, -v218
	v_fma_f32 v219, v211, s95, -v219
	v_fma_f32 v220, v212, s95, -v220
	v_fma_f32 v221, v213, s95, -v221
	v_fma_f32 v222, v214, s95, -v222
	v_fma_f32 v223, v215, s95, -v223
	v_fmac_f32_e32 v216, 0x3377d1cf, v208
	v_fmac_f32_e32 v217, 0x3377d1cf, v209
	v_fmac_f32_e32 v218, 0x3377d1cf, v210
	v_fmac_f32_e32 v219, 0x3377d1cf, v211
	v_fmac_f32_e32 v220, 0x3377d1cf, v212
	v_fmac_f32_e32 v221, 0x3377d1cf, v213
	v_fmac_f32_e32 v222, 0x3377d1cf, v214
	v_fmac_f32_e32 v223, 0x3377d1cf, v215
	v_fmac_f32_e32 v216, 0x3f317217, v208
	v_fmac_f32_e32 v217, 0x3f317217, v209
	v_fmac_f32_e32 v218, 0x3f317217, v210
	v_fmac_f32_e32 v219, 0x3f317217, v211
	v_fmac_f32_e32 v220, 0x3f317217, v212
	v_fmac_f32_e32 v221, 0x3f317217, v213
	v_fmac_f32_e32 v222, 0x3f317217, v214
	v_fmac_f32_e32 v223, 0x3f317217, v215
	v_sub_f32_e32 v200, v200, v216
	v_sub_f32_e32 v201, v201, v217
	v_sub_f32_e32 v202, v202, v218
	v_sub_f32_e32 v203, v203, v219
	v_sub_f32_e32 v204, v204, v220
	v_sub_f32_e32 v205, v205, v221
	v_sub_f32_e32 v206, v206, v222
	v_sub_f32_e32 v207, v207, v223
	v_mul_f32_e32 v192, 0x3d800000, v200
	v_mul_f32_e32 v193, 0x3d800000, v201
	v_mul_f32_e32 v194, 0x3d800000, v202
	v_mul_f32_e32 v195, 0x3d800000, v203
	v_mul_f32_e32 v196, 0x3d800000, v204
	v_mul_f32_e32 v197, 0x3d800000, v205
	v_mul_f32_e32 v198, 0x3d800000, v206
	v_mul_f32_e32 v199, 0x3d800000, v207
	v_cvt_pk_bf16_f32 v208, v184, v185
	v_cvt_pk_bf16_f32 v209, v186, v187
	v_cvt_pk_bf16_f32 v210, v188, v189
	v_cvt_pk_bf16_f32 v211, v190, v191
	v_cvt_pk_bf16_f32 v212, v192, v193
	v_cvt_pk_bf16_f32 v213, v194, v195
	v_cvt_pk_bf16_f32 v214, v196, v197
	v_cvt_pk_bf16_f32 v215, v198, v199
	v_mov_b32_dpp v216, v208 quad_perm:[1,0,3,2] row_mask:0xf bank_mask:0xf bound_ctrl:1
	v_mov_b32_dpp v217, v209 quad_perm:[1,0,3,2] row_mask:0xf bank_mask:0xf bound_ctrl:1
	v_mov_b32_dpp v218, v210 quad_perm:[1,0,3,2] row_mask:0xf bank_mask:0xf bound_ctrl:1
	v_mov_b32_dpp v219, v211 quad_perm:[1,0,3,2] row_mask:0xf bank_mask:0xf bound_ctrl:1
	v_mov_b32_dpp v220, v212 quad_perm:[1,0,3,2] row_mask:0xf bank_mask:0xf bound_ctrl:1
	v_mov_b32_dpp v221, v213 quad_perm:[1,0,3,2] row_mask:0xf bank_mask:0xf bound_ctrl:1
	v_mov_b32_dpp v222, v214 quad_perm:[1,0,3,2] row_mask:0xf bank_mask:0xf bound_ctrl:1
	v_mov_b32_dpp v223, v215 quad_perm:[1,0,3,2] row_mask:0xf bank_mask:0xf bound_ctrl:1
	v_perm_b32 v208, v216, v208, v164
	v_perm_b32 v209, v217, v209, v164
	v_perm_b32 v210, v218, v210, v164
	v_perm_b32 v211, v219, v211, v164
	v_perm_b32 v212, v220, v212, v164
	v_perm_b32 v213, v221, v213, v164
	v_perm_b32 v214, v222, v214, v164
	v_perm_b32 v215, v223, v215, v164
	global_store_dword v167, v208, s[8:9]
	global_store_dword v167, v209, s[8:9] offset:1024
	global_store_dword v167, v210, s[8:9] offset:32
	global_store_dword v167, v211, s[8:9] offset:1056
	global_store_dword v167, v212, s[8:9] offset:256
	global_store_dword v167, v213, s[8:9] offset:1280
	global_store_dword v167, v214, s[8:9] offset:288
	global_store_dword v167, v215, s[8:9] offset:1312
	ds_read_b64 v[180:181], v160 offset:51232
	v_add_u32_e32 v167, 0x4000, v163
	s_waitcnt lgkmcnt(0)
;   __device__ __forceinline__ void operator()(f32x4 (&acc)[2][2][4][2], int brow, int bcol, int wr, int wc, int fr, int fq) const {
;     ...
;                 f32x4 z4 = {0.f, 0.f, 0.f, 0.f};
;                 z4 = __builtin_amdgcn_mfma_f32_16x16x16bf16_1k(af, bfr[bj][n], z4, 0, 0, 0);
;                 int c = bj * 128 + wc * 32 + n * 16 + fr;
;                 float bb = bias[c];
;                 float ls[4];
; #pragma unroll
;                 for (int j = 0; j < 4; ++j) {
;                   float z = z4[j] + bb;
;                   ls[j] = (fminf(z, 0.f) - __logf(1.f + __expf(-fabsf(z)))) * (1.f / 16.f);
;                 }
;                 store_rm4(dst, 256, row0, c, ls[0], ls[1], ls[2], ls[3], fr & 1);
	v_mfma_f32_16x16x16_bf16 v[184:187], v[180:181], v[168:169], 0
	v_mfma_f32_16x16x16_bf16 v[188:191], v[180:181], v[170:171], 0
	v_mfma_f32_16x16x16_bf16 v[192:195], v[180:181], v[172:173], 0
	v_mfma_f32_16x16x16_bf16 v[196:199], v[180:181], v[174:175], 0
	s_nop 7
	s_nop 1
	v_add_f32_e32 v184, v176, v184
	v_add_f32_e32 v185, v176, v185
	v_add_f32_e32 v186, v176, v186
	v_add_f32_e32 v187, v176, v187
	v_add_f32_e32 v188, v177, v188
	v_add_f32_e32 v189, v177, v189
	v_add_f32_e32 v190, v177, v190
	v_add_f32_e32 v191, v177, v191
	v_min_f32_e32 v200, 0, v184
	v_min_f32_e32 v201, 0, v185
	v_min_f32_e32 v202, 0, v186
	v_min_f32_e32 v203, 0, v187
	v_min_f32_e32 v204, 0, v188
	v_min_f32_e32 v205, 0, v189
	v_min_f32_e32 v206, 0, v190
	v_min_f32_e32 v207, 0, v191
	v_mul_f32_e64 v208, |v184|, s93
	v_mul_f32_e64 v209, |v185|, s93
	v_mul_f32_e64 v210, |v186|, s93
	v_mul_f32_e64 v211, |v187|, s93
	v_mul_f32_e64 v212, |v188|, s93
	v_mul_f32_e64 v213, |v189|, s93
	v_mul_f32_e64 v214, |v190|, s93
	v_mul_f32_e64 v215, |v191|, s93
	v_exp_f32_e32 v208, v208
	v_exp_f32_e32 v209, v209
	v_exp_f32_e32 v210, v210
	v_exp_f32_e32 v211, v211
	v_exp_f32_e32 v212, v212
	v_exp_f32_e32 v213, v213
	v_exp_f32_e32 v214, v214
	v_exp_f32_e32 v215, v215
	v_add_f32_e32 v208, 1.0, v208
	v_add_f32_e32 v209, 1.0, v209
	v_add_f32_e32 v210, 1.0, v210
	v_add_f32_e32 v211, 1.0, v211
	v_add_f32_e32 v212, 1.0, v212
	v_add_f32_e32 v213, 1.0, v213
	v_add_f32_e32 v214, 1.0, v214
	v_add_f32_e32 v215, 1.0, v215
	v_log_f32_e32 v208, v208
	v_log_f32_e32 v209, v209
	v_log_f32_e32 v210, v210
	v_log_f32_e32 v211, v211
	v_log_f32_e32 v212, v212
	v_log_f32_e32 v213, v213
	v_log_f32_e32 v214, v214
	v_log_f32_e32 v215, v215
	v_mul_f32_e32 v216, 0x3f317217, v208
	v_mul_f32_e32 v217, 0x3f317217, v209
	v_mul_f32_e32 v218, 0x3f317217, v210
	v_mul_f32_e32 v219, 0x3f317217, v211
	v_mul_f32_e32 v220, 0x3f317217, v212
	v_mul_f32_e32 v221, 0x3f317217, v213
	v_mul_f32_e32 v222, 0x3f317217, v214
	v_mul_f32_e32 v223, 0x3f317217, v215
	v_fma_f32 v216, v208, s95, -v216
	v_fma_f32 v217, v209, s95, -v217
	v_fma_f32 v218, v210, s95, -v218
	v_fma_f32 v219, v211, s95, -v219
	v_fma_f32 v220, v212, s95, -v220
	v_fma_f32 v221, v213, s95, -v221
	v_fma_f32 v222, v214, s95, -v222
	v_fma_f32 v223, v215, s95, -v223
	v_fmac_f32_e32 v216, 0x3377d1cf, v208
	v_fmac_f32_e32 v217, 0x3377d1cf, v209
	v_fmac_f32_e32 v218, 0x3377d1cf, v210
	v_fmac_f32_e32 v219, 0x3377d1cf, v211
	v_fmac_f32_e32 v220, 0x3377d1cf, v212
	v_fmac_f32_e32 v221, 0x3377d1cf, v213
	v_fmac_f32_e32 v222, 0x3377d1cf, v214
	v_fmac_f32_e32 v223, 0x3377d1cf, v215
	v_fmac_f32_e32 v216, 0x3f317217, v208
	v_fmac_f32_e32 v217, 0x3f317217, v209
	v_fmac_f32_e32 v218, 0x3f317217, v210
	v_fmac_f32_e32 v219, 0x3f317217, v211
	v_fmac_f32_e32 v220, 0x3f317217, v212
	v_fmac_f32_e32 v221, 0x3f317217, v213
	v_fmac_f32_e32 v222, 0x3f317217, v214
	v_fmac_f32_e32 v223, 0x3f317217, v215
	v_sub_f32_e32 v200, v200, v216
	v_sub_f32_e32 v201, v201, v217
	v_sub_f32_e32 v202, v202, v218
	v_sub_f32_e32 v203, v203, v219
	v_sub_f32_e32 v204, v204, v220
	v_sub_f32_e32 v205, v205, v221
	v_sub_f32_e32 v206, v206, v222
	v_sub_f32_e32 v207, v207, v223
	v_mul_f32_e32 v184, 0x3d800000, v200
	v_mul_f32_e32 v185, 0x3d800000, v201
	v_mul_f32_e32 v186, 0x3d800000, v202
	v_mul_f32_e32 v187, 0x3d800000, v203
	v_mul_f32_e32 v188, 0x3d800000, v204
	v_mul_f32_e32 v189, 0x3d800000, v205
	v_mul_f32_e32 v190, 0x3d800000, v206
	v_mul_f32_e32 v191, 0x3d800000, v207
	v_add_f32_e32 v192, v178, v192
	v_add_f32_e32 v193, v178, v193
	v_add_f32_e32 v194, v178, v194
	v_add_f32_e32 v195, v178, v195
	v_add_f32_e32 v196, v179, v196
	v_add_f32_e32 v197, v179, v197
	v_add_f32_e32 v198, v179, v198
	v_add_f32_e32 v199, v179, v199
	v_min_f32_e32 v200, 0, v192
	v_min_f32_e32 v201, 0, v193
	v_min_f32_e32 v202, 0, v194
	v_min_f32_e32 v203, 0, v195
	v_min_f32_e32 v204, 0, v196
	v_min_f32_e32 v205, 0, v197
	v_min_f32_e32 v206, 0, v198
	v_min_f32_e32 v207, 0, v199
	v_mul_f32_e64 v208, |v192|, s93
	v_mul_f32_e64 v209, |v193|, s93
	v_mul_f32_e64 v210, |v194|, s93
	v_mul_f32_e64 v211, |v195|, s93
	v_mul_f32_e64 v212, |v196|, s93
	v_mul_f32_e64 v213, |v197|, s93
	v_mul_f32_e64 v214, |v198|, s93
	v_mul_f32_e64 v215, |v199|, s93
	v_exp_f32_e32 v208, v208
	v_exp_f32_e32 v209, v209
	v_exp_f32_e32 v210, v210
	v_exp_f32_e32 v211, v211
	v_exp_f32_e32 v212, v212
	v_exp_f32_e32 v213, v213
	v_exp_f32_e32 v214, v214
	v_exp_f32_e32 v215, v215
	v_add_f32_e32 v208, 1.0, v208
	v_add_f32_e32 v209, 1.0, v209
	v_add_f32_e32 v210, 1.0, v210
	v_add_f32_e32 v211, 1.0, v211
	v_add_f32_e32 v212, 1.0, v212
	v_add_f32_e32 v213, 1.0, v213
	v_add_f32_e32 v214, 1.0, v214
	v_add_f32_e32 v215, 1.0, v215
	v_log_f32_e32 v208, v208
	v_log_f32_e32 v209, v209
	v_log_f32_e32 v210, v210
	v_log_f32_e32 v211, v211
	v_log_f32_e32 v212, v212
	v_log_f32_e32 v213, v213
	v_log_f32_e32 v214, v214
	v_log_f32_e32 v215, v215
	v_mul_f32_e32 v216, 0x3f317217, v208
	v_mul_f32_e32 v217, 0x3f317217, v209
	v_mul_f32_e32 v218, 0x3f317217, v210
	v_mul_f32_e32 v219, 0x3f317217, v211
	v_mul_f32_e32 v220, 0x3f317217, v212
	v_mul_f32_e32 v221, 0x3f317217, v213
	v_mul_f32_e32 v222, 0x3f317217, v214
	v_mul_f32_e32 v223, 0x3f317217, v215
	v_fma_f32 v216, v208, s95, -v216
	v_fma_f32 v217, v209, s95, -v217
	v_fma_f32 v218, v210, s95, -v218
	v_fma_f32 v219, v211, s95, -v219
	v_fma_f32 v220, v212, s95, -v220
	v_fma_f32 v221, v213, s95, -v221
	v_fma_f32 v222, v214, s95, -v222
	v_fma_f32 v223, v215, s95, -v223
	v_fmac_f32_e32 v216, 0x3377d1cf, v208
	v_fmac_f32_e32 v217, 0x3377d1cf, v209
	v_fmac_f32_e32 v218, 0x3377d1cf, v210
	v_fmac_f32_e32 v219, 0x3377d1cf, v211
	v_fmac_f32_e32 v220, 0x3377d1cf, v212
; __device__ __forceinline__ void store_rm4(u16* dst, size_t ld, int row0, int c, float v0, float v1, float v2, float v3, bool odd) {
;   {
;     float s = odd ? v0 : v1, r = dpp_swap1(s);
;     float lo = odd ? r : v0, hi = odd ? v1 : r;
;     *(unsigned*)(dst + (size_t)(row0 + (odd ? 1 : 0)) * ld + (c - (odd ? 1 : 0))) = pack2(lo, hi);
;   }
;   {
;     float s = odd ? v2 : v3, r = dpp_swap1(s);
;     float lo = odd ? r : v2, hi = odd ? v3 : r;
;     *(unsigned*)(dst + (size_t)(row0 + 2 + (odd ? 1 : 0)) * ld + (c - (odd ? 1 : 0))) = pack2(lo, hi);
;   }
; }
;   __device__ __forceinline__ void operator()(f32x4 (&acc)[2][2][4][2], int brow, int bcol, int wr, int wc, int fr, int fq) const {
;     ...
;         for (int ai = 0; ai < 2; ++ai)
; #pragma unroll
;           for (int m = 0; m < 4; ++m) {
;             int rl = ai * 128 + wr * 64 + m * 16;
;             s16x4 af = *(const s16x4*)(glr + (rl + fr) * 32 + dir * 16 + fq * 4);
;             int row0 = brow + rl + fq * 4;
; #pragma unroll
;             for (int bj = 0; bj < 2; ++bj)
; #pragma unroll
;               for (int n = 0; n < 2; ++n) {
;                 f32x4 z4 = {0.f, 0.f, 0.f, 0.f};
;                 z4 = __builtin_amdgcn_mfma_f32_16x16x16bf16_1k(af, bfr[bj][n], z4, 0, 0, 0);
;                 int c = bj * 128 + wc * 32 + n * 16 + fr;
;                 float bb = bias[c];
;                 float ls[4];
; #pragma unroll
;                 for (int j = 0; j < 4; ++j) {
;                   float z = z4[j] + bb;
;                   ls[j] = (fminf(z, 0.f) - __logf(1.f + __expf(-fabsf(z)))) * (1.f / 16.f);
;                 }
;                 store_rm4(dst, 256, row0, c, ls[0], ls[1], ls[2], ls[3], fr & 1);
;               }
	v_fmac_f32_e32 v221, 0x3377d1cf, v213
	v_fmac_f32_e32 v222, 0x3377d1cf, v214
	v_fmac_f32_e32 v223, 0x3377d1cf, v215
	v_fmac_f32_e32 v216, 0x3f317217, v208
	v_fmac_f32_e32 v217, 0x3f317217, v209
	v_fmac_f32_e32 v218, 0x3f317217, v210
	v_fmac_f32_e32 v219, 0x3f317217, v211
	v_fmac_f32_e32 v220, 0x3f317217, v212
	v_fmac_f32_e32 v221, 0x3f317217, v213
	v_fmac_f32_e32 v222, 0x3f317217, v214
	v_fmac_f32_e32 v223, 0x3f317217, v215
	v_sub_f32_e32 v200, v200, v216
	v_sub_f32_e32 v201, v201, v217
	v_sub_f32_e32 v202, v202, v218
	v_sub_f32_e32 v203, v203, v219
	v_sub_f32_e32 v204, v204, v220
	v_sub_f32_e32 v205, v205, v221
	v_sub_f32_e32 v206, v206, v222
	v_sub_f32_e32 v207, v207, v223
	v_mul_f32_e32 v192, 0x3d800000, v200
	v_mul_f32_e32 v193, 0x3d800000, v201
	v_mul_f32_e32 v194, 0x3d800000, v202
	v_mul_f32_e32 v195, 0x3d800000, v203
	v_mul_f32_e32 v196, 0x3d800000, v204
	v_mul_f32_e32 v197, 0x3d800000, v205
	v_mul_f32_e32 v198, 0x3d800000, v206
	v_mul_f32_e32 v199, 0x3d800000, v207
	v_cvt_pk_bf16_f32 v208, v184, v185
	v_cvt_pk_bf16_f32 v209, v186, v187
	v_cvt_pk_bf16_f32 v210, v188, v189
	v_cvt_pk_bf16_f32 v211, v190, v191
	v_cvt_pk_bf16_f32 v212, v192, v193
	v_cvt_pk_bf16_f32 v213, v194, v195
	v_cvt_pk_bf16_f32 v214, v196, v197
	v_cvt_pk_bf16_f32 v215, v198, v199
	v_mov_b32_dpp v216, v208 quad_perm:[1,0,3,2] row_mask:0xf bank_mask:0xf bound_ctrl:1
	v_mov_b32_dpp v217, v209 quad_perm:[1,0,3,2] row_mask:0xf bank_mask:0xf bound_ctrl:1
	v_mov_b32_dpp v218, v210 quad_perm:[1,0,3,2] row_mask:0xf bank_mask:0xf bound_ctrl:1
	v_mov_b32_dpp v219, v211 quad_perm:[1,0,3,2] row_mask:0xf bank_mask:0xf bound_ctrl:1
	v_mov_b32_dpp v220, v212 quad_perm:[1,0,3,2] row_mask:0xf bank_mask:0xf bound_ctrl:1
	v_mov_b32_dpp v221, v213 quad_perm:[1,0,3,2] row_mask:0xf bank_mask:0xf bound_ctrl:1
	v_mov_b32_dpp v222, v214 quad_perm:[1,0,3,2] row_mask:0xf bank_mask:0xf bound_ctrl:1
	v_mov_b32_dpp v223, v215 quad_perm:[1,0,3,2] row_mask:0xf bank_mask:0xf bound_ctrl:1
	v_perm_b32 v208, v216, v208, v164
	v_perm_b32 v209, v217, v209, v164
	v_perm_b32 v210, v218, v210, v164
	v_perm_b32 v211, v219, v211, v164
	v_perm_b32 v212, v220, v212, v164
	v_perm_b32 v213, v221, v213, v164
	v_perm_b32 v214, v222, v214, v164
	v_perm_b32 v215, v223, v215, v164
	global_store_dword v167, v208, s[8:9]
	global_store_dword v167, v209, s[8:9] offset:1024
	global_store_dword v167, v210, s[8:9] offset:32
	global_store_dword v167, v211, s[8:9] offset:1056
	global_store_dword v167, v212, s[8:9] offset:256
	global_store_dword v167, v213, s[8:9] offset:1280
	global_store_dword v167, v214, s[8:9] offset:288
	global_store_dword v167, v215, s[8:9] offset:1312
	ds_read_b64 v[180:181], v160 offset:52256
	v_add_u32_e32 v167, 0x6000, v163
	s_waitcnt lgkmcnt(0)
	v_mfma_f32_16x16x16_bf16 v[184:187], v[180:181], v[168:169], 0
	v_mfma_f32_16x16x16_bf16 v[188:191], v[180:181], v[170:171], 0
	v_mfma_f32_16x16x16_bf16 v[192:195], v[180:181], v[172:173], 0
	v_mfma_f32_16x16x16_bf16 v[196:199], v[180:181], v[174:175], 0
	s_nop 7
	s_nop 1
	v_add_f32_e32 v184, v176, v184
	v_add_f32_e32 v185, v176, v185
	v_add_f32_e32 v186, v176, v186
	v_add_f32_e32 v187, v176, v187
	v_add_f32_e32 v188, v177, v188
	v_add_f32_e32 v189, v177, v189
	v_add_f32_e32 v190, v177, v190
	v_add_f32_e32 v191, v177, v191
	v_min_f32_e32 v200, 0, v184
	v_min_f32_e32 v201, 0, v185
	v_min_f32_e32 v202, 0, v186
	v_min_f32_e32 v203, 0, v187
	v_min_f32_e32 v204, 0, v188
	v_min_f32_e32 v205, 0, v189
	v_min_f32_e32 v206, 0, v190
	v_min_f32_e32 v207, 0, v191
	v_mul_f32_e64 v208, |v184|, s93
	v_mul_f32_e64 v209, |v185|, s93
	v_mul_f32_e64 v210, |v186|, s93
	v_mul_f32_e64 v211, |v187|, s93
	v_mul_f32_e64 v212, |v188|, s93
	v_mul_f32_e64 v213, |v189|, s93
	v_mul_f32_e64 v214, |v190|, s93
	v_mul_f32_e64 v215, |v191|, s93
	v_exp_f32_e32 v208, v208
	v_exp_f32_e32 v209, v209
	v_exp_f32_e32 v210, v210
	v_exp_f32_e32 v211, v211
	v_exp_f32_e32 v212, v212
	v_exp_f32_e32 v213, v213
	v_exp_f32_e32 v214, v214
	v_exp_f32_e32 v215, v215
	v_add_f32_e32 v208, 1.0, v208
	v_add_f32_e32 v209, 1.0, v209
	v_add_f32_e32 v210, 1.0, v210
	v_add_f32_e32 v211, 1.0, v211
	v_add_f32_e32 v212, 1.0, v212
	v_add_f32_e32 v213, 1.0, v213
	v_add_f32_e32 v214, 1.0, v214
	v_add_f32_e32 v215, 1.0, v215
	v_log_f32_e32 v208, v208
	v_log_f32_e32 v209, v209
	v_log_f32_e32 v210, v210
	v_log_f32_e32 v211, v211
	v_log_f32_e32 v212, v212
	v_log_f32_e32 v213, v213
	v_log_f32_e32 v214, v214
	v_log_f32_e32 v215, v215
	v_mul_f32_e32 v216, 0x3f317217, v208
	v_mul_f32_e32 v217, 0x3f317217, v209
	v_mul_f32_e32 v218, 0x3f317217, v210
	v_mul_f32_e32 v219, 0x3f317217, v211
	v_mul_f32_e32 v220, 0x3f317217, v212
	v_mul_f32_e32 v221, 0x3f317217, v213
	v_mul_f32_e32 v222, 0x3f317217, v214
	v_mul_f32_e32 v223, 0x3f317217, v215
	v_fma_f32 v216, v208, s95, -v216
	v_fma_f32 v217, v209, s95, -v217
	v_fma_f32 v218, v210, s95, -v218
	v_fma_f32 v219, v211, s95, -v219
	v_fma_f32 v220, v212, s95, -v220
	v_fma_f32 v221, v213, s95, -v221
	v_fma_f32 v222, v214, s95, -v222
	v_fma_f32 v223, v215, s95, -v223
	v_fmac_f32_e32 v216, 0x3377d1cf, v208
	v_fmac_f32_e32 v217, 0x3377d1cf, v209
	v_fmac_f32_e32 v218, 0x3377d1cf, v210
	v_fmac_f32_e32 v219, 0x3377d1cf, v211
	v_fmac_f32_e32 v220, 0x3377d1cf, v212
	v_fmac_f32_e32 v221, 0x3377d1cf, v213
	v_fmac_f32_e32 v222, 0x3377d1cf, v214
	v_fmac_f32_e32 v223, 0x3377d1cf, v215
	v_fmac_f32_e32 v216, 0x3f317217, v208
	v_fmac_f32_e32 v217, 0x3f317217, v209
	v_fmac_f32_e32 v218, 0x3f317217, v210
	v_fmac_f32_e32 v219, 0x3f317217, v211
	v_fmac_f32_e32 v220, 0x3f317217, v212
	v_fmac_f32_e32 v221, 0x3f317217, v213
	v_fmac_f32_e32 v222, 0x3f317217, v214
	v_fmac_f32_e32 v223, 0x3f317217, v215
; __device__ __forceinline__ void store_rm4(u16* dst, size_t ld, int row0, int c, float v0, float v1, float v2, float v3, bool odd) {
;   {
;     float s = odd ? v0 : v1, r = dpp_swap1(s);
;     float lo = odd ? r : v0, hi = odd ? v1 : r;
;     *(unsigned*)(dst + (size_t)(row0 + (odd ? 1 : 0)) * ld + (c - (odd ? 1 : 0))) = pack2(lo, hi);
;   }
;   {
;     float s = odd ? v2 : v3, r = dpp_swap1(s);
;     float lo = odd ? r : v2, hi = odd ? v3 : r;
;     *(unsigned*)(dst + (size_t)(row0 + 2 + (odd ? 1 : 0)) * ld + (c - (odd ? 1 : 0))) = pack2(lo, hi);
;   }
; }
;   __device__ __forceinline__ void operator()(f32x4 (&acc)[2][2][4][2], int brow, int bcol, int wr, int wc, int fr, int fq) const {
;     ...
;         for (int ai = 0; ai < 2; ++ai)
; #pragma unroll
;           for (int m = 0; m < 4; ++m) {
;             int rl = ai * 128 + wr * 64 + m * 16;
;             s16x4 af = *(const s16x4*)(glr + (rl + fr) * 32 + dir * 16 + fq * 4);
;             int row0 = brow + rl + fq * 4;
; #pragma unroll
;             for (int bj = 0; bj < 2; ++bj)
; #pragma unroll
;               for (int n = 0; n < 2; ++n) {
;                 f32x4 z4 = {0.f, 0.f, 0.f, 0.f};
;                 z4 = __builtin_amdgcn_mfma_f32_16x16x16bf16_1k(af, bfr[bj][n], z4, 0, 0, 0);
;                 int c = bj * 128 + wc * 32 + n * 16 + fr;
;                 float bb = bias[c];
;                 float ls[4];
; #pragma unroll
;                 for (int j = 0; j < 4; ++j) {
;                   float z = z4[j] + bb;
;                   ls[j] = (fminf(z, 0.f) - __logf(1.f + __expf(-fabsf(z)))) * (1.f / 16.f);
;                 }
;                 store_rm4(dst, 256, row0, c, ls[0], ls[1], ls[2], ls[3], fr & 1);
;               }
	v_sub_f32_e32 v200, v200, v216
	v_sub_f32_e32 v201, v201, v217
	v_sub_f32_e32 v202, v202, v218
	v_sub_f32_e32 v203, v203, v219
	v_sub_f32_e32 v204, v204, v220
	v_sub_f32_e32 v205, v205, v221
	v_sub_f32_e32 v206, v206, v222
	v_sub_f32_e32 v207, v207, v223
	v_mul_f32_e32 v184, 0x3d800000, v200
	v_mul_f32_e32 v185, 0x3d800000, v201
	v_mul_f32_e32 v186, 0x3d800000, v202
	v_mul_f32_e32 v187, 0x3d800000, v203
	v_mul_f32_e32 v188, 0x3d800000, v204
	v_mul_f32_e32 v189, 0x3d800000, v205
	v_mul_f32_e32 v190, 0x3d800000, v206
	v_mul_f32_e32 v191, 0x3d800000, v207
	v_add_f32_e32 v192, v178, v192
	v_add_f32_e32 v193, v178, v193
	v_add_f32_e32 v194, v178, v194
	v_add_f32_e32 v195, v178, v195
	v_add_f32_e32 v196, v179, v196
	v_add_f32_e32 v197, v179, v197
	v_add_f32_e32 v198, v179, v198
	v_add_f32_e32 v199, v179, v199
	v_min_f32_e32 v200, 0, v192
	v_min_f32_e32 v201, 0, v193
	v_min_f32_e32 v202, 0, v194
	v_min_f32_e32 v203, 0, v195
	v_min_f32_e32 v204, 0, v196
	v_min_f32_e32 v205, 0, v197
	v_min_f32_e32 v206, 0, v198
	v_min_f32_e32 v207, 0, v199
	v_mul_f32_e64 v208, |v192|, s93
	v_mul_f32_e64 v209, |v193|, s93
	v_mul_f32_e64 v210, |v194|, s93
	v_mul_f32_e64 v211, |v195|, s93
	v_mul_f32_e64 v212, |v196|, s93
	v_mul_f32_e64 v213, |v197|, s93
	v_mul_f32_e64 v214, |v198|, s93
	v_mul_f32_e64 v215, |v199|, s93
	v_exp_f32_e32 v208, v208
	v_exp_f32_e32 v209, v209
	v_exp_f32_e32 v210, v210
	v_exp_f32_e32 v211, v211
	v_exp_f32_e32 v212, v212
	v_exp_f32_e32 v213, v213
	v_exp_f32_e32 v214, v214
	v_exp_f32_e32 v215, v215
	v_add_f32_e32 v208, 1.0, v208
	v_add_f32_e32 v209, 1.0, v209
	v_add_f32_e32 v210, 1.0, v210
	v_add_f32_e32 v211, 1.0, v211
	v_add_f32_e32 v212, 1.0, v212
	v_add_f32_e32 v213, 1.0, v213
	v_add_f32_e32 v214, 1.0, v214
	v_add_f32_e32 v215, 1.0, v215
	v_log_f32_e32 v208, v208
	v_log_f32_e32 v209, v209
	v_log_f32_e32 v210, v210
	v_log_f32_e32 v211, v211
	v_log_f32_e32 v212, v212
	v_log_f32_e32 v213, v213
	v_log_f32_e32 v214, v214
	v_log_f32_e32 v215, v215
	v_mul_f32_e32 v216, 0x3f317217, v208
	v_mul_f32_e32 v217, 0x3f317217, v209
	v_mul_f32_e32 v218, 0x3f317217, v210
	v_mul_f32_e32 v219, 0x3f317217, v211
	v_mul_f32_e32 v220, 0x3f317217, v212
	v_mul_f32_e32 v221, 0x3f317217, v213
	v_mul_f32_e32 v222, 0x3f317217, v214
	v_mul_f32_e32 v223, 0x3f317217, v215
	v_fma_f32 v216, v208, s95, -v216
	v_fma_f32 v217, v209, s95, -v217
	v_fma_f32 v218, v210, s95, -v218
	v_fma_f32 v219, v211, s95, -v219
	v_fma_f32 v220, v212, s95, -v220
	v_fma_f32 v221, v213, s95, -v221
	v_fma_f32 v222, v214, s95, -v222
	v_fma_f32 v223, v215, s95, -v223
	v_fmac_f32_e32 v216, 0x3377d1cf, v208
	v_fmac_f32_e32 v217, 0x3377d1cf, v209
	v_fmac_f32_e32 v218, 0x3377d1cf, v210
	v_fmac_f32_e32 v219, 0x3377d1cf, v211
	v_fmac_f32_e32 v220, 0x3377d1cf, v212
	v_fmac_f32_e32 v221, 0x3377d1cf, v213
	v_fmac_f32_e32 v222, 0x3377d1cf, v214
	v_fmac_f32_e32 v223, 0x3377d1cf, v215
	v_fmac_f32_e32 v216, 0x3f317217, v208
	v_fmac_f32_e32 v217, 0x3f317217, v209
	v_fmac_f32_e32 v218, 0x3f317217, v210
	v_fmac_f32_e32 v219, 0x3f317217, v211
	v_fmac_f32_e32 v220, 0x3f317217, v212
	v_fmac_f32_e32 v221, 0x3f317217, v213
	v_fmac_f32_e32 v222, 0x3f317217, v214
	v_fmac_f32_e32 v223, 0x3f317217, v215
	v_sub_f32_e32 v200, v200, v216
	v_sub_f32_e32 v201, v201, v217
	v_sub_f32_e32 v202, v202, v218
	v_sub_f32_e32 v203, v203, v219
	v_sub_f32_e32 v204, v204, v220
	v_sub_f32_e32 v205, v205, v221
	v_sub_f32_e32 v206, v206, v222
	v_sub_f32_e32 v207, v207, v223
	v_mul_f32_e32 v192, 0x3d800000, v200
	v_mul_f32_e32 v193, 0x3d800000, v201
	v_mul_f32_e32 v194, 0x3d800000, v202
	v_mul_f32_e32 v195, 0x3d800000, v203
	v_mul_f32_e32 v196, 0x3d800000, v204
	v_mul_f32_e32 v197, 0x3d800000, v205
	v_mul_f32_e32 v198, 0x3d800000, v206
	v_mul_f32_e32 v199, 0x3d800000, v207
	v_cvt_pk_bf16_f32 v208, v184, v185
	v_cvt_pk_bf16_f32 v209, v186, v187
	v_cvt_pk_bf16_f32 v210, v188, v189
	v_cvt_pk_bf16_f32 v211, v190, v191
	v_cvt_pk_bf16_f32 v212, v192, v193
	v_cvt_pk_bf16_f32 v213, v194, v195
	v_cvt_pk_bf16_f32 v214, v196, v197
	v_cvt_pk_bf16_f32 v215, v198, v199
	v_mov_b32_dpp v216, v208 quad_perm:[1,0,3,2] row_mask:0xf bank_mask:0xf bound_ctrl:1
	v_mov_b32_dpp v217, v209 quad_perm:[1,0,3,2] row_mask:0xf bank_mask:0xf bound_ctrl:1
	v_mov_b32_dpp v218, v210 quad_perm:[1,0,3,2] row_mask:0xf bank_mask:0xf bound_ctrl:1
	v_mov_b32_dpp v219, v211 quad_perm:[1,0,3,2] row_mask:0xf bank_mask:0xf bound_ctrl:1
	v_mov_b32_dpp v220, v212 quad_perm:[1,0,3,2] row_mask:0xf bank_mask:0xf bound_ctrl:1
	v_mov_b32_dpp v221, v213 quad_perm:[1,0,3,2] row_mask:0xf bank_mask:0xf bound_ctrl:1
	v_mov_b32_dpp v222, v214 quad_perm:[1,0,3,2] row_mask:0xf bank_mask:0xf bound_ctrl:1
	v_mov_b32_dpp v223, v215 quad_perm:[1,0,3,2] row_mask:0xf bank_mask:0xf bound_ctrl:1
	v_perm_b32 v208, v216, v208, v164
	v_perm_b32 v209, v217, v209, v164
	v_perm_b32 v210, v218, v210, v164
	v_perm_b32 v211, v219, v211, v164
	v_perm_b32 v212, v220, v212, v164
	v_perm_b32 v213, v221, v213, v164
	v_perm_b32 v214, v222, v214, v164
	v_perm_b32 v215, v223, v215, v164
	global_store_dword v167, v208, s[8:9]
	global_store_dword v167, v209, s[8:9] offset:1024
	global_store_dword v167, v210, s[8:9] offset:32
	global_store_dword v167, v211, s[8:9] offset:1056
	global_store_dword v167, v212, s[8:9] offset:256
	global_store_dword v167, v213, s[8:9] offset:1280
	global_store_dword v167, v214, s[8:9] offset:288
	global_store_dword v167, v215, s[8:9] offset:1312
	ds_read_b64 v[180:181], v160 offset:57376
	v_add_u32_e32 v167, 0x10000, v163
	s_waitcnt lgkmcnt(0)
; __device__ __forceinline__ void store_rm4(u16* dst, size_t ld, int row0, int c, float v0, float v1, float v2, float v3, bool odd) {
;   {
;     float s = odd ? v0 : v1, r = dpp_swap1(s);
;     float lo = odd ? r : v0, hi = odd ? v1 : r;
;     *(unsigned*)(dst + (size_t)(row0 + (odd ? 1 : 0)) * ld + (c - (odd ? 1 : 0))) = pack2(lo, hi);
;   }
;   {
;     float s = odd ? v2 : v3, r = dpp_swap1(s);
;     float lo = odd ? r : v2, hi = odd ? v3 : r;
;     *(unsigned*)(dst + (size_t)(row0 + 2 + (odd ? 1 : 0)) * ld + (c - (odd ? 1 : 0))) = pack2(lo, hi);
;   }
; }
;   __device__ __forceinline__ void operator()(f32x4 (&acc)[2][2][4][2], int brow, int bcol, int wr, int wc, int fr, int fq) const {
;     ...
;         for (int ai = 0; ai < 2; ++ai)
; #pragma unroll
;           for (int m = 0; m < 4; ++m) {
;             int rl = ai * 128 + wr * 64 + m * 16;
;             s16x4 af = *(const s16x4*)(glr + (rl + fr) * 32 + dir * 16 + fq * 4);
;             int row0 = brow + rl + fq * 4;
; #pragma unroll
;             for (int bj = 0; bj < 2; ++bj)
; #pragma unroll
;               for (int n = 0; n < 2; ++n) {
;                 f32x4 z4 = {0.f, 0.f, 0.f, 0.f};
;                 z4 = __builtin_amdgcn_mfma_f32_16x16x16bf16_1k(af, bfr[bj][n], z4, 0, 0, 0);
;                 int c = bj * 128 + wc * 32 + n * 16 + fr;
;                 float bb = bias[c];
;                 float ls[4];
; #pragma unroll
;                 for (int j = 0; j < 4; ++j) {
;                   float z = z4[j] + bb;
;                   ls[j] = (fminf(z, 0.f) - __logf(1.f + __expf(-fabsf(z)))) * (1.f / 16.f);
;                 }
;                 store_rm4(dst, 256, row0, c, ls[0], ls[1], ls[2], ls[3], fr & 1);
;               }
	v_mfma_f32_16x16x16_bf16 v[184:187], v[180:181], v[168:169], 0
	v_mfma_f32_16x16x16_bf16 v[188:191], v[180:181], v[170:171], 0
	v_mfma_f32_16x16x16_bf16 v[192:195], v[180:181], v[172:173], 0
	v_mfma_f32_16x16x16_bf16 v[196:199], v[180:181], v[174:175], 0
	s_nop 7
	s_nop 1
	v_add_f32_e32 v184, v176, v184
	v_add_f32_e32 v185, v176, v185
	v_add_f32_e32 v186, v176, v186
	v_add_f32_e32 v187, v176, v187
	v_add_f32_e32 v188, v177, v188
	v_add_f32_e32 v189, v177, v189
	v_add_f32_e32 v190, v177, v190
	v_add_f32_e32 v191, v177, v191
	v_min_f32_e32 v200, 0, v184
	v_min_f32_e32 v201, 0, v185
	v_min_f32_e32 v202, 0, v186
	v_min_f32_e32 v203, 0, v187
	v_min_f32_e32 v204, 0, v188
	v_min_f32_e32 v205, 0, v189
	v_min_f32_e32 v206, 0, v190
	v_min_f32_e32 v207, 0, v191
	v_mul_f32_e64 v208, |v184|, s93
	v_mul_f32_e64 v209, |v185|, s93
	v_mul_f32_e64 v210, |v186|, s93
	v_mul_f32_e64 v211, |v187|, s93
	v_mul_f32_e64 v212, |v188|, s93
	v_mul_f32_e64 v213, |v189|, s93
	v_mul_f32_e64 v214, |v190|, s93
	v_mul_f32_e64 v215, |v191|, s93
	v_exp_f32_e32 v208, v208
	v_exp_f32_e32 v209, v209
	v_exp_f32_e32 v210, v210
	v_exp_f32_e32 v211, v211
	v_exp_f32_e32 v212, v212
	v_exp_f32_e32 v213, v213
	v_exp_f32_e32 v214, v214
	v_exp_f32_e32 v215, v215
	v_add_f32_e32 v208, 1.0, v208
	v_add_f32_e32 v209, 1.0, v209
	v_add_f32_e32 v210, 1.0, v210
	v_add_f32_e32 v211, 1.0, v211
	v_add_f32_e32 v212, 1.0, v212
	v_add_f32_e32 v213, 1.0, v213
	v_add_f32_e32 v214, 1.0, v214
	v_add_f32_e32 v215, 1.0, v215
	v_log_f32_e32 v208, v208
	v_log_f32_e32 v209, v209
	v_log_f32_e32 v210, v210
	v_log_f32_e32 v211, v211
	v_log_f32_e32 v212, v212
	v_log_f32_e32 v213, v213
	v_log_f32_e32 v214, v214
	v_log_f32_e32 v215, v215
	v_mul_f32_e32 v216, 0x3f317217, v208
	v_mul_f32_e32 v217, 0x3f317217, v209
	v_mul_f32_e32 v218, 0x3f317217, v210
	v_mul_f32_e32 v219, 0x3f317217, v211
	v_mul_f32_e32 v220, 0x3f317217, v212
	v_mul_f32_e32 v221, 0x3f317217, v213
	v_mul_f32_e32 v222, 0x3f317217, v214
	v_mul_f32_e32 v223, 0x3f317217, v215
	v_fma_f32 v216, v208, s95, -v216
	v_fma_f32 v217, v209, s95, -v217
	v_fma_f32 v218, v210, s95, -v218
	v_fma_f32 v219, v211, s95, -v219
	v_fma_f32 v220, v212, s95, -v220
	v_fma_f32 v221, v213, s95, -v221
	v_fma_f32 v222, v214, s95, -v222
	v_fma_f32 v223, v215, s95, -v223
	v_fmac_f32_e32 v216, 0x3377d1cf, v208
	v_fmac_f32_e32 v217, 0x3377d1cf, v209
	v_fmac_f32_e32 v218, 0x3377d1cf, v210
	v_fmac_f32_e32 v219, 0x3377d1cf, v211
	v_fmac_f32_e32 v220, 0x3377d1cf, v212
	v_fmac_f32_e32 v221, 0x3377d1cf, v213
	v_fmac_f32_e32 v222, 0x3377d1cf, v214
	v_fmac_f32_e32 v223, 0x3377d1cf, v215
	v_fmac_f32_e32 v216, 0x3f317217, v208
	v_fmac_f32_e32 v217, 0x3f317217, v209
	v_fmac_f32_e32 v218, 0x3f317217, v210
	v_fmac_f32_e32 v219, 0x3f317217, v211
	v_fmac_f32_e32 v220, 0x3f317217, v212
	v_fmac_f32_e32 v221, 0x3f317217, v213
	v_fmac_f32_e32 v222, 0x3f317217, v214
	v_fmac_f32_e32 v223, 0x3f317217, v215
	v_sub_f32_e32 v200, v200, v216
	v_sub_f32_e32 v201, v201, v217
	v_sub_f32_e32 v202, v202, v218
	v_sub_f32_e32 v203, v203, v219
	v_sub_f32_e32 v204, v204, v220
	v_sub_f32_e32 v205, v205, v221
	v_sub_f32_e32 v206, v206, v222
	v_sub_f32_e32 v207, v207, v223
	v_mul_f32_e32 v184, 0x3d800000, v200
	v_mul_f32_e32 v185, 0x3d800000, v201
	v_mul_f32_e32 v186, 0x3d800000, v202
	v_mul_f32_e32 v187, 0x3d800000, v203
	v_mul_f32_e32 v188, 0x3d800000, v204
	v_mul_f32_e32 v189, 0x3d800000, v205
	v_mul_f32_e32 v190, 0x3d800000, v206
	v_mul_f32_e32 v191, 0x3d800000, v207
	v_add_f32_e32 v192, v178, v192
	v_add_f32_e32 v193, v178, v193
	v_add_f32_e32 v194, v178, v194
	v_add_f32_e32 v195, v178, v195
	v_add_f32_e32 v196, v179, v196
	v_add_f32_e32 v197, v179, v197
	v_add_f32_e32 v198, v179, v198
	v_add_f32_e32 v199, v179, v199
	v_min_f32_e32 v200, 0, v192
	v_min_f32_e32 v201, 0, v193
	v_min_f32_e32 v202, 0, v194
	v_min_f32_e32 v203, 0, v195
	v_min_f32_e32 v204, 0, v196
	v_min_f32_e32 v205, 0, v197
	v_min_f32_e32 v206, 0, v198
	v_min_f32_e32 v207, 0, v199
	v_mul_f32_e64 v208, |v192|, s93
	v_mul_f32_e64 v209, |v193|, s93
	v_mul_f32_e64 v210, |v194|, s93
	v_mul_f32_e64 v211, |v195|, s93
	v_mul_f32_e64 v212, |v196|, s93
	v_mul_f32_e64 v213, |v197|, s93
	v_mul_f32_e64 v214, |v198|, s93
	v_mul_f32_e64 v215, |v199|, s93
	v_exp_f32_e32 v208, v208
	v_exp_f32_e32 v209, v209
	v_exp_f32_e32 v210, v210
	v_exp_f32_e32 v211, v211
	v_exp_f32_e32 v212, v212
	v_exp_f32_e32 v213, v213
	v_exp_f32_e32 v214, v214
	v_exp_f32_e32 v215, v215
	v_add_f32_e32 v208, 1.0, v208
	v_add_f32_e32 v209, 1.0, v209
	v_add_f32_e32 v210, 1.0, v210
	v_add_f32_e32 v211, 1.0, v211
	v_add_f32_e32 v212, 1.0, v212
	v_add_f32_e32 v213, 1.0, v213
	v_add_f32_e32 v214, 1.0, v214
	v_add_f32_e32 v215, 1.0, v215
	v_log_f32_e32 v208, v208
	v_log_f32_e32 v209, v209
	v_log_f32_e32 v210, v210
	v_log_f32_e32 v211, v211
	v_log_f32_e32 v212, v212
	v_log_f32_e32 v213, v213
	v_log_f32_e32 v214, v214
	v_log_f32_e32 v215, v215
	v_mul_f32_e32 v216, 0x3f317217, v208
	v_mul_f32_e32 v217, 0x3f317217, v209
	v_mul_f32_e32 v218, 0x3f317217, v210
	v_mul_f32_e32 v219, 0x3f317217, v211
	v_mul_f32_e32 v220, 0x3f317217, v212
	v_mul_f32_e32 v221, 0x3f317217, v213
	v_mul_f32_e32 v222, 0x3f317217, v214
	v_mul_f32_e32 v223, 0x3f317217, v215
	v_fma_f32 v216, v208, s95, -v216
	v_fma_f32 v217, v209, s95, -v217
	v_fma_f32 v218, v210, s95, -v218
	v_fma_f32 v219, v211, s95, -v219
	v_fma_f32 v220, v212, s95, -v220
	v_fma_f32 v221, v213, s95, -v221
	v_fma_f32 v222, v214, s95, -v222
	v_fma_f32 v223, v215, s95, -v223
	v_fmac_f32_e32 v216, 0x3377d1cf, v208
	v_fmac_f32_e32 v217, 0x3377d1cf, v209
	v_fmac_f32_e32 v218, 0x3377d1cf, v210
	v_fmac_f32_e32 v219, 0x3377d1cf, v211
	v_fmac_f32_e32 v220, 0x3377d1cf, v212
; __device__ __forceinline__ void store_rm4(u16* dst, size_t ld, int row0, int c, float v0, float v1, float v2, float v3, bool odd) {
;   {
;     float s = odd ? v0 : v1, r = dpp_swap1(s);
;     float lo = odd ? r : v0, hi = odd ? v1 : r;
;     *(unsigned*)(dst + (size_t)(row0 + (odd ? 1 : 0)) * ld + (c - (odd ? 1 : 0))) = pack2(lo, hi);
;   }
;   {
;     float s = odd ? v2 : v3, r = dpp_swap1(s);
;     float lo = odd ? r : v2, hi = odd ? v3 : r;
;     *(unsigned*)(dst + (size_t)(row0 + 2 + (odd ? 1 : 0)) * ld + (c - (odd ? 1 : 0))) = pack2(lo, hi);
;   }
; }
;   __device__ __forceinline__ void operator()(f32x4 (&acc)[2][2][4][2], int brow, int bcol, int wr, int wc, int fr, int fq) const {
;     ...
;         for (int ai = 0; ai < 2; ++ai)
; #pragma unroll
;           for (int m = 0; m < 4; ++m) {
;             int rl = ai * 128 + wr * 64 + m * 16;
;             s16x4 af = *(const s16x4*)(glr + (rl + fr) * 32 + dir * 16 + fq * 4);
;             int row0 = brow + rl + fq * 4;
; #pragma unroll
;             for (int bj = 0; bj < 2; ++bj)
; #pragma unroll
;               for (int n = 0; n < 2; ++n) {
;                 f32x4 z4 = {0.f, 0.f, 0.f, 0.f};
;                 z4 = __builtin_amdgcn_mfma_f32_16x16x16bf16_1k(af, bfr[bj][n], z4, 0, 0, 0);
;                 int c = bj * 128 + wc * 32 + n * 16 + fr;
;                 float bb = bias[c];
;                 float ls[4];
; #pragma unroll
;                 for (int j = 0; j < 4; ++j) {
;                   float z = z4[j] + bb;
;                   ls[j] = (fminf(z, 0.f) - __logf(1.f + __expf(-fabsf(z)))) * (1.f / 16.f);
;                 }
;                 store_rm4(dst, 256, row0, c, ls[0], ls[1], ls[2], ls[3], fr & 1);
;               }
	v_fmac_f32_e32 v221, 0x3377d1cf, v213
	v_fmac_f32_e32 v222, 0x3377d1cf, v214
	v_fmac_f32_e32 v223, 0x3377d1cf, v215
	v_fmac_f32_e32 v216, 0x3f317217, v208
	v_fmac_f32_e32 v217, 0x3f317217, v209
	v_fmac_f32_e32 v218, 0x3f317217, v210
	v_fmac_f32_e32 v219, 0x3f317217, v211
	v_fmac_f32_e32 v220, 0x3f317217, v212
	v_fmac_f32_e32 v221, 0x3f317217, v213
	v_fmac_f32_e32 v222, 0x3f317217, v214
	v_fmac_f32_e32 v223, 0x3f317217, v215
	v_sub_f32_e32 v200, v200, v216
	v_sub_f32_e32 v201, v201, v217
	v_sub_f32_e32 v202, v202, v218
	v_sub_f32_e32 v203, v203, v219
	v_sub_f32_e32 v204, v204, v220
	v_sub_f32_e32 v205, v205, v221
	v_sub_f32_e32 v206, v206, v222
	v_sub_f32_e32 v207, v207, v223
	v_mul_f32_e32 v192, 0x3d800000, v200
	v_mul_f32_e32 v193, 0x3d800000, v201
	v_mul_f32_e32 v194, 0x3d800000, v202
	v_mul_f32_e32 v195, 0x3d800000, v203
	v_mul_f32_e32 v196, 0x3d800000, v204
	v_mul_f32_e32 v197, 0x3d800000, v205
	v_mul_f32_e32 v198, 0x3d800000, v206
	v_mul_f32_e32 v199, 0x3d800000, v207
	v_cvt_pk_bf16_f32 v208, v184, v185
	v_cvt_pk_bf16_f32 v209, v186, v187
	v_cvt_pk_bf16_f32 v210, v188, v189
	v_cvt_pk_bf16_f32 v211, v190, v191
	v_cvt_pk_bf16_f32 v212, v192, v193
	v_cvt_pk_bf16_f32 v213, v194, v195
	v_cvt_pk_bf16_f32 v214, v196, v197
	v_cvt_pk_bf16_f32 v215, v198, v199
	v_mov_b32_dpp v216, v208 quad_perm:[1,0,3,2] row_mask:0xf bank_mask:0xf bound_ctrl:1
	v_mov_b32_dpp v217, v209 quad_perm:[1,0,3,2] row_mask:0xf bank_mask:0xf bound_ctrl:1
	v_mov_b32_dpp v218, v210 quad_perm:[1,0,3,2] row_mask:0xf bank_mask:0xf bound_ctrl:1
	v_mov_b32_dpp v219, v211 quad_perm:[1,0,3,2] row_mask:0xf bank_mask:0xf bound_ctrl:1
	v_mov_b32_dpp v220, v212 quad_perm:[1,0,3,2] row_mask:0xf bank_mask:0xf bound_ctrl:1
	v_mov_b32_dpp v221, v213 quad_perm:[1,0,3,2] row_mask:0xf bank_mask:0xf bound_ctrl:1
	v_mov_b32_dpp v222, v214 quad_perm:[1,0,3,2] row_mask:0xf bank_mask:0xf bound_ctrl:1
	v_mov_b32_dpp v223, v215 quad_perm:[1,0,3,2] row_mask:0xf bank_mask:0xf bound_ctrl:1
	v_perm_b32 v208, v216, v208, v164
	v_perm_b32 v209, v217, v209, v164
	v_perm_b32 v210, v218, v210, v164
	v_perm_b32 v211, v219, v211, v164
	v_perm_b32 v212, v220, v212, v164
	v_perm_b32 v213, v221, v213, v164
	v_perm_b32 v214, v222, v214, v164
	v_perm_b32 v215, v223, v215, v164
	global_store_dword v167, v208, s[8:9]
	global_store_dword v167, v209, s[8:9] offset:1024
	global_store_dword v167, v210, s[8:9] offset:32
	global_store_dword v167, v211, s[8:9] offset:1056
	global_store_dword v167, v212, s[8:9] offset:256
	global_store_dword v167, v213, s[8:9] offset:1280
	global_store_dword v167, v214, s[8:9] offset:288
	global_store_dword v167, v215, s[8:9] offset:1312
	ds_read_b64 v[180:181], v160 offset:58400
	v_add_u32_e32 v167, 0x12000, v163
	s_waitcnt lgkmcnt(0)
	v_mfma_f32_16x16x16_bf16 v[184:187], v[180:181], v[168:169], 0
	v_mfma_f32_16x16x16_bf16 v[188:191], v[180:181], v[170:171], 0
	v_mfma_f32_16x16x16_bf16 v[192:195], v[180:181], v[172:173], 0
	v_mfma_f32_16x16x16_bf16 v[196:199], v[180:181], v[174:175], 0
	s_nop 7
	s_nop 1
	v_add_f32_e32 v184, v176, v184
	v_add_f32_e32 v185, v176, v185
	v_add_f32_e32 v186, v176, v186
	v_add_f32_e32 v187, v176, v187
	v_add_f32_e32 v188, v177, v188
	v_add_f32_e32 v189, v177, v189
	v_add_f32_e32 v190, v177, v190
	v_add_f32_e32 v191, v177, v191
	v_min_f32_e32 v200, 0, v184
	v_min_f32_e32 v201, 0, v185
	v_min_f32_e32 v202, 0, v186
	v_min_f32_e32 v203, 0, v187
	v_min_f32_e32 v204, 0, v188
	v_min_f32_e32 v205, 0, v189
	v_min_f32_e32 v206, 0, v190
	v_min_f32_e32 v207, 0, v191
	v_mul_f32_e64 v208, |v184|, s93
	v_mul_f32_e64 v209, |v185|, s93
	v_mul_f32_e64 v210, |v186|, s93
	v_mul_f32_e64 v211, |v187|, s93
	v_mul_f32_e64 v212, |v188|, s93
	v_mul_f32_e64 v213, |v189|, s93
	v_mul_f32_e64 v214, |v190|, s93
	v_mul_f32_e64 v215, |v191|, s93
	v_exp_f32_e32 v208, v208
	v_exp_f32_e32 v209, v209
	v_exp_f32_e32 v210, v210
	v_exp_f32_e32 v211, v211
	v_exp_f32_e32 v212, v212
	v_exp_f32_e32 v213, v213
	v_exp_f32_e32 v214, v214
	v_exp_f32_e32 v215, v215
	v_add_f32_e32 v208, 1.0, v208
	v_add_f32_e32 v209, 1.0, v209
	v_add_f32_e32 v210, 1.0, v210
	v_add_f32_e32 v211, 1.0, v211
	v_add_f32_e32 v212, 1.0, v212
	v_add_f32_e32 v213, 1.0, v213
	v_add_f32_e32 v214, 1.0, v214
	v_add_f32_e32 v215, 1.0, v215
	v_log_f32_e32 v208, v208
	v_log_f32_e32 v209, v209
	v_log_f32_e32 v210, v210
	v_log_f32_e32 v211, v211
	v_log_f32_e32 v212, v212
	v_log_f32_e32 v213, v213
	v_log_f32_e32 v214, v214
	v_log_f32_e32 v215, v215
	v_mul_f32_e32 v216, 0x3f317217, v208
	v_mul_f32_e32 v217, 0x3f317217, v209
	v_mul_f32_e32 v218, 0x3f317217, v210
	v_mul_f32_e32 v219, 0x3f317217, v211
	v_mul_f32_e32 v220, 0x3f317217, v212
	v_mul_f32_e32 v221, 0x3f317217, v213
	v_mul_f32_e32 v222, 0x3f317217, v214
	v_mul_f32_e32 v223, 0x3f317217, v215
	v_fma_f32 v216, v208, s95, -v216
	v_fma_f32 v217, v209, s95, -v217
	v_fma_f32 v218, v210, s95, -v218
	v_fma_f32 v219, v211, s95, -v219
	v_fma_f32 v220, v212, s95, -v220
	v_fma_f32 v221, v213, s95, -v221
	v_fma_f32 v222, v214, s95, -v222
	v_fma_f32 v223, v215, s95, -v223
	v_fmac_f32_e32 v216, 0x3377d1cf, v208
	v_fmac_f32_e32 v217, 0x3377d1cf, v209
	v_fmac_f32_e32 v218, 0x3377d1cf, v210
	v_fmac_f32_e32 v219, 0x3377d1cf, v211
	v_fmac_f32_e32 v220, 0x3377d1cf, v212
	v_fmac_f32_e32 v221, 0x3377d1cf, v213
	v_fmac_f32_e32 v222, 0x3377d1cf, v214
	v_fmac_f32_e32 v223, 0x3377d1cf, v215
	v_fmac_f32_e32 v216, 0x3f317217, v208
	v_fmac_f32_e32 v217, 0x3f317217, v209
	v_fmac_f32_e32 v218, 0x3f317217, v210
	v_fmac_f32_e32 v219, 0x3f317217, v211
	v_fmac_f32_e32 v220, 0x3f317217, v212
	v_fmac_f32_e32 v221, 0x3f317217, v213
	v_fmac_f32_e32 v222, 0x3f317217, v214
	v_fmac_f32_e32 v223, 0x3f317217, v215
; __device__ __forceinline__ void store_rm4(u16* dst, size_t ld, int row0, int c, float v0, float v1, float v2, float v3, bool odd) {
;   {
;     float s = odd ? v0 : v1, r = dpp_swap1(s);
;     float lo = odd ? r : v0, hi = odd ? v1 : r;
;     *(unsigned*)(dst + (size_t)(row0 + (odd ? 1 : 0)) * ld + (c - (odd ? 1 : 0))) = pack2(lo, hi);
;   }
;   {
;     float s = odd ? v2 : v3, r = dpp_swap1(s);
;     float lo = odd ? r : v2, hi = odd ? v3 : r;
;     *(unsigned*)(dst + (size_t)(row0 + 2 + (odd ? 1 : 0)) * ld + (c - (odd ? 1 : 0))) = pack2(lo, hi);
;   }
; }
;   __device__ __forceinline__ void operator()(f32x4 (&acc)[2][2][4][2], int brow, int bcol, int wr, int wc, int fr, int fq) const {
;     ...
;         for (int ai = 0; ai < 2; ++ai)
; #pragma unroll
;           for (int m = 0; m < 4; ++m) {
;             int rl = ai * 128 + wr * 64 + m * 16;
;             s16x4 af = *(const s16x4*)(glr + (rl + fr) * 32 + dir * 16 + fq * 4);
;             int row0 = brow + rl + fq * 4;
; #pragma unroll
;             for (int bj = 0; bj < 2; ++bj)
; #pragma unroll
;               for (int n = 0; n < 2; ++n) {
;                 f32x4 z4 = {0.f, 0.f, 0.f, 0.f};
;                 z4 = __builtin_amdgcn_mfma_f32_16x16x16bf16_1k(af, bfr[bj][n], z4, 0, 0, 0);
;                 int c = bj * 128 + wc * 32 + n * 16 + fr;
;                 float bb = bias[c];
;                 float ls[4];
; #pragma unroll
;                 for (int j = 0; j < 4; ++j) {
;                   float z = z4[j] + bb;
;                   ls[j] = (fminf(z, 0.f) - __logf(1.f + __expf(-fabsf(z)))) * (1.f / 16.f);
;                 }
;                 store_rm4(dst, 256, row0, c, ls[0], ls[1], ls[2], ls[3], fr & 1);
;               }
	v_sub_f32_e32 v200, v200, v216
	v_sub_f32_e32 v201, v201, v217
	v_sub_f32_e32 v202, v202, v218
	v_sub_f32_e32 v203, v203, v219
	v_sub_f32_e32 v204, v204, v220
	v_sub_f32_e32 v205, v205, v221
	v_sub_f32_e32 v206, v206, v222
	v_sub_f32_e32 v207, v207, v223
	v_mul_f32_e32 v184, 0x3d800000, v200
	v_mul_f32_e32 v185, 0x3d800000, v201
	v_mul_f32_e32 v186, 0x3d800000, v202
	v_mul_f32_e32 v187, 0x3d800000, v203
	v_mul_f32_e32 v188, 0x3d800000, v204
	v_mul_f32_e32 v189, 0x3d800000, v205
	v_mul_f32_e32 v190, 0x3d800000, v206
	v_mul_f32_e32 v191, 0x3d800000, v207
	v_add_f32_e32 v192, v178, v192
	v_add_f32_e32 v193, v178, v193
	v_add_f32_e32 v194, v178, v194
	v_add_f32_e32 v195, v178, v195
	v_add_f32_e32 v196, v179, v196
	v_add_f32_e32 v197, v179, v197
	v_add_f32_e32 v198, v179, v198
	v_add_f32_e32 v199, v179, v199
	v_min_f32_e32 v200, 0, v192
	v_min_f32_e32 v201, 0, v193
	v_min_f32_e32 v202, 0, v194
	v_min_f32_e32 v203, 0, v195
	v_min_f32_e32 v204, 0, v196
	v_min_f32_e32 v205, 0, v197
	v_min_f32_e32 v206, 0, v198
	v_min_f32_e32 v207, 0, v199
	v_mul_f32_e64 v208, |v192|, s93
	v_mul_f32_e64 v209, |v193|, s93
	v_mul_f32_e64 v210, |v194|, s93
	v_mul_f32_e64 v211, |v195|, s93
	v_mul_f32_e64 v212, |v196|, s93
	v_mul_f32_e64 v213, |v197|, s93
	v_mul_f32_e64 v214, |v198|, s93
	v_mul_f32_e64 v215, |v199|, s93
	v_exp_f32_e32 v208, v208
	v_exp_f32_e32 v209, v209
	v_exp_f32_e32 v210, v210
	v_exp_f32_e32 v211, v211
	v_exp_f32_e32 v212, v212
	v_exp_f32_e32 v213, v213
	v_exp_f32_e32 v214, v214
	v_exp_f32_e32 v215, v215
	v_add_f32_e32 v208, 1.0, v208
	v_add_f32_e32 v209, 1.0, v209
	v_add_f32_e32 v210, 1.0, v210
	v_add_f32_e32 v211, 1.0, v211
	v_add_f32_e32 v212, 1.0, v212
	v_add_f32_e32 v213, 1.0, v213
	v_add_f32_e32 v214, 1.0, v214
	v_add_f32_e32 v215, 1.0, v215
	v_log_f32_e32 v208, v208
	v_log_f32_e32 v209, v209
	v_log_f32_e32 v210, v210
	v_log_f32_e32 v211, v211
	v_log_f32_e32 v212, v212
	v_log_f32_e32 v213, v213
	v_log_f32_e32 v214, v214
	v_log_f32_e32 v215, v215
	v_mul_f32_e32 v216, 0x3f317217, v208
	v_mul_f32_e32 v217, 0x3f317217, v209
	v_mul_f32_e32 v218, 0x3f317217, v210
	v_mul_f32_e32 v219, 0x3f317217, v211
	v_mul_f32_e32 v220, 0x3f317217, v212
	v_mul_f32_e32 v221, 0x3f317217, v213
	v_mul_f32_e32 v222, 0x3f317217, v214
	v_mul_f32_e32 v223, 0x3f317217, v215
	v_fma_f32 v216, v208, s95, -v216
	v_fma_f32 v217, v209, s95, -v217
	v_fma_f32 v218, v210, s95, -v218
	v_fma_f32 v219, v211, s95, -v219
	v_fma_f32 v220, v212, s95, -v220
	v_fma_f32 v221, v213, s95, -v221
	v_fma_f32 v222, v214, s95, -v222
	v_fma_f32 v223, v215, s95, -v223
	v_fmac_f32_e32 v216, 0x3377d1cf, v208
	v_fmac_f32_e32 v217, 0x3377d1cf, v209
	v_fmac_f32_e32 v218, 0x3377d1cf, v210
	v_fmac_f32_e32 v219, 0x3377d1cf, v211
	v_fmac_f32_e32 v220, 0x3377d1cf, v212
	v_fmac_f32_e32 v221, 0x3377d1cf, v213
	v_fmac_f32_e32 v222, 0x3377d1cf, v214
	v_fmac_f32_e32 v223, 0x3377d1cf, v215
	v_fmac_f32_e32 v216, 0x3f317217, v208
	v_fmac_f32_e32 v217, 0x3f317217, v209
	v_fmac_f32_e32 v218, 0x3f317217, v210
	v_fmac_f32_e32 v219, 0x3f317217, v211
	v_fmac_f32_e32 v220, 0x3f317217, v212
	v_fmac_f32_e32 v221, 0x3f317217, v213
	v_fmac_f32_e32 v222, 0x3f317217, v214
	v_fmac_f32_e32 v223, 0x3f317217, v215
	v_sub_f32_e32 v200, v200, v216
	v_sub_f32_e32 v201, v201, v217
	v_sub_f32_e32 v202, v202, v218
	v_sub_f32_e32 v203, v203, v219
	v_sub_f32_e32 v204, v204, v220
	v_sub_f32_e32 v205, v205, v221
	v_sub_f32_e32 v206, v206, v222
	v_sub_f32_e32 v207, v207, v223
	v_mul_f32_e32 v192, 0x3d800000, v200
	v_mul_f32_e32 v193, 0x3d800000, v201
	v_mul_f32_e32 v194, 0x3d800000, v202
	v_mul_f32_e32 v195, 0x3d800000, v203
	v_mul_f32_e32 v196, 0x3d800000, v204
	v_mul_f32_e32 v197, 0x3d800000, v205
	v_mul_f32_e32 v198, 0x3d800000, v206
	v_mul_f32_e32 v199, 0x3d800000, v207
	v_cvt_pk_bf16_f32 v208, v184, v185
	v_cvt_pk_bf16_f32 v209, v186, v187
	v_cvt_pk_bf16_f32 v210, v188, v189
	v_cvt_pk_bf16_f32 v211, v190, v191
	v_cvt_pk_bf16_f32 v212, v192, v193
	v_cvt_pk_bf16_f32 v213, v194, v195
	v_cvt_pk_bf16_f32 v214, v196, v197
	v_cvt_pk_bf16_f32 v215, v198, v199
	v_mov_b32_dpp v216, v208 quad_perm:[1,0,3,2] row_mask:0xf bank_mask:0xf bound_ctrl:1
	v_mov_b32_dpp v217, v209 quad_perm:[1,0,3,2] row_mask:0xf bank_mask:0xf bound_ctrl:1
	v_mov_b32_dpp v218, v210 quad_perm:[1,0,3,2] row_mask:0xf bank_mask:0xf bound_ctrl:1
	v_mov_b32_dpp v219, v211 quad_perm:[1,0,3,2] row_mask:0xf bank_mask:0xf bound_ctrl:1
	v_mov_b32_dpp v220, v212 quad_perm:[1,0,3,2] row_mask:0xf bank_mask:0xf bound_ctrl:1
	v_mov_b32_dpp v221, v213 quad_perm:[1,0,3,2] row_mask:0xf bank_mask:0xf bound_ctrl:1
	v_mov_b32_dpp v222, v214 quad_perm:[1,0,3,2] row_mask:0xf bank_mask:0xf bound_ctrl:1
	v_mov_b32_dpp v223, v215 quad_perm:[1,0,3,2] row_mask:0xf bank_mask:0xf bound_ctrl:1
	v_perm_b32 v208, v216, v208, v164
	v_perm_b32 v209, v217, v209, v164
	v_perm_b32 v210, v218, v210, v164
	v_perm_b32 v211, v219, v211, v164
	v_perm_b32 v212, v220, v212, v164
	v_perm_b32 v213, v221, v213, v164
	v_perm_b32 v214, v222, v214, v164
	v_perm_b32 v215, v223, v215, v164
	global_store_dword v167, v208, s[8:9]
	global_store_dword v167, v209, s[8:9] offset:1024
	global_store_dword v167, v210, s[8:9] offset:32
	global_store_dword v167, v211, s[8:9] offset:1056
	global_store_dword v167, v212, s[8:9] offset:256
	global_store_dword v167, v213, s[8:9] offset:1280
	global_store_dword v167, v214, s[8:9] offset:288
	global_store_dword v167, v215, s[8:9] offset:1312
	ds_read_b64 v[180:181], v160 offset:59424
	v_add_u32_e32 v167, 0x14000, v163
	s_waitcnt lgkmcnt(0)
; __device__ __forceinline__ void store_rm4(u16* dst, size_t ld, int row0, int c, float v0, float v1, float v2, float v3, bool odd) {
;   {
;     float s = odd ? v0 : v1, r = dpp_swap1(s);
;     float lo = odd ? r : v0, hi = odd ? v1 : r;
;     *(unsigned*)(dst + (size_t)(row0 + (odd ? 1 : 0)) * ld + (c - (odd ? 1 : 0))) = pack2(lo, hi);
;   }
;   {
;     float s = odd ? v2 : v3, r = dpp_swap1(s);
;     float lo = odd ? r : v2, hi = odd ? v3 : r;
;     *(unsigned*)(dst + (size_t)(row0 + 2 + (odd ? 1 : 0)) * ld + (c - (odd ? 1 : 0))) = pack2(lo, hi);
;   }
; }
;   __device__ __forceinline__ void operator()(f32x4 (&acc)[2][2][4][2], int brow, int bcol, int wr, int wc, int fr, int fq) const {
;     ...
;         for (int ai = 0; ai < 2; ++ai)
; #pragma unroll
;           for (int m = 0; m < 4; ++m) {
;             int rl = ai * 128 + wr * 64 + m * 16;
;             s16x4 af = *(const s16x4*)(glr + (rl + fr) * 32 + dir * 16 + fq * 4);
;             int row0 = brow + rl + fq * 4;
; #pragma unroll
;             for (int bj = 0; bj < 2; ++bj)
; #pragma unroll
;               for (int n = 0; n < 2; ++n) {
;                 f32x4 z4 = {0.f, 0.f, 0.f, 0.f};
;                 z4 = __builtin_amdgcn_mfma_f32_16x16x16bf16_1k(af, bfr[bj][n], z4, 0, 0, 0);
;                 int c = bj * 128 + wc * 32 + n * 16 + fr;
;                 float bb = bias[c];
;                 float ls[4];
; #pragma unroll
;                 for (int j = 0; j < 4; ++j) {
;                   float z = z4[j] + bb;
;                   ls[j] = (fminf(z, 0.f) - __logf(1.f + __expf(-fabsf(z)))) * (1.f / 16.f);
;                 }
;                 store_rm4(dst, 256, row0, c, ls[0], ls[1], ls[2], ls[3], fr & 1);
;               }
	v_mfma_f32_16x16x16_bf16 v[184:187], v[180:181], v[168:169], 0
	v_mfma_f32_16x16x16_bf16 v[188:191], v[180:181], v[170:171], 0
	v_mfma_f32_16x16x16_bf16 v[192:195], v[180:181], v[172:173], 0
	v_mfma_f32_16x16x16_bf16 v[196:199], v[180:181], v[174:175], 0
	s_nop 7
	s_nop 1
	v_add_f32_e32 v184, v176, v184
	v_add_f32_e32 v185, v176, v185
	v_add_f32_e32 v186, v176, v186
	v_add_f32_e32 v187, v176, v187
	v_add_f32_e32 v188, v177, v188
	v_add_f32_e32 v189, v177, v189
	v_add_f32_e32 v190, v177, v190
	v_add_f32_e32 v191, v177, v191
	v_min_f32_e32 v200, 0, v184
	v_min_f32_e32 v201, 0, v185
	v_min_f32_e32 v202, 0, v186
	v_min_f32_e32 v203, 0, v187
	v_min_f32_e32 v204, 0, v188
	v_min_f32_e32 v205, 0, v189
	v_min_f32_e32 v206, 0, v190
	v_min_f32_e32 v207, 0, v191
	v_mul_f32_e64 v208, |v184|, s93
	v_mul_f32_e64 v209, |v185|, s93
	v_mul_f32_e64 v210, |v186|, s93
	v_mul_f32_e64 v211, |v187|, s93
	v_mul_f32_e64 v212, |v188|, s93
	v_mul_f32_e64 v213, |v189|, s93
	v_mul_f32_e64 v214, |v190|, s93
	v_mul_f32_e64 v215, |v191|, s93
	v_exp_f32_e32 v208, v208
	v_exp_f32_e32 v209, v209
	v_exp_f32_e32 v210, v210
	v_exp_f32_e32 v211, v211
	v_exp_f32_e32 v212, v212
	v_exp_f32_e32 v213, v213
	v_exp_f32_e32 v214, v214
	v_exp_f32_e32 v215, v215
	v_add_f32_e32 v208, 1.0, v208
	v_add_f32_e32 v209, 1.0, v209
	v_add_f32_e32 v210, 1.0, v210
	v_add_f32_e32 v211, 1.0, v211
	v_add_f32_e32 v212, 1.0, v212
	v_add_f32_e32 v213, 1.0, v213
	v_add_f32_e32 v214, 1.0, v214
	v_add_f32_e32 v215, 1.0, v215
	v_log_f32_e32 v208, v208
	v_log_f32_e32 v209, v209
	v_log_f32_e32 v210, v210
	v_log_f32_e32 v211, v211
	v_log_f32_e32 v212, v212
	v_log_f32_e32 v213, v213
	v_log_f32_e32 v214, v214
	v_log_f32_e32 v215, v215
	v_mul_f32_e32 v216, 0x3f317217, v208
	v_mul_f32_e32 v217, 0x3f317217, v209
	v_mul_f32_e32 v218, 0x3f317217, v210
	v_mul_f32_e32 v219, 0x3f317217, v211
	v_mul_f32_e32 v220, 0x3f317217, v212
	v_mul_f32_e32 v221, 0x3f317217, v213
	v_mul_f32_e32 v222, 0x3f317217, v214
	v_mul_f32_e32 v223, 0x3f317217, v215
	v_fma_f32 v216, v208, s95, -v216
	v_fma_f32 v217, v209, s95, -v217
	v_fma_f32 v218, v210, s95, -v218
	v_fma_f32 v219, v211, s95, -v219
	v_fma_f32 v220, v212, s95, -v220
	v_fma_f32 v221, v213, s95, -v221
	v_fma_f32 v222, v214, s95, -v222
	v_fma_f32 v223, v215, s95, -v223
	v_fmac_f32_e32 v216, 0x3377d1cf, v208
	v_fmac_f32_e32 v217, 0x3377d1cf, v209
	v_fmac_f32_e32 v218, 0x3377d1cf, v210
	v_fmac_f32_e32 v219, 0x3377d1cf, v211
	v_fmac_f32_e32 v220, 0x3377d1cf, v212
	v_fmac_f32_e32 v221, 0x3377d1cf, v213
	v_fmac_f32_e32 v222, 0x3377d1cf, v214
	v_fmac_f32_e32 v223, 0x3377d1cf, v215
	v_fmac_f32_e32 v216, 0x3f317217, v208
	v_fmac_f32_e32 v217, 0x3f317217, v209
	v_fmac_f32_e32 v218, 0x3f317217, v210
	v_fmac_f32_e32 v219, 0x3f317217, v211
	v_fmac_f32_e32 v220, 0x3f317217, v212
	v_fmac_f32_e32 v221, 0x3f317217, v213
	v_fmac_f32_e32 v222, 0x3f317217, v214
	v_fmac_f32_e32 v223, 0x3f317217, v215
	v_sub_f32_e32 v200, v200, v216
	v_sub_f32_e32 v201, v201, v217
	v_sub_f32_e32 v202, v202, v218
	v_sub_f32_e32 v203, v203, v219
	v_sub_f32_e32 v204, v204, v220
	v_sub_f32_e32 v205, v205, v221
	v_sub_f32_e32 v206, v206, v222
	v_sub_f32_e32 v207, v207, v223
	v_mul_f32_e32 v184, 0x3d800000, v200
	v_mul_f32_e32 v185, 0x3d800000, v201
	v_mul_f32_e32 v186, 0x3d800000, v202
	v_mul_f32_e32 v187, 0x3d800000, v203
	v_mul_f32_e32 v188, 0x3d800000, v204
	v_mul_f32_e32 v189, 0x3d800000, v205
	v_mul_f32_e32 v190, 0x3d800000, v206
	v_mul_f32_e32 v191, 0x3d800000, v207
	v_add_f32_e32 v192, v178, v192
	v_add_f32_e32 v193, v178, v193
	v_add_f32_e32 v194, v178, v194
	v_add_f32_e32 v195, v178, v195
	v_add_f32_e32 v196, v179, v196
	v_add_f32_e32 v197, v179, v197
	v_add_f32_e32 v198, v179, v198
	v_add_f32_e32 v199, v179, v199
	v_min_f32_e32 v200, 0, v192
	v_min_f32_e32 v201, 0, v193
	v_min_f32_e32 v202, 0, v194
	v_min_f32_e32 v203, 0, v195
	v_min_f32_e32 v204, 0, v196
	v_min_f32_e32 v205, 0, v197
	v_min_f32_e32 v206, 0, v198
	v_min_f32_e32 v207, 0, v199
	v_mul_f32_e64 v208, |v192|, s93
	v_mul_f32_e64 v209, |v193|, s93
	v_mul_f32_e64 v210, |v194|, s93
	v_mul_f32_e64 v211, |v195|, s93
	v_mul_f32_e64 v212, |v196|, s93
	v_mul_f32_e64 v213, |v197|, s93
	v_mul_f32_e64 v214, |v198|, s93
	v_mul_f32_e64 v215, |v199|, s93
	v_exp_f32_e32 v208, v208
	v_exp_f32_e32 v209, v209
	v_exp_f32_e32 v210, v210
	v_exp_f32_e32 v211, v211
	v_exp_f32_e32 v212, v212
	v_exp_f32_e32 v213, v213
	v_exp_f32_e32 v214, v214
	v_exp_f32_e32 v215, v215
	v_add_f32_e32 v208, 1.0, v208
	v_add_f32_e32 v209, 1.0, v209
	v_add_f32_e32 v210, 1.0, v210
	v_add_f32_e32 v211, 1.0, v211
	v_add_f32_e32 v212, 1.0, v212
	v_add_f32_e32 v213, 1.0, v213
	v_add_f32_e32 v214, 1.0, v214
	v_add_f32_e32 v215, 1.0, v215
	v_log_f32_e32 v208, v208
	v_log_f32_e32 v209, v209
	v_log_f32_e32 v210, v210
	v_log_f32_e32 v211, v211
	v_log_f32_e32 v212, v212
	v_log_f32_e32 v213, v213
	v_log_f32_e32 v214, v214
	v_log_f32_e32 v215, v215
	v_mul_f32_e32 v216, 0x3f317217, v208
	v_mul_f32_e32 v217, 0x3f317217, v209
	v_mul_f32_e32 v218, 0x3f317217, v210
	v_mul_f32_e32 v219, 0x3f317217, v211
	v_mul_f32_e32 v220, 0x3f317217, v212
	v_mul_f32_e32 v221, 0x3f317217, v213
	v_mul_f32_e32 v222, 0x3f317217, v214
	v_mul_f32_e32 v223, 0x3f317217, v215
	v_fma_f32 v216, v208, s95, -v216
	v_fma_f32 v217, v209, s95, -v217
	v_fma_f32 v218, v210, s95, -v218
	v_fma_f32 v219, v211, s95, -v219
	v_fma_f32 v220, v212, s95, -v220
	v_fma_f32 v221, v213, s95, -v221
	v_fma_f32 v222, v214, s95, -v222
	v_fma_f32 v223, v215, s95, -v223
	v_fmac_f32_e32 v216, 0x3377d1cf, v208
	v_fmac_f32_e32 v217, 0x3377d1cf, v209
	v_fmac_f32_e32 v218, 0x3377d1cf, v210
	v_fmac_f32_e32 v219, 0x3377d1cf, v211
	v_fmac_f32_e32 v220, 0x3377d1cf, v212
; __device__ __forceinline__ void store_rm4(u16* dst, size_t ld, int row0, int c, float v0, float v1, float v2, float v3, bool odd) {
;   {
;     float s = odd ? v0 : v1, r = dpp_swap1(s);
;     float lo = odd ? r : v0, hi = odd ? v1 : r;
;     *(unsigned*)(dst + (size_t)(row0 + (odd ? 1 : 0)) * ld + (c - (odd ? 1 : 0))) = pack2(lo, hi);
;   }
;   {
;     float s = odd ? v2 : v3, r = dpp_swap1(s);
;     float lo = odd ? r : v2, hi = odd ? v3 : r;
;     *(unsigned*)(dst + (size_t)(row0 + 2 + (odd ? 1 : 0)) * ld + (c - (odd ? 1 : 0))) = pack2(lo, hi);
;   }
; }
;   __device__ __forceinline__ void operator()(f32x4 (&acc)[2][2][4][2], int brow, int bcol, int wr, int wc, int fr, int fq) const {
;     ...
;         for (int ai = 0; ai < 2; ++ai)
; #pragma unroll
;           for (int m = 0; m < 4; ++m) {
;             int rl = ai * 128 + wr * 64 + m * 16;
;             s16x4 af = *(const s16x4*)(glr + (rl + fr) * 32 + dir * 16 + fq * 4);
;             int row0 = brow + rl + fq * 4;
; #pragma unroll
;             for (int bj = 0; bj < 2; ++bj)
; #pragma unroll
;               for (int n = 0; n < 2; ++n) {
;                 f32x4 z4 = {0.f, 0.f, 0.f, 0.f};
;                 z4 = __builtin_amdgcn_mfma_f32_16x16x16bf16_1k(af, bfr[bj][n], z4, 0, 0, 0);
;                 int c = bj * 128 + wc * 32 + n * 16 + fr;
;                 float bb = bias[c];
;                 float ls[4];
; #pragma unroll
;                 for (int j = 0; j < 4; ++j) {
;                   float z = z4[j] + bb;
;                   ls[j] = (fminf(z, 0.f) - __logf(1.f + __expf(-fabsf(z)))) * (1.f / 16.f);
;                 }
;                 store_rm4(dst, 256, row0, c, ls[0], ls[1], ls[2], ls[3], fr & 1);
;               }
	v_fmac_f32_e32 v221, 0x3377d1cf, v213
	v_fmac_f32_e32 v222, 0x3377d1cf, v214
	v_fmac_f32_e32 v223, 0x3377d1cf, v215
	v_fmac_f32_e32 v216, 0x3f317217, v208
	v_fmac_f32_e32 v217, 0x3f317217, v209
	v_fmac_f32_e32 v218, 0x3f317217, v210
	v_fmac_f32_e32 v219, 0x3f317217, v211
	v_fmac_f32_e32 v220, 0x3f317217, v212
	v_fmac_f32_e32 v221, 0x3f317217, v213
	v_fmac_f32_e32 v222, 0x3f317217, v214
	v_fmac_f32_e32 v223, 0x3f317217, v215
	v_sub_f32_e32 v200, v200, v216
	v_sub_f32_e32 v201, v201, v217
	v_sub_f32_e32 v202, v202, v218
	v_sub_f32_e32 v203, v203, v219
	v_sub_f32_e32 v204, v204, v220
	v_sub_f32_e32 v205, v205, v221
	v_sub_f32_e32 v206, v206, v222
	v_sub_f32_e32 v207, v207, v223
	v_mul_f32_e32 v192, 0x3d800000, v200
	v_mul_f32_e32 v193, 0x3d800000, v201
	v_mul_f32_e32 v194, 0x3d800000, v202
	v_mul_f32_e32 v195, 0x3d800000, v203
	v_mul_f32_e32 v196, 0x3d800000, v204
	v_mul_f32_e32 v197, 0x3d800000, v205
	v_mul_f32_e32 v198, 0x3d800000, v206
	v_mul_f32_e32 v199, 0x3d800000, v207
	v_cvt_pk_bf16_f32 v208, v184, v185
	v_cvt_pk_bf16_f32 v209, v186, v187
	v_cvt_pk_bf16_f32 v210, v188, v189
	v_cvt_pk_bf16_f32 v211, v190, v191
	v_cvt_pk_bf16_f32 v212, v192, v193
	v_cvt_pk_bf16_f32 v213, v194, v195
	v_cvt_pk_bf16_f32 v214, v196, v197
	v_cvt_pk_bf16_f32 v215, v198, v199
	v_mov_b32_dpp v216, v208 quad_perm:[1,0,3,2] row_mask:0xf bank_mask:0xf bound_ctrl:1
	v_mov_b32_dpp v217, v209 quad_perm:[1,0,3,2] row_mask:0xf bank_mask:0xf bound_ctrl:1
	v_mov_b32_dpp v218, v210 quad_perm:[1,0,3,2] row_mask:0xf bank_mask:0xf bound_ctrl:1
	v_mov_b32_dpp v219, v211 quad_perm:[1,0,3,2] row_mask:0xf bank_mask:0xf bound_ctrl:1
	v_mov_b32_dpp v220, v212 quad_perm:[1,0,3,2] row_mask:0xf bank_mask:0xf bound_ctrl:1
	v_mov_b32_dpp v221, v213 quad_perm:[1,0,3,2] row_mask:0xf bank_mask:0xf bound_ctrl:1
	v_mov_b32_dpp v222, v214 quad_perm:[1,0,3,2] row_mask:0xf bank_mask:0xf bound_ctrl:1
	v_mov_b32_dpp v223, v215 quad_perm:[1,0,3,2] row_mask:0xf bank_mask:0xf bound_ctrl:1
	v_perm_b32 v208, v216, v208, v164
	v_perm_b32 v209, v217, v209, v164
	v_perm_b32 v210, v218, v210, v164
	v_perm_b32 v211, v219, v211, v164
	v_perm_b32 v212, v220, v212, v164
	v_perm_b32 v213, v221, v213, v164
	v_perm_b32 v214, v222, v214, v164
	v_perm_b32 v215, v223, v215, v164
	global_store_dword v167, v208, s[8:9]
	global_store_dword v167, v209, s[8:9] offset:1024
	global_store_dword v167, v210, s[8:9] offset:32
	global_store_dword v167, v211, s[8:9] offset:1056
	global_store_dword v167, v212, s[8:9] offset:256
	global_store_dword v167, v213, s[8:9] offset:1280
	global_store_dword v167, v214, s[8:9] offset:288
	global_store_dword v167, v215, s[8:9] offset:1312
	ds_read_b64 v[180:181], v160 offset:60448
	v_add_u32_e32 v167, 0x16000, v163
	s_waitcnt lgkmcnt(0)
	v_mfma_f32_16x16x16_bf16 v[184:187], v[180:181], v[168:169], 0
	v_mfma_f32_16x16x16_bf16 v[188:191], v[180:181], v[170:171], 0
	v_mfma_f32_16x16x16_bf16 v[192:195], v[180:181], v[172:173], 0
	v_mfma_f32_16x16x16_bf16 v[196:199], v[180:181], v[174:175], 0
	s_nop 7
	s_nop 1
	v_add_f32_e32 v184, v176, v184
	v_add_f32_e32 v185, v176, v185
	v_add_f32_e32 v186, v176, v186
	v_add_f32_e32 v187, v176, v187
	v_add_f32_e32 v188, v177, v188
	v_add_f32_e32 v189, v177, v189
	v_add_f32_e32 v190, v177, v190
	v_add_f32_e32 v191, v177, v191
	v_min_f32_e32 v200, 0, v184
	v_min_f32_e32 v201, 0, v185
	v_min_f32_e32 v202, 0, v186
	v_min_f32_e32 v203, 0, v187
	v_min_f32_e32 v204, 0, v188
	v_min_f32_e32 v205, 0, v189
	v_min_f32_e32 v206, 0, v190
	v_min_f32_e32 v207, 0, v191
	v_mul_f32_e64 v208, |v184|, s93
	v_mul_f32_e64 v209, |v185|, s93
	v_mul_f32_e64 v210, |v186|, s93
	v_mul_f32_e64 v211, |v187|, s93
	v_mul_f32_e64 v212, |v188|, s93
	v_mul_f32_e64 v213, |v189|, s93
	v_mul_f32_e64 v214, |v190|, s93
	v_mul_f32_e64 v215, |v191|, s93
	v_exp_f32_e32 v208, v208
	v_exp_f32_e32 v209, v209
	v_exp_f32_e32 v210, v210
	v_exp_f32_e32 v211, v211
	v_exp_f32_e32 v212, v212
	v_exp_f32_e32 v213, v213
	v_exp_f32_e32 v214, v214
	v_exp_f32_e32 v215, v215
	v_add_f32_e32 v208, 1.0, v208
	v_add_f32_e32 v209, 1.0, v209
	v_add_f32_e32 v210, 1.0, v210
	v_add_f32_e32 v211, 1.0, v211
	v_add_f32_e32 v212, 1.0, v212
	v_add_f32_e32 v213, 1.0, v213
	v_add_f32_e32 v214, 1.0, v214
	v_add_f32_e32 v215, 1.0, v215
	v_log_f32_e32 v208, v208
	v_log_f32_e32 v209, v209
	v_log_f32_e32 v210, v210
	v_log_f32_e32 v211, v211
	v_log_f32_e32 v212, v212
	v_log_f32_e32 v213, v213
	v_log_f32_e32 v214, v214
	v_log_f32_e32 v215, v215
	v_mul_f32_e32 v216, 0x3f317217, v208
	v_mul_f32_e32 v217, 0x3f317217, v209
	v_mul_f32_e32 v218, 0x3f317217, v210
	v_mul_f32_e32 v219, 0x3f317217, v211
	v_mul_f32_e32 v220, 0x3f317217, v212
	v_mul_f32_e32 v221, 0x3f317217, v213
	v_mul_f32_e32 v222, 0x3f317217, v214
	v_mul_f32_e32 v223, 0x3f317217, v215
	v_fma_f32 v216, v208, s95, -v216
	v_fma_f32 v217, v209, s95, -v217
	v_fma_f32 v218, v210, s95, -v218
	v_fma_f32 v219, v211, s95, -v219
	v_fma_f32 v220, v212, s95, -v220
	v_fma_f32 v221, v213, s95, -v221
	v_fma_f32 v222, v214, s95, -v222
	v_fma_f32 v223, v215, s95, -v223
	v_fmac_f32_e32 v216, 0x3377d1cf, v208
	v_fmac_f32_e32 v217, 0x3377d1cf, v209
	v_fmac_f32_e32 v218, 0x3377d1cf, v210
	v_fmac_f32_e32 v219, 0x3377d1cf, v211
	v_fmac_f32_e32 v220, 0x3377d1cf, v212
	v_fmac_f32_e32 v221, 0x3377d1cf, v213
	v_fmac_f32_e32 v222, 0x3377d1cf, v214
	v_fmac_f32_e32 v223, 0x3377d1cf, v215
	v_fmac_f32_e32 v216, 0x3f317217, v208
	v_fmac_f32_e32 v217, 0x3f317217, v209
	v_fmac_f32_e32 v218, 0x3f317217, v210
	v_fmac_f32_e32 v219, 0x3f317217, v211
	v_fmac_f32_e32 v220, 0x3f317217, v212
; __device__ __forceinline__ void store_rm4(u16* dst, size_t ld, int row0, int c, float v0, float v1, float v2, float v3, bool odd) {
;   {
;     float s = odd ? v0 : v1, r = dpp_swap1(s);
;     float lo = odd ? r : v0, hi = odd ? v1 : r;
;     *(unsigned*)(dst + (size_t)(row0 + (odd ? 1 : 0)) * ld + (c - (odd ? 1 : 0))) = pack2(lo, hi);
;   }
;   {
;     float s = odd ? v2 : v3, r = dpp_swap1(s);
;     float lo = odd ? r : v2, hi = odd ? v3 : r;
;     *(unsigned*)(dst + (size_t)(row0 + 2 + (odd ? 1 : 0)) * ld + (c - (odd ? 1 : 0))) = pack2(lo, hi);
;   }
; }
;   __device__ __forceinline__ void operator()(f32x4 (&acc)[2][2][4][2], int brow, int bcol, int wr, int wc, int fr, int fq) const {
;     ...
;         for (int ai = 0; ai < 2; ++ai)
; #pragma unroll
;           for (int m = 0; m < 4; ++m) {
;             int rl = ai * 128 + wr * 64 + m * 16;
;             s16x4 af = *(const s16x4*)(glr + (rl + fr) * 32 + dir * 16 + fq * 4);
;             int row0 = brow + rl + fq * 4;
; #pragma unroll
;             for (int bj = 0; bj < 2; ++bj)
; #pragma unroll
;               for (int n = 0; n < 2; ++n) {
;                 f32x4 z4 = {0.f, 0.f, 0.f, 0.f};
;                 z4 = __builtin_amdgcn_mfma_f32_16x16x16bf16_1k(af, bfr[bj][n], z4, 0, 0, 0);
;                 int c = bj * 128 + wc * 32 + n * 16 + fr;
;                 float bb = bias[c];
;                 float ls[4];
; #pragma unroll
;                 for (int j = 0; j < 4; ++j) {
;                   float z = z4[j] + bb;
;                   ls[j] = (fminf(z, 0.f) - __logf(1.f + __expf(-fabsf(z)))) * (1.f / 16.f);
;                 }
;                 store_rm4(dst, 256, row0, c, ls[0], ls[1], ls[2], ls[3], fr & 1);
;               }
	v_fmac_f32_e32 v221, 0x3f317217, v213
	v_fmac_f32_e32 v222, 0x3f317217, v214
	v_fmac_f32_e32 v223, 0x3f317217, v215
	v_sub_f32_e32 v200, v200, v216
	v_sub_f32_e32 v201, v201, v217
	v_sub_f32_e32 v202, v202, v218
	v_sub_f32_e32 v203, v203, v219
	v_sub_f32_e32 v204, v204, v220
	v_sub_f32_e32 v205, v205, v221
	v_sub_f32_e32 v206, v206, v222
	v_sub_f32_e32 v207, v207, v223
	v_mul_f32_e32 v184, 0x3d800000, v200
	v_mul_f32_e32 v185, 0x3d800000, v201
	v_mul_f32_e32 v186, 0x3d800000, v202
	v_mul_f32_e32 v187, 0x3d800000, v203
	v_mul_f32_e32 v188, 0x3d800000, v204
	v_mul_f32_e32 v189, 0x3d800000, v205
	v_mul_f32_e32 v190, 0x3d800000, v206
	v_mul_f32_e32 v191, 0x3d800000, v207
	v_add_f32_e32 v192, v178, v192
	v_add_f32_e32 v193, v178, v193
	v_add_f32_e32 v194, v178, v194
	v_add_f32_e32 v195, v178, v195
	v_add_f32_e32 v196, v179, v196
	v_add_f32_e32 v197, v179, v197
	v_add_f32_e32 v198, v179, v198
	v_add_f32_e32 v199, v179, v199
	v_min_f32_e32 v200, 0, v192
	v_min_f32_e32 v201, 0, v193
	v_min_f32_e32 v202, 0, v194
	v_min_f32_e32 v203, 0, v195
	v_min_f32_e32 v204, 0, v196
	v_min_f32_e32 v205, 0, v197
	v_min_f32_e32 v206, 0, v198
	v_min_f32_e32 v207, 0, v199
	v_mul_f32_e64 v208, |v192|, s93
	v_mul_f32_e64 v209, |v193|, s93
	v_mul_f32_e64 v210, |v194|, s93
	v_mul_f32_e64 v211, |v195|, s93
	v_mul_f32_e64 v212, |v196|, s93
	v_mul_f32_e64 v213, |v197|, s93
	v_mul_f32_e64 v214, |v198|, s93
	v_mul_f32_e64 v215, |v199|, s93
	v_exp_f32_e32 v208, v208
	v_exp_f32_e32 v209, v209
	v_exp_f32_e32 v210, v210
	v_exp_f32_e32 v211, v211
	v_exp_f32_e32 v212, v212
	v_exp_f32_e32 v213, v213
	v_exp_f32_e32 v214, v214
	v_exp_f32_e32 v215, v215
	v_add_f32_e32 v208, 1.0, v208
	v_add_f32_e32 v209, 1.0, v209
	v_add_f32_e32 v210, 1.0, v210
	v_add_f32_e32 v211, 1.0, v211
	v_add_f32_e32 v212, 1.0, v212
	v_add_f32_e32 v213, 1.0, v213
	v_add_f32_e32 v214, 1.0, v214
	v_add_f32_e32 v215, 1.0, v215
	v_log_f32_e32 v208, v208
	v_log_f32_e32 v209, v209
	v_log_f32_e32 v210, v210
	v_log_f32_e32 v211, v211
	v_log_f32_e32 v212, v212
	v_log_f32_e32 v213, v213
	v_log_f32_e32 v214, v214
	v_log_f32_e32 v215, v215
	v_mul_f32_e32 v216, 0x3f317217, v208
	v_mul_f32_e32 v217, 0x3f317217, v209
	v_mul_f32_e32 v218, 0x3f317217, v210
	v_mul_f32_e32 v219, 0x3f317217, v211
	v_mul_f32_e32 v220, 0x3f317217, v212
	v_mul_f32_e32 v221, 0x3f317217, v213
	v_mul_f32_e32 v222, 0x3f317217, v214
	v_mul_f32_e32 v223, 0x3f317217, v215
	v_fma_f32 v216, v208, s95, -v216
	v_fma_f32 v217, v209, s95, -v217
	v_fma_f32 v218, v210, s95, -v218
	v_fma_f32 v219, v211, s95, -v219
	v_fma_f32 v220, v212, s95, -v220
	v_fma_f32 v221, v213, s95, -v221
	v_fma_f32 v222, v214, s95, -v222
	v_fma_f32 v223, v215, s95, -v223
	v_fmac_f32_e32 v216, 0x3377d1cf, v208
	v_fmac_f32_e32 v217, 0x3377d1cf, v209
	v_fmac_f32_e32 v218, 0x3377d1cf, v210
	v_fmac_f32_e32 v219, 0x3377d1cf, v211
	v_fmac_f32_e32 v220, 0x3377d1cf, v212
	v_fmac_f32_e32 v221, 0x3377d1cf, v213
	v_fmac_f32_e32 v222, 0x3377d1cf, v214
	v_fmac_f32_e32 v223, 0x3377d1cf, v215
	v_fmac_f32_e32 v216, 0x3f317217, v208
	v_fmac_f32_e32 v217, 0x3f317217, v209
	v_fmac_f32_e32 v218, 0x3f317217, v210
	v_fmac_f32_e32 v219, 0x3f317217, v211
	v_fmac_f32_e32 v220, 0x3f317217, v212
	v_fmac_f32_e32 v221, 0x3f317217, v213
	v_fmac_f32_e32 v222, 0x3f317217, v214
	v_fmac_f32_e32 v223, 0x3f317217, v215
	v_sub_f32_e32 v200, v200, v216
	v_sub_f32_e32 v201, v201, v217
	v_sub_f32_e32 v202, v202, v218
	v_sub_f32_e32 v203, v203, v219
	v_sub_f32_e32 v204, v204, v220
	v_sub_f32_e32 v205, v205, v221
	v_sub_f32_e32 v206, v206, v222
	v_sub_f32_e32 v207, v207, v223
	v_mul_f32_e32 v192, 0x3d800000, v200
	v_mul_f32_e32 v193, 0x3d800000, v201
	v_mul_f32_e32 v194, 0x3d800000, v202
	v_mul_f32_e32 v195, 0x3d800000, v203
	v_mul_f32_e32 v196, 0x3d800000, v204
	v_mul_f32_e32 v197, 0x3d800000, v205
	v_mul_f32_e32 v198, 0x3d800000, v206
	v_mul_f32_e32 v199, 0x3d800000, v207
	v_cvt_pk_bf16_f32 v208, v184, v185
	v_cvt_pk_bf16_f32 v209, v186, v187
	v_cvt_pk_bf16_f32 v210, v188, v189
	v_cvt_pk_bf16_f32 v211, v190, v191
	v_cvt_pk_bf16_f32 v212, v192, v193
	v_cvt_pk_bf16_f32 v213, v194, v195
	v_cvt_pk_bf16_f32 v214, v196, v197
	v_cvt_pk_bf16_f32 v215, v198, v199
	v_mov_b32_dpp v216, v208 quad_perm:[1,0,3,2] row_mask:0xf bank_mask:0xf bound_ctrl:1
	v_mov_b32_dpp v217, v209 quad_perm:[1,0,3,2] row_mask:0xf bank_mask:0xf bound_ctrl:1
	v_mov_b32_dpp v218, v210 quad_perm:[1,0,3,2] row_mask:0xf bank_mask:0xf bound_ctrl:1
	v_mov_b32_dpp v219, v211 quad_perm:[1,0,3,2] row_mask:0xf bank_mask:0xf bound_ctrl:1
	v_mov_b32_dpp v220, v212 quad_perm:[1,0,3,2] row_mask:0xf bank_mask:0xf bound_ctrl:1
	v_mov_b32_dpp v221, v213 quad_perm:[1,0,3,2] row_mask:0xf bank_mask:0xf bound_ctrl:1
	v_mov_b32_dpp v222, v214 quad_perm:[1,0,3,2] row_mask:0xf bank_mask:0xf bound_ctrl:1
	v_mov_b32_dpp v223, v215 quad_perm:[1,0,3,2] row_mask:0xf bank_mask:0xf bound_ctrl:1
	v_perm_b32 v208, v216, v208, v164
	v_perm_b32 v209, v217, v209, v164
	v_perm_b32 v210, v218, v210, v164
	v_perm_b32 v211, v219, v211, v164
	v_perm_b32 v212, v220, v212, v164
	v_perm_b32 v213, v221, v213, v164
	v_perm_b32 v214, v222, v214, v164
	v_perm_b32 v215, v223, v215, v164
	global_store_dword v167, v208, s[8:9]
	global_store_dword v167, v209, s[8:9] offset:1024
	global_store_dword v167, v210, s[8:9] offset:32
	global_store_dword v167, v211, s[8:9] offset:1056
	global_store_dword v167, v212, s[8:9] offset:256
	global_store_dword v167, v213, s[8:9] offset:1280
	global_store_dword v167, v214, s[8:9] offset:288
	global_store_dword v167, v215, s[8:9] offset:1312
	s_mov_b64 s[0:1], 0
